# GEMM K-loops: the back-to-back s_setprio 0 / s_setprio 1 pair in the middle of each 32-MFMA section removed (priority stays raised through the section)
# speedup vs baseline: 1.0131x; 1.0131x over previous
.LBB0_164:
	s_add_u32 s50, s16, 0x100
	s_addc_u32 s51, s17, 0
	s_mov_b32 s86, -2
	s_add_u32 s16, s14, 0x100
	s_addc_u32 s17, s15, 0
	s_add_i32 s22, 0, 0x10000
	s_cmp_eq_u32 s86, 8
	s_cselect_b32 s39, s11, s17
	s_cselect_b32 s38, s10, s16
	v_add_u32_e32 v142, s22, v145
	s_cselect_b32 s19, s13, s51
	s_cselect_b32 s18, s12, s50
	s_add_i32 s23, 0, 0x14000
	ds_read_b128 v[138:141], v142
	ds_read_b128 v[148:151], v142 offset:1024
	ds_read_b128 v[152:155], v142 offset:2048
	ds_read_b128 v[156:159], v142 offset:3072
	v_add_u32_e32 v142, s23, v145
	ds_read_b128 v[170:173], v142
	ds_read_b128 v[174:177], v142 offset:1024
	ds_read_b128 v[178:181], v142 offset:2048
	ds_read_b128 v[182:185], v142 offset:3072
	v_lshl_add_u64 v[142:143], s[14:15], 0, v[134:135]
	s_add_i32 m0, s41, 0xc000
	ds_read_b128 v[186:189], v147
	ds_read_b128 v[190:193], v147 offset:1024
	ds_read_b128 v[194:197], v147 offset:2048
	ds_read_b128 v[198:201], v147 offset:3072
	ds_read_b128 v[202:205], v147 offset:4096
	ds_read_b128 v[206:209], v147 offset:5120
	ds_read_b128 v[210:213], v147 offset:6144
	ds_read_b128 v[222:225], v147 offset:7168
	global_load_lds_dwordx4 v[142:143], off
	v_lshl_add_u64 v[142:143], s[14:15], 0, v[136:137]
	s_add_i32 m0, s41, 0xe000
	s_nop 0
	global_load_lds_dwordx4 v[142:143], off
	s_waitcnt vmcnt(8)
	s_waitcnt lgkmcnt(0)
	s_barrier
	s_setprio 1
	s_waitcnt lgkmcnt(0)
	v_mfma_f32_16x16x32_bf16 v[124:127], v[138:141], v[186:189], 0
	v_mfma_f32_16x16x32_bf16 v[120:123], v[152:155], v[186:189], 0
	v_mfma_f32_16x16x32_bf16 v[108:111], v[138:141], v[194:197], 0
	v_mfma_f32_16x16x32_bf16 v[104:107], v[152:155], v[194:197], 0
	v_mfma_f32_16x16x32_bf16 v[92:95], v[138:141], v[202:205], 0
	v_mfma_f32_16x16x32_bf16 v[88:91], v[152:155], v[202:205], 0
	v_mfma_f32_16x16x32_bf16 v[76:79], v[138:141], v[210:213], 0
	v_mfma_f32_16x16x32_bf16 v[72:75], v[152:155], v[210:213], 0
	v_mfma_f32_16x16x32_bf16 v[124:127], v[148:151], v[190:193], v[124:127]
	v_mfma_f32_16x16x32_bf16 v[120:123], v[156:159], v[190:193], v[120:123]
	v_mfma_f32_16x16x32_bf16 v[108:111], v[148:151], v[198:201], v[108:111]
	v_mfma_f32_16x16x32_bf16 v[104:107], v[156:159], v[198:201], v[104:107]
	v_mfma_f32_16x16x32_bf16 v[92:95], v[148:151], v[206:209], v[92:95]
	v_mfma_f32_16x16x32_bf16 v[88:91], v[156:159], v[206:209], v[88:91]
	v_mfma_f32_16x16x32_bf16 v[76:79], v[148:151], v[222:225], v[76:79]
	v_mfma_f32_16x16x32_bf16 v[72:75], v[156:159], v[222:225], v[72:75]
	v_mfma_f32_16x16x32_bf16 v[116:119], v[170:173], v[186:189], 0
	v_mfma_f32_16x16x32_bf16 v[112:115], v[178:181], v[186:189], 0
	v_mfma_f32_16x16x32_bf16 v[100:103], v[170:173], v[194:197], 0
	v_mfma_f32_16x16x32_bf16 v[96:99], v[178:181], v[194:197], 0
	v_mfma_f32_16x16x32_bf16 v[84:87], v[170:173], v[202:205], 0
	v_mfma_f32_16x16x32_bf16 v[80:83], v[178:181], v[202:205], 0
	v_mfma_f32_16x16x32_bf16 v[68:71], v[170:173], v[210:213], 0
	v_mfma_f32_16x16x32_bf16 v[64:67], v[178:181], v[210:213], 0
	v_mfma_f32_16x16x32_bf16 v[116:119], v[174:177], v[190:193], v[116:119]
	v_mfma_f32_16x16x32_bf16 v[112:115], v[182:185], v[190:193], v[112:115]
	v_mfma_f32_16x16x32_bf16 v[100:103], v[174:177], v[198:201], v[100:103]
	v_mfma_f32_16x16x32_bf16 v[96:99], v[182:185], v[198:201], v[96:99]
	v_mfma_f32_16x16x32_bf16 v[84:87], v[174:177], v[206:209], v[84:87]
	v_mfma_f32_16x16x32_bf16 v[80:83], v[182:185], v[206:209], v[80:83]
	v_mfma_f32_16x16x32_bf16 v[68:71], v[174:177], v[222:225], v[68:71]
	v_mfma_f32_16x16x32_bf16 v[64:67], v[182:185], v[222:225], v[64:67]
	s_setprio 0
	s_barrier
	s_add_i32 s14, s22, s27
	v_lshl_add_u64 v[142:143], s[18:19], 0, v[160:161]
	s_mov_b32 m0, s14
	ds_read_b128 v[186:189], v147 offset:16384
	ds_read_b128 v[190:193], v147 offset:17408
	ds_read_b128 v[194:197], v147 offset:18432
	ds_read_b128 v[198:201], v147 offset:19456
	ds_read_b128 v[202:205], v147 offset:20480
	ds_read_b128 v[206:209], v147 offset:21504
	ds_read_b128 v[210:213], v147 offset:22528
	ds_read_b128 v[222:225], v147 offset:23552
	global_load_lds_dwordx4 v[142:143], off
	s_add_i32 m0, s14, 0x2000
	s_add_u32 s14, s18, 0x30000
	v_lshl_add_u64 v[162:163], s[18:19], 0, v[128:129]
	s_addc_u32 s15, s19, 0
	s_add_i32 s22, s23, s27
	global_load_lds_dwordx4 v[162:163], off
	v_lshl_add_u64 v[164:165], s[14:15], 0, v[160:161]
	s_mov_b32 m0, s22
	v_lshl_add_u64 v[214:215], s[38:39], 0, v[130:131]
	global_load_lds_dwordx4 v[164:165], off
	v_lshl_add_u64 v[164:165], s[14:15], 0, v[128:129]
	s_add_i32 m0, s22, 0x2000
	s_nop 0
	global_load_lds_dwordx4 v[164:165], off
	v_lshl_add_u64 v[164:165], s[38:39], 0, v[132:133]
	s_mov_b32 m0, s41
	s_nop 0
	global_load_lds_dwordx4 v[164:165], off
	s_mov_b32 m0, s42
	s_nop 0
	global_load_lds_dwordx4 v[214:215], off
	s_waitcnt vmcnt(8)
	s_waitcnt lgkmcnt(0)
	s_barrier
	s_setprio 1
	s_waitcnt lgkmcnt(0)
	v_mfma_f32_16x16x32_bf16 v[60:63], v[138:141], v[186:189], 0
	v_mfma_f32_16x16x32_bf16 v[56:59], v[152:155], v[186:189], 0
	v_mfma_f32_16x16x32_bf16 v[44:47], v[138:141], v[194:197], 0
	v_mfma_f32_16x16x32_bf16 v[40:43], v[152:155], v[194:197], 0
	v_mfma_f32_16x16x32_bf16 v[28:31], v[138:141], v[202:205], 0
	v_mfma_f32_16x16x32_bf16 v[24:27], v[152:155], v[202:205], 0
	v_mfma_f32_16x16x32_bf16 v[12:15], v[138:141], v[210:213], 0
	v_mfma_f32_16x16x32_bf16 v[8:11], v[152:155], v[210:213], 0
	v_mfma_f32_16x16x32_bf16 v[60:63], v[148:151], v[190:193], v[60:63]
	v_mfma_f32_16x16x32_bf16 v[56:59], v[156:159], v[190:193], v[56:59]
	v_mfma_f32_16x16x32_bf16 v[44:47], v[148:151], v[198:201], v[44:47]
	v_mfma_f32_16x16x32_bf16 v[40:43], v[156:159], v[198:201], v[40:43]
	v_mfma_f32_16x16x32_bf16 v[28:31], v[148:151], v[206:209], v[28:31]
	v_mfma_f32_16x16x32_bf16 v[24:27], v[156:159], v[206:209], v[24:27]
	v_mfma_f32_16x16x32_bf16 v[12:15], v[148:151], v[222:225], v[12:15]
	v_mfma_f32_16x16x32_bf16 v[8:11], v[156:159], v[222:225], v[8:11]
	v_mfma_f32_16x16x32_bf16 v[52:55], v[170:173], v[186:189], 0
	v_mfma_f32_16x16x32_bf16 v[48:51], v[178:181], v[186:189], 0
	v_mfma_f32_16x16x32_bf16 v[36:39], v[170:173], v[194:197], 0
	v_mfma_f32_16x16x32_bf16 v[32:35], v[178:181], v[194:197], 0
	v_mfma_f32_16x16x32_bf16 v[20:23], v[170:173], v[202:205], 0
	v_mfma_f32_16x16x32_bf16 v[16:19], v[178:181], v[202:205], 0
	v_mfma_f32_16x16x32_bf16 v[4:7], v[170:173], v[210:213], 0
	v_mfma_f32_16x16x32_bf16 v[0:3], v[178:181], v[210:213], 0
	v_mfma_f32_16x16x32_bf16 v[52:55], v[174:177], v[190:193], v[52:55]
	v_mfma_f32_16x16x32_bf16 v[48:51], v[182:185], v[190:193], v[48:51]
	v_mfma_f32_16x16x32_bf16 v[36:39], v[174:177], v[198:201], v[36:39]
	v_mfma_f32_16x16x32_bf16 v[32:35], v[182:185], v[198:201], v[32:35]
	v_mfma_f32_16x16x32_bf16 v[20:23], v[174:177], v[206:209], v[20:23]
	v_mfma_f32_16x16x32_bf16 v[16:19], v[182:185], v[206:209], v[16:19]
	v_mfma_f32_16x16x32_bf16 v[4:7], v[174:177], v[222:225], v[4:7]
	v_mfma_f32_16x16x32_bf16 v[0:3], v[182:185], v[222:225], v[0:3]
	s_setprio 0
	s_barrier
	s_add_i32 s22, 0, 0x18000
	s_add_i32 s23, 0, 0x1c000
	v_add_u32_e32 v156, s22, v145
	v_add_u32_e32 v167, s23, v145
	ds_read_b128 v[138:141], v156
	ds_read_b128 v[148:151], v156 offset:1024
	ds_read_b128 v[152:155], v156 offset:2048
	ds_read_b128 v[156:159], v156 offset:3072
	ds_read_b128 v[170:173], v167
	ds_read_b128 v[174:177], v167 offset:1024
	ds_read_b128 v[178:181], v167 offset:2048
	ds_read_b128 v[182:185], v167 offset:3072
	s_add_u32 s14, s38, 0x30000
	s_addc_u32 s15, s39, 0
	s_mov_b32 m0, s43
	v_lshl_add_u64 v[226:227], s[14:15], 0, v[132:133]
	ds_read_b128 v[186:189], v147 offset:32768
	ds_read_b128 v[190:193], v147 offset:33792
	ds_read_b128 v[194:197], v147 offset:34816
	ds_read_b128 v[198:201], v147 offset:35840
	ds_read_b128 v[202:205], v147 offset:36864
	ds_read_b128 v[206:209], v147 offset:37888
	ds_read_b128 v[210:213], v147 offset:38912
	ds_read_b128 v[222:225], v147 offset:39936
	global_load_lds_dwordx4 v[226:227], off
	v_lshl_add_u64 v[226:227], s[14:15], 0, v[130:131]
	s_mov_b32 m0, s80
	s_nop 0
	global_load_lds_dwordx4 v[226:227], off
	s_waitcnt vmcnt(8)
	s_waitcnt lgkmcnt(0)
	s_barrier
	s_setprio 1
	s_waitcnt lgkmcnt(0)
	v_mfma_f32_16x16x32_bf16 v[124:127], v[138:141], v[186:189], v[124:127]
	v_mfma_f32_16x16x32_bf16 v[120:123], v[152:155], v[186:189], v[120:123]
	v_mfma_f32_16x16x32_bf16 v[108:111], v[138:141], v[194:197], v[108:111]
	v_mfma_f32_16x16x32_bf16 v[104:107], v[152:155], v[194:197], v[104:107]
	v_mfma_f32_16x16x32_bf16 v[92:95], v[138:141], v[202:205], v[92:95]
	v_mfma_f32_16x16x32_bf16 v[88:91], v[152:155], v[202:205], v[88:91]
	v_mfma_f32_16x16x32_bf16 v[76:79], v[138:141], v[210:213], v[76:79]
	v_mfma_f32_16x16x32_bf16 v[72:75], v[152:155], v[210:213], v[72:75]
	v_mfma_f32_16x16x32_bf16 v[124:127], v[148:151], v[190:193], v[124:127]
	v_mfma_f32_16x16x32_bf16 v[120:123], v[156:159], v[190:193], v[120:123]
	v_mfma_f32_16x16x32_bf16 v[108:111], v[148:151], v[198:201], v[108:111]
	v_mfma_f32_16x16x32_bf16 v[104:107], v[156:159], v[198:201], v[104:107]
	v_mfma_f32_16x16x32_bf16 v[92:95], v[148:151], v[206:209], v[92:95]
	v_mfma_f32_16x16x32_bf16 v[88:91], v[156:159], v[206:209], v[88:91]
	v_mfma_f32_16x16x32_bf16 v[76:79], v[148:151], v[222:225], v[76:79]
	v_mfma_f32_16x16x32_bf16 v[72:75], v[156:159], v[222:225], v[72:75]
	v_mfma_f32_16x16x32_bf16 v[116:119], v[170:173], v[186:189], v[116:119]
	v_mfma_f32_16x16x32_bf16 v[112:115], v[178:181], v[186:189], v[112:115]
	v_mfma_f32_16x16x32_bf16 v[100:103], v[170:173], v[194:197], v[100:103]
	v_mfma_f32_16x16x32_bf16 v[96:99], v[178:181], v[194:197], v[96:99]
	v_mfma_f32_16x16x32_bf16 v[84:87], v[170:173], v[202:205], v[84:87]
	v_mfma_f32_16x16x32_bf16 v[80:83], v[178:181], v[202:205], v[80:83]
	v_mfma_f32_16x16x32_bf16 v[68:71], v[170:173], v[210:213], v[68:71]
	v_mfma_f32_16x16x32_bf16 v[64:67], v[178:181], v[210:213], v[64:67]
	v_mfma_f32_16x16x32_bf16 v[116:119], v[174:177], v[190:193], v[116:119]
	v_mfma_f32_16x16x32_bf16 v[112:115], v[182:185], v[190:193], v[112:115]
	v_mfma_f32_16x16x32_bf16 v[100:103], v[174:177], v[198:201], v[100:103]
	v_mfma_f32_16x16x32_bf16 v[96:99], v[182:185], v[198:201], v[96:99]
	v_mfma_f32_16x16x32_bf16 v[84:87], v[174:177], v[206:209], v[84:87]
	v_mfma_f32_16x16x32_bf16 v[80:83], v[182:185], v[206:209], v[80:83]
	v_mfma_f32_16x16x32_bf16 v[68:71], v[174:177], v[222:225], v[68:71]
	v_mfma_f32_16x16x32_bf16 v[64:67], v[182:185], v[222:225], v[64:67]
	s_setprio 0
	s_barrier
	s_add_i32 s14, s22, s27
	v_lshl_add_u64 v[142:143], v[142:143], 0, s[48:49]
	s_mov_b32 m0, s14
	ds_read_b128 v[186:189], v147 offset:49152
	ds_read_b128 v[190:193], v147 offset:50176
	ds_read_b128 v[194:197], v147 offset:51200
	ds_read_b128 v[198:201], v147 offset:52224
	ds_read_b128 v[202:205], v147 offset:53248
	ds_read_b128 v[206:209], v147 offset:54272
	ds_read_b128 v[210:213], v147 offset:55296
	ds_read_b128 v[222:225], v147 offset:56320
	global_load_lds_dwordx4 v[142:143], off
	s_add_i32 m0, s14, 0x2000
	s_add_u32 s14, s18, 0x30080
	v_lshl_add_u64 v[142:143], v[162:163], 0, s[48:49]
	s_addc_u32 s15, s19, 0
	s_add_i32 s18, s23, s27
	global_load_lds_dwordx4 v[142:143], off
	v_lshl_add_u64 v[142:143], s[14:15], 0, v[160:161]
	s_mov_b32 m0, s18
	s_nop 0
	global_load_lds_dwordx4 v[142:143], off
	v_lshl_add_u64 v[142:143], s[14:15], 0, v[128:129]
	s_add_i32 m0, s18, 0x2000
	s_nop 0
	global_load_lds_dwordx4 v[142:143], off
	v_lshl_add_u64 v[142:143], v[164:165], 0, s[48:49]
	s_mov_b32 m0, s81
	s_nop 0
	global_load_lds_dwordx4 v[142:143], off
	v_lshl_add_u64 v[142:143], v[214:215], 0, s[48:49]
	s_mov_b32 m0, s82
	s_nop 0
	global_load_lds_dwordx4 v[142:143], off
	s_waitcnt vmcnt(8)
	s_waitcnt lgkmcnt(0)
	s_barrier
	s_setprio 1
	s_waitcnt lgkmcnt(0)
	v_mfma_f32_16x16x32_bf16 v[60:63], v[138:141], v[186:189], v[60:63]
	v_mfma_f32_16x16x32_bf16 v[56:59], v[152:155], v[186:189], v[56:59]
	v_mfma_f32_16x16x32_bf16 v[44:47], v[138:141], v[194:197], v[44:47]
	v_mfma_f32_16x16x32_bf16 v[40:43], v[152:155], v[194:197], v[40:43]
	v_mfma_f32_16x16x32_bf16 v[28:31], v[138:141], v[202:205], v[28:31]
	v_mfma_f32_16x16x32_bf16 v[24:27], v[152:155], v[202:205], v[24:27]
	v_mfma_f32_16x16x32_bf16 v[12:15], v[138:141], v[210:213], v[12:15]
	v_mfma_f32_16x16x32_bf16 v[8:11], v[152:155], v[210:213], v[8:11]
	v_mfma_f32_16x16x32_bf16 v[60:63], v[148:151], v[190:193], v[60:63]
	v_mfma_f32_16x16x32_bf16 v[56:59], v[156:159], v[190:193], v[56:59]
	v_mfma_f32_16x16x32_bf16 v[44:47], v[148:151], v[198:201], v[44:47]
	v_mfma_f32_16x16x32_bf16 v[40:43], v[156:159], v[198:201], v[40:43]
	v_mfma_f32_16x16x32_bf16 v[28:31], v[148:151], v[206:209], v[28:31]
	v_mfma_f32_16x16x32_bf16 v[24:27], v[156:159], v[206:209], v[24:27]
	v_mfma_f32_16x16x32_bf16 v[12:15], v[148:151], v[222:225], v[12:15]
	v_mfma_f32_16x16x32_bf16 v[8:11], v[156:159], v[222:225], v[8:11]
	v_mfma_f32_16x16x32_bf16 v[52:55], v[170:173], v[186:189], v[52:55]
	v_mfma_f32_16x16x32_bf16 v[48:51], v[178:181], v[186:189], v[48:51]
	v_mfma_f32_16x16x32_bf16 v[36:39], v[170:173], v[194:197], v[36:39]
	v_mfma_f32_16x16x32_bf16 v[32:35], v[178:181], v[194:197], v[32:35]
	v_mfma_f32_16x16x32_bf16 v[20:23], v[170:173], v[202:205], v[20:23]
	v_mfma_f32_16x16x32_bf16 v[16:19], v[178:181], v[202:205], v[16:19]
	v_mfma_f32_16x16x32_bf16 v[4:7], v[170:173], v[210:213], v[4:7]
	v_mfma_f32_16x16x32_bf16 v[0:3], v[178:181], v[210:213], v[0:3]
	v_mfma_f32_16x16x32_bf16 v[52:55], v[174:177], v[190:193], v[52:55]
	v_mfma_f32_16x16x32_bf16 v[48:51], v[182:185], v[190:193], v[48:51]
	v_mfma_f32_16x16x32_bf16 v[36:39], v[174:177], v[198:201], v[36:39]
	v_mfma_f32_16x16x32_bf16 v[32:35], v[182:185], v[198:201], v[32:35]
	v_mfma_f32_16x16x32_bf16 v[20:23], v[174:177], v[206:209], v[20:23]
	v_mfma_f32_16x16x32_bf16 v[16:19], v[182:185], v[206:209], v[16:19]
	v_mfma_f32_16x16x32_bf16 v[4:7], v[174:177], v[222:225], v[4:7]
	v_mfma_f32_16x16x32_bf16 v[0:3], v[182:185], v[222:225], v[0:3]
	s_setprio 0
	s_barrier
	s_add_i32 s86, s86, 2
	s_add_u32 s50, s50, 0x100
	s_addc_u32 s51, s51, 0
	s_cmp_gt_u32 s86, 9
	s_mov_b64 s[14:15], s[16:17]
.LBB0_165:
	s_add_u32 s16, s14, 0x100
	s_addc_u32 s17, s15, 0
	s_add_i32 s22, 0, 0x10000
	s_cmp_eq_u32 s86, 8
	s_cselect_b32 s39, s11, s17
	s_cselect_b32 s38, s10, s16
	v_add_u32_e32 v142, s22, v145
	s_cselect_b32 s19, s13, s51
	s_cselect_b32 s18, s12, s50
	s_add_i32 s23, 0, 0x14000
	ds_read_b128 v[138:141], v142
	ds_read_b128 v[148:151], v142 offset:1024
	ds_read_b128 v[152:155], v142 offset:2048
	ds_read_b128 v[156:159], v142 offset:3072
	v_add_u32_e32 v142, s23, v145
	ds_read_b128 v[170:173], v142
	ds_read_b128 v[174:177], v142 offset:1024
	ds_read_b128 v[178:181], v142 offset:2048
	ds_read_b128 v[182:185], v142 offset:3072
	v_lshl_add_u64 v[142:143], s[14:15], 0, v[134:135]
	s_add_i32 m0, s41, 0xc000
	ds_read_b128 v[186:189], v147
	ds_read_b128 v[190:193], v147 offset:1024
	ds_read_b128 v[194:197], v147 offset:2048
	ds_read_b128 v[198:201], v147 offset:3072
	ds_read_b128 v[202:205], v147 offset:4096
	ds_read_b128 v[206:209], v147 offset:5120
	ds_read_b128 v[210:213], v147 offset:6144
	ds_read_b128 v[222:225], v147 offset:7168
	global_load_lds_dwordx4 v[142:143], off
	v_lshl_add_u64 v[142:143], s[14:15], 0, v[136:137]
	s_add_i32 m0, s41, 0xe000
	s_nop 0
	global_load_lds_dwordx4 v[142:143], off
	s_waitcnt vmcnt(8)
	s_waitcnt lgkmcnt(0)
	s_barrier
	s_setprio 1
	s_waitcnt lgkmcnt(0)
	v_mfma_f32_16x16x32_bf16 v[124:127], v[138:141], v[186:189], v[124:127]
	v_mfma_f32_16x16x32_bf16 v[120:123], v[152:155], v[186:189], v[120:123]
	v_mfma_f32_16x16x32_bf16 v[108:111], v[138:141], v[194:197], v[108:111]
	v_mfma_f32_16x16x32_bf16 v[104:107], v[152:155], v[194:197], v[104:107]
	v_mfma_f32_16x16x32_bf16 v[92:95], v[138:141], v[202:205], v[92:95]
	v_mfma_f32_16x16x32_bf16 v[88:91], v[152:155], v[202:205], v[88:91]
	v_mfma_f32_16x16x32_bf16 v[76:79], v[138:141], v[210:213], v[76:79]
	v_mfma_f32_16x16x32_bf16 v[72:75], v[152:155], v[210:213], v[72:75]
	v_mfma_f32_16x16x32_bf16 v[124:127], v[148:151], v[190:193], v[124:127]
	v_mfma_f32_16x16x32_bf16 v[120:123], v[156:159], v[190:193], v[120:123]
	v_mfma_f32_16x16x32_bf16 v[108:111], v[148:151], v[198:201], v[108:111]
	v_mfma_f32_16x16x32_bf16 v[104:107], v[156:159], v[198:201], v[104:107]
	v_mfma_f32_16x16x32_bf16 v[92:95], v[148:151], v[206:209], v[92:95]
	v_mfma_f32_16x16x32_bf16 v[88:91], v[156:159], v[206:209], v[88:91]
	v_mfma_f32_16x16x32_bf16 v[76:79], v[148:151], v[222:225], v[76:79]
	v_mfma_f32_16x16x32_bf16 v[72:75], v[156:159], v[222:225], v[72:75]
	v_mfma_f32_16x16x32_bf16 v[116:119], v[170:173], v[186:189], v[116:119]
	v_mfma_f32_16x16x32_bf16 v[112:115], v[178:181], v[186:189], v[112:115]
	v_mfma_f32_16x16x32_bf16 v[100:103], v[170:173], v[194:197], v[100:103]
	v_mfma_f32_16x16x32_bf16 v[96:99], v[178:181], v[194:197], v[96:99]
	v_mfma_f32_16x16x32_bf16 v[84:87], v[170:173], v[202:205], v[84:87]
	v_mfma_f32_16x16x32_bf16 v[80:83], v[178:181], v[202:205], v[80:83]
	v_mfma_f32_16x16x32_bf16 v[68:71], v[170:173], v[210:213], v[68:71]
	v_mfma_f32_16x16x32_bf16 v[64:67], v[178:181], v[210:213], v[64:67]
	v_mfma_f32_16x16x32_bf16 v[116:119], v[174:177], v[190:193], v[116:119]
	v_mfma_f32_16x16x32_bf16 v[112:115], v[182:185], v[190:193], v[112:115]
	v_mfma_f32_16x16x32_bf16 v[100:103], v[174:177], v[198:201], v[100:103]
	v_mfma_f32_16x16x32_bf16 v[96:99], v[182:185], v[198:201], v[96:99]
	v_mfma_f32_16x16x32_bf16 v[84:87], v[174:177], v[206:209], v[84:87]
	v_mfma_f32_16x16x32_bf16 v[80:83], v[182:185], v[206:209], v[80:83]
	v_mfma_f32_16x16x32_bf16 v[68:71], v[174:177], v[222:225], v[68:71]
	v_mfma_f32_16x16x32_bf16 v[64:67], v[182:185], v[222:225], v[64:67]
	s_setprio 0
	s_barrier
	s_add_i32 s14, s22, s27
	v_lshl_add_u64 v[142:143], s[18:19], 0, v[160:161]
	s_mov_b32 m0, s14
	ds_read_b128 v[186:189], v147 offset:16384
	ds_read_b128 v[190:193], v147 offset:17408
	ds_read_b128 v[194:197], v147 offset:18432
	ds_read_b128 v[198:201], v147 offset:19456
	ds_read_b128 v[202:205], v147 offset:20480
	ds_read_b128 v[206:209], v147 offset:21504
	ds_read_b128 v[210:213], v147 offset:22528
	ds_read_b128 v[222:225], v147 offset:23552
	global_load_lds_dwordx4 v[142:143], off
	s_add_i32 m0, s14, 0x2000
	s_add_u32 s14, s18, 0x30000
	v_lshl_add_u64 v[162:163], s[18:19], 0, v[128:129]
	s_addc_u32 s15, s19, 0
	s_add_i32 s22, s23, s27
	global_load_lds_dwordx4 v[162:163], off
	v_lshl_add_u64 v[164:165], s[14:15], 0, v[160:161]
	s_mov_b32 m0, s22
	v_lshl_add_u64 v[214:215], s[38:39], 0, v[130:131]
	global_load_lds_dwordx4 v[164:165], off
	v_lshl_add_u64 v[164:165], s[14:15], 0, v[128:129]
	s_add_i32 m0, s22, 0x2000
	s_nop 0
	global_load_lds_dwordx4 v[164:165], off
	v_lshl_add_u64 v[164:165], s[38:39], 0, v[132:133]
	s_mov_b32 m0, s41
	s_nop 0
	global_load_lds_dwordx4 v[164:165], off
	s_mov_b32 m0, s42
	s_nop 0
	global_load_lds_dwordx4 v[214:215], off
	s_waitcnt vmcnt(8)
	s_waitcnt lgkmcnt(0)
	s_barrier
	s_setprio 1
	s_waitcnt lgkmcnt(0)
	v_mfma_f32_16x16x32_bf16 v[60:63], v[138:141], v[186:189], v[60:63]
	v_mfma_f32_16x16x32_bf16 v[56:59], v[152:155], v[186:189], v[56:59]
	v_mfma_f32_16x16x32_bf16 v[44:47], v[138:141], v[194:197], v[44:47]
	v_mfma_f32_16x16x32_bf16 v[40:43], v[152:155], v[194:197], v[40:43]
	v_mfma_f32_16x16x32_bf16 v[28:31], v[138:141], v[202:205], v[28:31]
	v_mfma_f32_16x16x32_bf16 v[24:27], v[152:155], v[202:205], v[24:27]
	v_mfma_f32_16x16x32_bf16 v[12:15], v[138:141], v[210:213], v[12:15]
	v_mfma_f32_16x16x32_bf16 v[8:11], v[152:155], v[210:213], v[8:11]
	v_mfma_f32_16x16x32_bf16 v[60:63], v[148:151], v[190:193], v[60:63]
	v_mfma_f32_16x16x32_bf16 v[56:59], v[156:159], v[190:193], v[56:59]
	v_mfma_f32_16x16x32_bf16 v[44:47], v[148:151], v[198:201], v[44:47]
	v_mfma_f32_16x16x32_bf16 v[40:43], v[156:159], v[198:201], v[40:43]
	v_mfma_f32_16x16x32_bf16 v[28:31], v[148:151], v[206:209], v[28:31]
	v_mfma_f32_16x16x32_bf16 v[24:27], v[156:159], v[206:209], v[24:27]
	v_mfma_f32_16x16x32_bf16 v[12:15], v[148:151], v[222:225], v[12:15]
	v_mfma_f32_16x16x32_bf16 v[8:11], v[156:159], v[222:225], v[8:11]
	v_mfma_f32_16x16x32_bf16 v[52:55], v[170:173], v[186:189], v[52:55]
	v_mfma_f32_16x16x32_bf16 v[48:51], v[178:181], v[186:189], v[48:51]
	v_mfma_f32_16x16x32_bf16 v[36:39], v[170:173], v[194:197], v[36:39]
	v_mfma_f32_16x16x32_bf16 v[32:35], v[178:181], v[194:197], v[32:35]
	v_mfma_f32_16x16x32_bf16 v[20:23], v[170:173], v[202:205], v[20:23]
	v_mfma_f32_16x16x32_bf16 v[16:19], v[178:181], v[202:205], v[16:19]
	v_mfma_f32_16x16x32_bf16 v[4:7], v[170:173], v[210:213], v[4:7]
	v_mfma_f32_16x16x32_bf16 v[0:3], v[178:181], v[210:213], v[0:3]
	v_mfma_f32_16x16x32_bf16 v[52:55], v[174:177], v[190:193], v[52:55]
	v_mfma_f32_16x16x32_bf16 v[48:51], v[182:185], v[190:193], v[48:51]
	v_mfma_f32_16x16x32_bf16 v[36:39], v[174:177], v[198:201], v[36:39]
	v_mfma_f32_16x16x32_bf16 v[32:35], v[182:185], v[198:201], v[32:35]
	v_mfma_f32_16x16x32_bf16 v[20:23], v[174:177], v[206:209], v[20:23]
	v_mfma_f32_16x16x32_bf16 v[16:19], v[182:185], v[206:209], v[16:19]
	v_mfma_f32_16x16x32_bf16 v[4:7], v[174:177], v[222:225], v[4:7]
	v_mfma_f32_16x16x32_bf16 v[0:3], v[182:185], v[222:225], v[0:3]
	s_setprio 0
	s_barrier
	s_add_i32 s22, 0, 0x18000
	s_add_i32 s23, 0, 0x1c000
	v_add_u32_e32 v156, s22, v145
	v_add_u32_e32 v167, s23, v145
	ds_read_b128 v[138:141], v156
	ds_read_b128 v[148:151], v156 offset:1024
	ds_read_b128 v[152:155], v156 offset:2048
	ds_read_b128 v[156:159], v156 offset:3072
	ds_read_b128 v[170:173], v167
	ds_read_b128 v[174:177], v167 offset:1024
	ds_read_b128 v[178:181], v167 offset:2048
	ds_read_b128 v[182:185], v167 offset:3072
	s_add_u32 s14, s38, 0x30000
	s_addc_u32 s15, s39, 0
	s_mov_b32 m0, s43
	v_lshl_add_u64 v[226:227], s[14:15], 0, v[132:133]
	ds_read_b128 v[186:189], v147 offset:32768
	ds_read_b128 v[190:193], v147 offset:33792
	ds_read_b128 v[194:197], v147 offset:34816
	ds_read_b128 v[198:201], v147 offset:35840
	ds_read_b128 v[202:205], v147 offset:36864
	ds_read_b128 v[206:209], v147 offset:37888
	ds_read_b128 v[210:213], v147 offset:38912
	ds_read_b128 v[222:225], v147 offset:39936
	global_load_lds_dwordx4 v[226:227], off
	v_lshl_add_u64 v[226:227], s[14:15], 0, v[130:131]
	s_mov_b32 m0, s80
	s_nop 0
	global_load_lds_dwordx4 v[226:227], off
	s_waitcnt vmcnt(8)
	s_waitcnt lgkmcnt(0)
	s_barrier
	s_setprio 1
	s_waitcnt lgkmcnt(0)
	v_mfma_f32_16x16x32_bf16 v[124:127], v[138:141], v[186:189], v[124:127]
	v_mfma_f32_16x16x32_bf16 v[120:123], v[152:155], v[186:189], v[120:123]
	v_mfma_f32_16x16x32_bf16 v[108:111], v[138:141], v[194:197], v[108:111]
	v_mfma_f32_16x16x32_bf16 v[104:107], v[152:155], v[194:197], v[104:107]
	v_mfma_f32_16x16x32_bf16 v[92:95], v[138:141], v[202:205], v[92:95]
	v_mfma_f32_16x16x32_bf16 v[88:91], v[152:155], v[202:205], v[88:91]
	v_mfma_f32_16x16x32_bf16 v[76:79], v[138:141], v[210:213], v[76:79]
	v_mfma_f32_16x16x32_bf16 v[72:75], v[152:155], v[210:213], v[72:75]
	v_mfma_f32_16x16x32_bf16 v[124:127], v[148:151], v[190:193], v[124:127]
	v_mfma_f32_16x16x32_bf16 v[120:123], v[156:159], v[190:193], v[120:123]
	v_mfma_f32_16x16x32_bf16 v[108:111], v[148:151], v[198:201], v[108:111]
	v_mfma_f32_16x16x32_bf16 v[104:107], v[156:159], v[198:201], v[104:107]
	v_mfma_f32_16x16x32_bf16 v[92:95], v[148:151], v[206:209], v[92:95]
	v_mfma_f32_16x16x32_bf16 v[88:91], v[156:159], v[206:209], v[88:91]
	v_mfma_f32_16x16x32_bf16 v[76:79], v[148:151], v[222:225], v[76:79]
	v_mfma_f32_16x16x32_bf16 v[72:75], v[156:159], v[222:225], v[72:75]
	v_mfma_f32_16x16x32_bf16 v[116:119], v[170:173], v[186:189], v[116:119]
	v_mfma_f32_16x16x32_bf16 v[112:115], v[178:181], v[186:189], v[112:115]
	v_mfma_f32_16x16x32_bf16 v[100:103], v[170:173], v[194:197], v[100:103]
	v_mfma_f32_16x16x32_bf16 v[96:99], v[178:181], v[194:197], v[96:99]
	v_mfma_f32_16x16x32_bf16 v[84:87], v[170:173], v[202:205], v[84:87]
	v_mfma_f32_16x16x32_bf16 v[80:83], v[178:181], v[202:205], v[80:83]
	v_mfma_f32_16x16x32_bf16 v[68:71], v[170:173], v[210:213], v[68:71]
	v_mfma_f32_16x16x32_bf16 v[64:67], v[178:181], v[210:213], v[64:67]
	v_mfma_f32_16x16x32_bf16 v[116:119], v[174:177], v[190:193], v[116:119]
	v_mfma_f32_16x16x32_bf16 v[112:115], v[182:185], v[190:193], v[112:115]
	v_mfma_f32_16x16x32_bf16 v[100:103], v[174:177], v[198:201], v[100:103]
	v_mfma_f32_16x16x32_bf16 v[96:99], v[182:185], v[198:201], v[96:99]
	v_mfma_f32_16x16x32_bf16 v[84:87], v[174:177], v[206:209], v[84:87]
	v_mfma_f32_16x16x32_bf16 v[80:83], v[182:185], v[206:209], v[80:83]
	v_mfma_f32_16x16x32_bf16 v[68:71], v[174:177], v[222:225], v[68:71]
	v_mfma_f32_16x16x32_bf16 v[64:67], v[182:185], v[222:225], v[64:67]
	s_setprio 0
	s_barrier
	s_add_i32 s14, s22, s27
	v_lshl_add_u64 v[142:143], v[142:143], 0, s[48:49]
	s_mov_b32 m0, s14
	ds_read_b128 v[186:189], v147 offset:49152
	ds_read_b128 v[190:193], v147 offset:50176
	ds_read_b128 v[194:197], v147 offset:51200
	ds_read_b128 v[198:201], v147 offset:52224
	ds_read_b128 v[202:205], v147 offset:53248
	ds_read_b128 v[206:209], v147 offset:54272
	ds_read_b128 v[210:213], v147 offset:55296
	ds_read_b128 v[222:225], v147 offset:56320
	global_load_lds_dwordx4 v[142:143], off
	s_add_i32 m0, s14, 0x2000
	s_add_u32 s14, s18, 0x30080
	v_lshl_add_u64 v[142:143], v[162:163], 0, s[48:49]
	s_addc_u32 s15, s19, 0
	s_add_i32 s18, s23, s27
	global_load_lds_dwordx4 v[142:143], off
	v_lshl_add_u64 v[142:143], s[14:15], 0, v[160:161]
	s_mov_b32 m0, s18
	s_nop 0
	global_load_lds_dwordx4 v[142:143], off
	v_lshl_add_u64 v[142:143], s[14:15], 0, v[128:129]
	s_add_i32 m0, s18, 0x2000
	s_nop 0
	global_load_lds_dwordx4 v[142:143], off
	v_lshl_add_u64 v[142:143], v[164:165], 0, s[48:49]
	s_mov_b32 m0, s81
	s_nop 0
	global_load_lds_dwordx4 v[142:143], off
	v_lshl_add_u64 v[142:143], v[214:215], 0, s[48:49]
	s_mov_b32 m0, s82
	s_nop 0
	global_load_lds_dwordx4 v[142:143], off
	s_waitcnt vmcnt(8)
	s_waitcnt lgkmcnt(0)
	s_barrier
	s_setprio 1
	s_waitcnt lgkmcnt(0)
	v_mfma_f32_16x16x32_bf16 v[60:63], v[138:141], v[186:189], v[60:63]
	v_mfma_f32_16x16x32_bf16 v[56:59], v[152:155], v[186:189], v[56:59]
	v_mfma_f32_16x16x32_bf16 v[44:47], v[138:141], v[194:197], v[44:47]
	v_mfma_f32_16x16x32_bf16 v[40:43], v[152:155], v[194:197], v[40:43]
	v_mfma_f32_16x16x32_bf16 v[28:31], v[138:141], v[202:205], v[28:31]
	v_mfma_f32_16x16x32_bf16 v[24:27], v[152:155], v[202:205], v[24:27]
	v_mfma_f32_16x16x32_bf16 v[12:15], v[138:141], v[210:213], v[12:15]
	v_mfma_f32_16x16x32_bf16 v[8:11], v[152:155], v[210:213], v[8:11]
	v_mfma_f32_16x16x32_bf16 v[60:63], v[148:151], v[190:193], v[60:63]
	v_mfma_f32_16x16x32_bf16 v[56:59], v[156:159], v[190:193], v[56:59]
	v_mfma_f32_16x16x32_bf16 v[44:47], v[148:151], v[198:201], v[44:47]
	v_mfma_f32_16x16x32_bf16 v[40:43], v[156:159], v[198:201], v[40:43]
	v_mfma_f32_16x16x32_bf16 v[28:31], v[148:151], v[206:209], v[28:31]
	v_mfma_f32_16x16x32_bf16 v[24:27], v[156:159], v[206:209], v[24:27]
	v_mfma_f32_16x16x32_bf16 v[12:15], v[148:151], v[222:225], v[12:15]
	v_mfma_f32_16x16x32_bf16 v[8:11], v[156:159], v[222:225], v[8:11]
	v_mfma_f32_16x16x32_bf16 v[52:55], v[170:173], v[186:189], v[52:55]
	v_mfma_f32_16x16x32_bf16 v[48:51], v[178:181], v[186:189], v[48:51]
	v_mfma_f32_16x16x32_bf16 v[36:39], v[170:173], v[194:197], v[36:39]
	v_mfma_f32_16x16x32_bf16 v[32:35], v[178:181], v[194:197], v[32:35]
	v_mfma_f32_16x16x32_bf16 v[20:23], v[170:173], v[202:205], v[20:23]
	v_mfma_f32_16x16x32_bf16 v[16:19], v[178:181], v[202:205], v[16:19]
	v_mfma_f32_16x16x32_bf16 v[4:7], v[170:173], v[210:213], v[4:7]
	v_mfma_f32_16x16x32_bf16 v[0:3], v[178:181], v[210:213], v[0:3]
	v_mfma_f32_16x16x32_bf16 v[52:55], v[174:177], v[190:193], v[52:55]
	v_mfma_f32_16x16x32_bf16 v[48:51], v[182:185], v[190:193], v[48:51]
	v_mfma_f32_16x16x32_bf16 v[36:39], v[174:177], v[198:201], v[36:39]
	v_mfma_f32_16x16x32_bf16 v[32:35], v[182:185], v[198:201], v[32:35]
	v_mfma_f32_16x16x32_bf16 v[20:23], v[174:177], v[206:209], v[20:23]
	v_mfma_f32_16x16x32_bf16 v[16:19], v[182:185], v[206:209], v[16:19]
	v_mfma_f32_16x16x32_bf16 v[4:7], v[174:177], v[222:225], v[4:7]
	v_mfma_f32_16x16x32_bf16 v[0:3], v[182:185], v[222:225], v[0:3]
	s_setprio 0
	s_barrier
	s_add_i32 s86, s86, 2
	s_add_u32 s50, s50, 0x100
	s_addc_u32 s51, s51, 0
	s_cmp_gt_u32 s86, 9
	s_mov_b64 s[14:15], s[16:17]
	s_cbranch_scc0 .LBB0_165
	s_and_b64 vcc, exec, s[8:9]
	s_cbranch_vccz .LBB0_168
	s_barrier

.LBB0_252:
	s_ashr_i32 s19, s18, 31
	s_lshl_b64 s[6:7], s[18:19], 19
	s_add_u32 s84, s0, s6
	s_addc_u32 s85, s1, s7
	s_and_b64 s[6:7], s[38:39], exec
	s_cselect_b32 s4, s85, s43
	s_cselect_b32 s11, s84, s42
	s_ashr_i32 s17, s16, 31
	s_lshl_b64 s[6:7], s[16:17], 19
	s_add_u32 s6, s26, s6
	s_addc_u32 s7, s27, s7
	s_and_b64 s[24:25], s[38:39], exec
	s_cselect_b32 s17, s7, s83
	s_cselect_b32 s19, s6, s82
	s_add_u32 s42, s42, 0x40080
	s_addc_u32 s43, s43, 0
	s_add_u32 s24, s82, 0x100
	s_addc_u32 s25, s83, 0
	s_mov_b32 s41, -2
	s_waitcnt lgkmcnt(0)
	s_add_u32 s22, s42, 0xfffc0080
	s_addc_u32 s23, s43, -1
	s_add_i32 s28, 0, 0x10000
	s_cmp_eq_u32 s41, 12
	s_cselect_b32 vcc_hi, s4, s23
	s_cselect_b32 vcc_lo, s11, s22
	v_add_u32_e32 v160, s28, v167
	s_cselect_b32 s83, s17, s25
	s_cselect_b32 s82, s19, s24
	s_add_i32 s22, 0, 0x14000
	ds_read_b128 v[148:151], v160
	ds_read_b128 v[152:155], v160 offset:1024
	ds_read_b128 v[156:159], v160 offset:2048
	ds_read_b128 v[174:177], v160 offset:3072
	v_add_u32_e32 v160, s22, v167
	ds_read_b128 v[178:181], v160
	ds_read_b128 v[182:185], v160 offset:1024
	ds_read_b128 v[186:189], v160 offset:2048
	ds_read_b128 v[190:193], v160 offset:3072
	v_lshl_add_u64 v[162:163], s[42:43], 0, v[144:145]
	s_add_i32 m0, s81, 0xc000
	ds_read_b128 v[194:197], v173
	ds_read_b128 v[198:201], v173 offset:1024
	ds_read_b128 v[202:205], v173 offset:2048
	ds_read_b128 v[206:209], v173 offset:3072
	ds_read_b128 v[210:213], v173 offset:4096
	ds_read_b128 v[222:225], v173 offset:5120
	ds_read_b128 v[234:237], v173 offset:6144
	ds_read_b128 v[238:241], v173 offset:7168
	global_load_lds_dwordx4 v[162:163], off
	v_lshl_add_u64 v[162:163], s[42:43], 0, v[146:147]
	s_add_i32 m0, s81, 0xe000
	s_nop 0
	global_load_lds_dwordx4 v[162:163], off
	s_waitcnt vmcnt(8)
	s_waitcnt lgkmcnt(0)
	s_barrier
	s_setprio 1
	s_waitcnt lgkmcnt(0)
	v_mfma_f32_16x16x32_bf16 v[124:127], v[148:151], v[194:197], 0
	v_mfma_f32_16x16x32_bf16 v[120:123], v[156:159], v[194:197], 0
	v_mfma_f32_16x16x32_bf16 v[108:111], v[148:151], v[202:205], 0
	v_mfma_f32_16x16x32_bf16 v[104:107], v[156:159], v[202:205], 0
	v_mfma_f32_16x16x32_bf16 v[92:95], v[148:151], v[210:213], 0
	v_mfma_f32_16x16x32_bf16 v[88:91], v[156:159], v[210:213], 0
	v_mfma_f32_16x16x32_bf16 v[76:79], v[148:151], v[234:237], 0
	v_mfma_f32_16x16x32_bf16 v[72:75], v[156:159], v[234:237], 0
	v_mfma_f32_16x16x32_bf16 v[124:127], v[152:155], v[198:201], v[124:127]
	v_mfma_f32_16x16x32_bf16 v[120:123], v[174:177], v[198:201], v[120:123]
	v_mfma_f32_16x16x32_bf16 v[108:111], v[152:155], v[206:209], v[108:111]
	v_mfma_f32_16x16x32_bf16 v[104:107], v[174:177], v[206:209], v[104:107]
	v_mfma_f32_16x16x32_bf16 v[92:95], v[152:155], v[222:225], v[92:95]
	v_mfma_f32_16x16x32_bf16 v[88:91], v[174:177], v[222:225], v[88:91]
	v_mfma_f32_16x16x32_bf16 v[76:79], v[152:155], v[238:241], v[76:79]
	v_mfma_f32_16x16x32_bf16 v[72:75], v[174:177], v[238:241], v[72:75]
	v_mfma_f32_16x16x32_bf16 v[116:119], v[178:181], v[194:197], 0
	v_mfma_f32_16x16x32_bf16 v[112:115], v[186:189], v[194:197], 0
	v_mfma_f32_16x16x32_bf16 v[100:103], v[178:181], v[202:205], 0
	v_mfma_f32_16x16x32_bf16 v[96:99], v[186:189], v[202:205], 0
	v_mfma_f32_16x16x32_bf16 v[84:87], v[178:181], v[210:213], 0
	v_mfma_f32_16x16x32_bf16 v[80:83], v[186:189], v[210:213], 0
	v_mfma_f32_16x16x32_bf16 v[68:71], v[178:181], v[234:237], 0
	v_mfma_f32_16x16x32_bf16 v[64:67], v[186:189], v[234:237], 0
	v_mfma_f32_16x16x32_bf16 v[116:119], v[182:185], v[198:201], v[116:119]
	v_mfma_f32_16x16x32_bf16 v[112:115], v[190:193], v[198:201], v[112:115]
	v_mfma_f32_16x16x32_bf16 v[100:103], v[182:185], v[206:209], v[100:103]
	v_mfma_f32_16x16x32_bf16 v[96:99], v[190:193], v[206:209], v[96:99]
	v_mfma_f32_16x16x32_bf16 v[84:87], v[182:185], v[222:225], v[84:87]
	v_mfma_f32_16x16x32_bf16 v[80:83], v[190:193], v[222:225], v[80:83]
	v_mfma_f32_16x16x32_bf16 v[68:71], v[182:185], v[238:241], v[68:71]
	v_mfma_f32_16x16x32_bf16 v[64:67], v[190:193], v[238:241], v[64:67]
	s_setprio 0
	s_barrier
	s_add_i32 s23, s28, s80
	v_lshl_add_u64 v[162:163], s[82:83], 0, v[130:131]
	s_mov_b32 m0, s23
	ds_read_b128 v[194:197], v173 offset:16384
	ds_read_b128 v[198:201], v173 offset:17408
	ds_read_b128 v[202:205], v173 offset:18432
	ds_read_b128 v[206:209], v173 offset:19456
	ds_read_b128 v[210:213], v173 offset:20480
	ds_read_b128 v[222:225], v173 offset:21504
	ds_read_b128 v[234:237], v173 offset:22528
	ds_read_b128 v[238:241], v173 offset:23552
	global_load_lds_dwordx4 v[162:163], off
	s_add_i32 m0, s23, 0x2000
	s_add_u32 s50, s82, 0x40000
	v_lshl_add_u64 v[164:165], s[82:83], 0, v[134:135]
	s_addc_u32 s51, s83, 0
	s_add_i32 s22, s22, s80
	global_load_lds_dwordx4 v[164:165], off
	v_lshl_add_u64 v[170:171], s[50:51], 0, v[130:131]
	s_mov_b32 m0, s22
	v_lshl_add_u64 v[214:215], vcc, 0, v[132:133]
	global_load_lds_dwordx4 v[170:171], off
	v_lshl_add_u64 v[170:171], s[50:51], 0, v[134:135]
	s_add_i32 m0, s22, 0x2000
	s_nop 0
	global_load_lds_dwordx4 v[170:171], off
	v_lshl_add_u64 v[170:171], vcc, 0, v[128:129]
	s_mov_b32 m0, s81
	s_nop 0
	global_load_lds_dwordx4 v[170:171], off
	s_mov_b32 m0, s86
	s_nop 0
	global_load_lds_dwordx4 v[214:215], off
	s_waitcnt vmcnt(8)
	s_waitcnt lgkmcnt(0)
	s_barrier
	s_setprio 1
	s_waitcnt lgkmcnt(0)
	v_mfma_f32_16x16x32_bf16 v[60:63], v[148:151], v[194:197], 0
	v_mfma_f32_16x16x32_bf16 v[56:59], v[156:159], v[194:197], 0
	v_mfma_f32_16x16x32_bf16 v[44:47], v[148:151], v[202:205], 0
	v_mfma_f32_16x16x32_bf16 v[40:43], v[156:159], v[202:205], 0
	v_mfma_f32_16x16x32_bf16 v[28:31], v[148:151], v[210:213], 0
	v_mfma_f32_16x16x32_bf16 v[24:27], v[156:159], v[210:213], 0
	v_mfma_f32_16x16x32_bf16 v[12:15], v[148:151], v[234:237], 0
	v_mfma_f32_16x16x32_bf16 v[8:11], v[156:159], v[234:237], 0
	v_mfma_f32_16x16x32_bf16 v[60:63], v[152:155], v[198:201], v[60:63]
	v_mfma_f32_16x16x32_bf16 v[56:59], v[174:177], v[198:201], v[56:59]
	v_mfma_f32_16x16x32_bf16 v[44:47], v[152:155], v[206:209], v[44:47]
	v_mfma_f32_16x16x32_bf16 v[40:43], v[174:177], v[206:209], v[40:43]
	v_mfma_f32_16x16x32_bf16 v[28:31], v[152:155], v[222:225], v[28:31]
	v_mfma_f32_16x16x32_bf16 v[24:27], v[174:177], v[222:225], v[24:27]
	v_mfma_f32_16x16x32_bf16 v[12:15], v[152:155], v[238:241], v[12:15]
	v_mfma_f32_16x16x32_bf16 v[8:11], v[174:177], v[238:241], v[8:11]
	v_mfma_f32_16x16x32_bf16 v[52:55], v[178:181], v[194:197], 0
	v_mfma_f32_16x16x32_bf16 v[48:51], v[186:189], v[194:197], 0
	v_mfma_f32_16x16x32_bf16 v[36:39], v[178:181], v[202:205], 0
	v_mfma_f32_16x16x32_bf16 v[32:35], v[186:189], v[202:205], 0
	v_mfma_f32_16x16x32_bf16 v[20:23], v[178:181], v[210:213], 0
	v_mfma_f32_16x16x32_bf16 v[16:19], v[186:189], v[210:213], 0
	v_mfma_f32_16x16x32_bf16 v[4:7], v[178:181], v[234:237], 0
	v_mfma_f32_16x16x32_bf16 v[0:3], v[186:189], v[234:237], 0
	v_mfma_f32_16x16x32_bf16 v[52:55], v[182:185], v[198:201], v[52:55]
	v_mfma_f32_16x16x32_bf16 v[48:51], v[190:193], v[198:201], v[48:51]
	v_mfma_f32_16x16x32_bf16 v[36:39], v[182:185], v[206:209], v[36:39]
	v_mfma_f32_16x16x32_bf16 v[32:35], v[190:193], v[206:209], v[32:35]
	v_mfma_f32_16x16x32_bf16 v[20:23], v[182:185], v[222:225], v[20:23]
	v_mfma_f32_16x16x32_bf16 v[16:19], v[190:193], v[222:225], v[16:19]
	v_mfma_f32_16x16x32_bf16 v[4:7], v[182:185], v[238:241], v[4:7]
	v_mfma_f32_16x16x32_bf16 v[0:3], v[190:193], v[238:241], v[0:3]
	s_setprio 0
	s_barrier
	s_add_i32 s22, 0, 0x18000
	v_add_u32_e32 v160, s22, v167
	s_add_i32 s23, 0, 0x1c000
	ds_read_b128 v[148:151], v160
	ds_read_b128 v[152:155], v160 offset:1024
	ds_read_b128 v[156:159], v160 offset:2048
	ds_read_b128 v[174:177], v160 offset:3072
	v_add_u32_e32 v160, s23, v167
	ds_read_b128 v[178:181], v160
	ds_read_b128 v[182:185], v160 offset:1024
	ds_read_b128 v[186:189], v160 offset:2048
	ds_read_b128 v[190:193], v160 offset:3072
	s_add_u32 s50, vcc_lo, 0x40000
	s_addc_u32 s51, vcc_hi, 0
	s_mov_b32 m0, s87
	v_lshl_add_u64 v[226:227], s[50:51], 0, v[128:129]
	ds_read_b128 v[194:197], v173 offset:32768
	ds_read_b128 v[198:201], v173 offset:33792
	ds_read_b128 v[202:205], v173 offset:34816
	ds_read_b128 v[206:209], v173 offset:35840
	ds_read_b128 v[210:213], v173 offset:36864
	ds_read_b128 v[222:225], v173 offset:37888
	ds_read_b128 v[234:237], v173 offset:38912
	ds_read_b128 v[238:241], v173 offset:39936
	global_load_lds_dwordx4 v[226:227], off
	v_lshl_add_u64 v[226:227], s[50:51], 0, v[132:133]
	s_mov_b32 m0, s88
	s_nop 0
	global_load_lds_dwordx4 v[226:227], off
	s_waitcnt vmcnt(8)
	s_waitcnt lgkmcnt(0)
	s_barrier
	s_setprio 1
	s_waitcnt lgkmcnt(0)
	v_mfma_f32_16x16x32_bf16 v[124:127], v[148:151], v[194:197], v[124:127]
	v_mfma_f32_16x16x32_bf16 v[120:123], v[156:159], v[194:197], v[120:123]
	v_mfma_f32_16x16x32_bf16 v[108:111], v[148:151], v[202:205], v[108:111]
	v_mfma_f32_16x16x32_bf16 v[104:107], v[156:159], v[202:205], v[104:107]
	v_mfma_f32_16x16x32_bf16 v[92:95], v[148:151], v[210:213], v[92:95]
	v_mfma_f32_16x16x32_bf16 v[88:91], v[156:159], v[210:213], v[88:91]
	v_mfma_f32_16x16x32_bf16 v[76:79], v[148:151], v[234:237], v[76:79]
	v_mfma_f32_16x16x32_bf16 v[72:75], v[156:159], v[234:237], v[72:75]
	v_mfma_f32_16x16x32_bf16 v[124:127], v[152:155], v[198:201], v[124:127]
	v_mfma_f32_16x16x32_bf16 v[120:123], v[174:177], v[198:201], v[120:123]
	v_mfma_f32_16x16x32_bf16 v[108:111], v[152:155], v[206:209], v[108:111]
	v_mfma_f32_16x16x32_bf16 v[104:107], v[174:177], v[206:209], v[104:107]
	v_mfma_f32_16x16x32_bf16 v[92:95], v[152:155], v[222:225], v[92:95]
	v_mfma_f32_16x16x32_bf16 v[88:91], v[174:177], v[222:225], v[88:91]
	v_mfma_f32_16x16x32_bf16 v[76:79], v[152:155], v[238:241], v[76:79]
	v_mfma_f32_16x16x32_bf16 v[72:75], v[174:177], v[238:241], v[72:75]
	v_mfma_f32_16x16x32_bf16 v[116:119], v[178:181], v[194:197], v[116:119]
	v_mfma_f32_16x16x32_bf16 v[112:115], v[186:189], v[194:197], v[112:115]
	v_mfma_f32_16x16x32_bf16 v[100:103], v[178:181], v[202:205], v[100:103]
	v_mfma_f32_16x16x32_bf16 v[96:99], v[186:189], v[202:205], v[96:99]
	v_mfma_f32_16x16x32_bf16 v[84:87], v[178:181], v[210:213], v[84:87]
	v_mfma_f32_16x16x32_bf16 v[80:83], v[186:189], v[210:213], v[80:83]
	v_mfma_f32_16x16x32_bf16 v[68:71], v[178:181], v[234:237], v[68:71]
	v_mfma_f32_16x16x32_bf16 v[64:67], v[186:189], v[234:237], v[64:67]
	v_mfma_f32_16x16x32_bf16 v[116:119], v[182:185], v[198:201], v[116:119]
	v_mfma_f32_16x16x32_bf16 v[112:115], v[190:193], v[198:201], v[112:115]
	v_mfma_f32_16x16x32_bf16 v[100:103], v[182:185], v[206:209], v[100:103]
	v_mfma_f32_16x16x32_bf16 v[96:99], v[190:193], v[206:209], v[96:99]
	v_mfma_f32_16x16x32_bf16 v[84:87], v[182:185], v[222:225], v[84:87]
	v_mfma_f32_16x16x32_bf16 v[80:83], v[190:193], v[222:225], v[80:83]
	v_mfma_f32_16x16x32_bf16 v[68:71], v[182:185], v[238:241], v[68:71]
	v_mfma_f32_16x16x32_bf16 v[64:67], v[190:193], v[238:241], v[64:67]
	s_setprio 0
	s_barrier
	s_add_i32 s22, s22, s80
	v_lshl_add_u64 v[162:163], v[162:163], 0, s[48:49]
	s_mov_b32 m0, s22
	ds_read_b128 v[194:197], v173 offset:49152
	ds_read_b128 v[198:201], v173 offset:50176
	ds_read_b128 v[202:205], v173 offset:51200
	ds_read_b128 v[206:209], v173 offset:52224
	ds_read_b128 v[210:213], v173 offset:53248
	ds_read_b128 v[222:225], v173 offset:54272
	ds_read_b128 v[234:237], v173 offset:55296
	ds_read_b128 v[238:241], v173 offset:56320
	global_load_lds_dwordx4 v[162:163], off
	s_add_i32 m0, s22, 0x2000
	s_add_u32 s50, s82, 0x40080
	v_lshl_add_u64 v[162:163], v[164:165], 0, s[48:49]
	s_addc_u32 s51, s83, 0
	s_add_i32 s22, s23, s80
	global_load_lds_dwordx4 v[162:163], off
	v_lshl_add_u64 v[162:163], s[50:51], 0, v[130:131]
	s_mov_b32 m0, s22
	s_nop 0
	global_load_lds_dwordx4 v[162:163], off
	v_lshl_add_u64 v[162:163], s[50:51], 0, v[134:135]
	s_add_i32 m0, s22, 0x2000
	s_nop 0
	global_load_lds_dwordx4 v[162:163], off
	v_lshl_add_u64 v[162:163], v[170:171], 0, s[48:49]
	s_mov_b32 m0, s90
	s_nop 0
	global_load_lds_dwordx4 v[162:163], off
	v_lshl_add_u64 v[162:163], v[214:215], 0, s[48:49]
	s_mov_b32 m0, s91
	s_nop 0
	global_load_lds_dwordx4 v[162:163], off
	s_waitcnt vmcnt(8)
	s_waitcnt lgkmcnt(0)
	s_barrier
	s_setprio 1
	s_waitcnt lgkmcnt(0)
	v_mfma_f32_16x16x32_bf16 v[60:63], v[148:151], v[194:197], v[60:63]
	v_mfma_f32_16x16x32_bf16 v[56:59], v[156:159], v[194:197], v[56:59]
	v_mfma_f32_16x16x32_bf16 v[44:47], v[148:151], v[202:205], v[44:47]
	v_mfma_f32_16x16x32_bf16 v[40:43], v[156:159], v[202:205], v[40:43]
	v_mfma_f32_16x16x32_bf16 v[28:31], v[148:151], v[210:213], v[28:31]
	v_mfma_f32_16x16x32_bf16 v[24:27], v[156:159], v[210:213], v[24:27]
	v_mfma_f32_16x16x32_bf16 v[12:15], v[148:151], v[234:237], v[12:15]
	v_mfma_f32_16x16x32_bf16 v[8:11], v[156:159], v[234:237], v[8:11]
	v_mfma_f32_16x16x32_bf16 v[60:63], v[152:155], v[198:201], v[60:63]
	v_mfma_f32_16x16x32_bf16 v[56:59], v[174:177], v[198:201], v[56:59]
	v_mfma_f32_16x16x32_bf16 v[44:47], v[152:155], v[206:209], v[44:47]
	v_mfma_f32_16x16x32_bf16 v[40:43], v[174:177], v[206:209], v[40:43]
	v_mfma_f32_16x16x32_bf16 v[28:31], v[152:155], v[222:225], v[28:31]
	v_mfma_f32_16x16x32_bf16 v[24:27], v[174:177], v[222:225], v[24:27]
	v_mfma_f32_16x16x32_bf16 v[12:15], v[152:155], v[238:241], v[12:15]
	v_mfma_f32_16x16x32_bf16 v[8:11], v[174:177], v[238:241], v[8:11]
	v_mfma_f32_16x16x32_bf16 v[52:55], v[178:181], v[194:197], v[52:55]
	v_mfma_f32_16x16x32_bf16 v[48:51], v[186:189], v[194:197], v[48:51]
	v_mfma_f32_16x16x32_bf16 v[36:39], v[178:181], v[202:205], v[36:39]
	v_mfma_f32_16x16x32_bf16 v[32:35], v[186:189], v[202:205], v[32:35]
	v_mfma_f32_16x16x32_bf16 v[20:23], v[178:181], v[210:213], v[20:23]
	v_mfma_f32_16x16x32_bf16 v[16:19], v[186:189], v[210:213], v[16:19]
	v_mfma_f32_16x16x32_bf16 v[4:7], v[178:181], v[234:237], v[4:7]
	v_mfma_f32_16x16x32_bf16 v[0:3], v[186:189], v[234:237], v[0:3]
	v_mfma_f32_16x16x32_bf16 v[52:55], v[182:185], v[198:201], v[52:55]
	v_mfma_f32_16x16x32_bf16 v[48:51], v[190:193], v[198:201], v[48:51]
	v_mfma_f32_16x16x32_bf16 v[36:39], v[182:185], v[206:209], v[36:39]
	v_mfma_f32_16x16x32_bf16 v[32:35], v[190:193], v[206:209], v[32:35]
	v_mfma_f32_16x16x32_bf16 v[20:23], v[182:185], v[222:225], v[20:23]
	v_mfma_f32_16x16x32_bf16 v[16:19], v[190:193], v[222:225], v[16:19]
	v_mfma_f32_16x16x32_bf16 v[4:7], v[182:185], v[238:241], v[4:7]
	v_mfma_f32_16x16x32_bf16 v[0:3], v[190:193], v[238:241], v[0:3]
	s_setprio 0
	s_barrier
	s_add_i32 s41, s41, 2
	s_add_u32 s42, s42, 0x100
	s_addc_u32 s43, s43, 0
	s_add_u32 s24, s24, 0x100
	s_addc_u32 s25, s25, 0
	s_cmp_gt_u32 s41, 13
.LBB0_253:
	s_add_u32 s22, s42, 0xfffc0080
	s_addc_u32 s23, s43, -1
	s_add_i32 s28, 0, 0x10000
	s_cmp_eq_u32 s41, 12
	s_cselect_b32 vcc_hi, s4, s23
	s_cselect_b32 vcc_lo, s11, s22
	v_add_u32_e32 v160, s28, v167
	s_cselect_b32 s83, s17, s25
	s_cselect_b32 s82, s19, s24
	s_add_i32 s22, 0, 0x14000
	ds_read_b128 v[148:151], v160
	ds_read_b128 v[152:155], v160 offset:1024
	ds_read_b128 v[156:159], v160 offset:2048
	ds_read_b128 v[174:177], v160 offset:3072
	v_add_u32_e32 v160, s22, v167
	ds_read_b128 v[178:181], v160
	ds_read_b128 v[182:185], v160 offset:1024
	ds_read_b128 v[186:189], v160 offset:2048
	ds_read_b128 v[190:193], v160 offset:3072
	v_lshl_add_u64 v[162:163], s[42:43], 0, v[144:145]
	s_add_i32 m0, s81, 0xc000
	ds_read_b128 v[194:197], v173
	ds_read_b128 v[198:201], v173 offset:1024
	ds_read_b128 v[202:205], v173 offset:2048
	ds_read_b128 v[206:209], v173 offset:3072
	ds_read_b128 v[210:213], v173 offset:4096
	ds_read_b128 v[222:225], v173 offset:5120
	ds_read_b128 v[234:237], v173 offset:6144
	ds_read_b128 v[238:241], v173 offset:7168
	global_load_lds_dwordx4 v[162:163], off
	v_lshl_add_u64 v[162:163], s[42:43], 0, v[146:147]
	s_add_i32 m0, s81, 0xe000
	s_nop 0
	global_load_lds_dwordx4 v[162:163], off
	s_waitcnt vmcnt(8)
	s_waitcnt lgkmcnt(0)
	s_barrier
	s_setprio 1
	s_waitcnt lgkmcnt(0)
	v_mfma_f32_16x16x32_bf16 v[124:127], v[148:151], v[194:197], v[124:127]
	v_mfma_f32_16x16x32_bf16 v[120:123], v[156:159], v[194:197], v[120:123]
	v_mfma_f32_16x16x32_bf16 v[108:111], v[148:151], v[202:205], v[108:111]
	v_mfma_f32_16x16x32_bf16 v[104:107], v[156:159], v[202:205], v[104:107]
	v_mfma_f32_16x16x32_bf16 v[92:95], v[148:151], v[210:213], v[92:95]
	v_mfma_f32_16x16x32_bf16 v[88:91], v[156:159], v[210:213], v[88:91]
	v_mfma_f32_16x16x32_bf16 v[76:79], v[148:151], v[234:237], v[76:79]
	v_mfma_f32_16x16x32_bf16 v[72:75], v[156:159], v[234:237], v[72:75]
	v_mfma_f32_16x16x32_bf16 v[124:127], v[152:155], v[198:201], v[124:127]
	v_mfma_f32_16x16x32_bf16 v[120:123], v[174:177], v[198:201], v[120:123]
	v_mfma_f32_16x16x32_bf16 v[108:111], v[152:155], v[206:209], v[108:111]
	v_mfma_f32_16x16x32_bf16 v[104:107], v[174:177], v[206:209], v[104:107]
	v_mfma_f32_16x16x32_bf16 v[92:95], v[152:155], v[222:225], v[92:95]
	v_mfma_f32_16x16x32_bf16 v[88:91], v[174:177], v[222:225], v[88:91]
	v_mfma_f32_16x16x32_bf16 v[76:79], v[152:155], v[238:241], v[76:79]
	v_mfma_f32_16x16x32_bf16 v[72:75], v[174:177], v[238:241], v[72:75]
	v_mfma_f32_16x16x32_bf16 v[116:119], v[178:181], v[194:197], v[116:119]
	v_mfma_f32_16x16x32_bf16 v[112:115], v[186:189], v[194:197], v[112:115]
	v_mfma_f32_16x16x32_bf16 v[100:103], v[178:181], v[202:205], v[100:103]
	v_mfma_f32_16x16x32_bf16 v[96:99], v[186:189], v[202:205], v[96:99]
	v_mfma_f32_16x16x32_bf16 v[84:87], v[178:181], v[210:213], v[84:87]
	v_mfma_f32_16x16x32_bf16 v[80:83], v[186:189], v[210:213], v[80:83]
	v_mfma_f32_16x16x32_bf16 v[68:71], v[178:181], v[234:237], v[68:71]
	v_mfma_f32_16x16x32_bf16 v[64:67], v[186:189], v[234:237], v[64:67]
	v_mfma_f32_16x16x32_bf16 v[116:119], v[182:185], v[198:201], v[116:119]
	v_mfma_f32_16x16x32_bf16 v[112:115], v[190:193], v[198:201], v[112:115]
	v_mfma_f32_16x16x32_bf16 v[100:103], v[182:185], v[206:209], v[100:103]
	v_mfma_f32_16x16x32_bf16 v[96:99], v[190:193], v[206:209], v[96:99]
	v_mfma_f32_16x16x32_bf16 v[84:87], v[182:185], v[222:225], v[84:87]
	v_mfma_f32_16x16x32_bf16 v[80:83], v[190:193], v[222:225], v[80:83]
	v_mfma_f32_16x16x32_bf16 v[68:71], v[182:185], v[238:241], v[68:71]
	v_mfma_f32_16x16x32_bf16 v[64:67], v[190:193], v[238:241], v[64:67]
	s_setprio 0
	s_barrier
	s_add_i32 s23, s28, s80
	v_lshl_add_u64 v[162:163], s[82:83], 0, v[130:131]
	s_mov_b32 m0, s23
	ds_read_b128 v[194:197], v173 offset:16384
	ds_read_b128 v[198:201], v173 offset:17408
	ds_read_b128 v[202:205], v173 offset:18432
	ds_read_b128 v[206:209], v173 offset:19456
	ds_read_b128 v[210:213], v173 offset:20480
	ds_read_b128 v[222:225], v173 offset:21504
	ds_read_b128 v[234:237], v173 offset:22528
	ds_read_b128 v[238:241], v173 offset:23552
	global_load_lds_dwordx4 v[162:163], off
	s_add_i32 m0, s23, 0x2000
	s_add_u32 s50, s82, 0x40000
	v_lshl_add_u64 v[164:165], s[82:83], 0, v[134:135]
	s_addc_u32 s51, s83, 0
	s_add_i32 s22, s22, s80
	global_load_lds_dwordx4 v[164:165], off
	v_lshl_add_u64 v[170:171], s[50:51], 0, v[130:131]
	s_mov_b32 m0, s22
	v_lshl_add_u64 v[214:215], vcc, 0, v[132:133]
	global_load_lds_dwordx4 v[170:171], off
	v_lshl_add_u64 v[170:171], s[50:51], 0, v[134:135]
	s_add_i32 m0, s22, 0x2000
	s_nop 0
	global_load_lds_dwordx4 v[170:171], off
	v_lshl_add_u64 v[170:171], vcc, 0, v[128:129]
	s_mov_b32 m0, s81
	s_nop 0
	global_load_lds_dwordx4 v[170:171], off
	s_mov_b32 m0, s86
	s_nop 0
	global_load_lds_dwordx4 v[214:215], off
	s_waitcnt vmcnt(8)
	s_waitcnt lgkmcnt(0)
	s_barrier
	s_setprio 1
	s_waitcnt lgkmcnt(0)
	v_mfma_f32_16x16x32_bf16 v[60:63], v[148:151], v[194:197], v[60:63]
	v_mfma_f32_16x16x32_bf16 v[56:59], v[156:159], v[194:197], v[56:59]
	v_mfma_f32_16x16x32_bf16 v[44:47], v[148:151], v[202:205], v[44:47]
	v_mfma_f32_16x16x32_bf16 v[40:43], v[156:159], v[202:205], v[40:43]
	v_mfma_f32_16x16x32_bf16 v[28:31], v[148:151], v[210:213], v[28:31]
	v_mfma_f32_16x16x32_bf16 v[24:27], v[156:159], v[210:213], v[24:27]
	v_mfma_f32_16x16x32_bf16 v[12:15], v[148:151], v[234:237], v[12:15]
	v_mfma_f32_16x16x32_bf16 v[8:11], v[156:159], v[234:237], v[8:11]
	v_mfma_f32_16x16x32_bf16 v[60:63], v[152:155], v[198:201], v[60:63]
	v_mfma_f32_16x16x32_bf16 v[56:59], v[174:177], v[198:201], v[56:59]
	v_mfma_f32_16x16x32_bf16 v[44:47], v[152:155], v[206:209], v[44:47]
	v_mfma_f32_16x16x32_bf16 v[40:43], v[174:177], v[206:209], v[40:43]
	v_mfma_f32_16x16x32_bf16 v[28:31], v[152:155], v[222:225], v[28:31]
	v_mfma_f32_16x16x32_bf16 v[24:27], v[174:177], v[222:225], v[24:27]
	v_mfma_f32_16x16x32_bf16 v[12:15], v[152:155], v[238:241], v[12:15]
	v_mfma_f32_16x16x32_bf16 v[8:11], v[174:177], v[238:241], v[8:11]
	v_mfma_f32_16x16x32_bf16 v[52:55], v[178:181], v[194:197], v[52:55]
	v_mfma_f32_16x16x32_bf16 v[48:51], v[186:189], v[194:197], v[48:51]
	v_mfma_f32_16x16x32_bf16 v[36:39], v[178:181], v[202:205], v[36:39]
	v_mfma_f32_16x16x32_bf16 v[32:35], v[186:189], v[202:205], v[32:35]
	v_mfma_f32_16x16x32_bf16 v[20:23], v[178:181], v[210:213], v[20:23]
	v_mfma_f32_16x16x32_bf16 v[16:19], v[186:189], v[210:213], v[16:19]
	v_mfma_f32_16x16x32_bf16 v[4:7], v[178:181], v[234:237], v[4:7]
	v_mfma_f32_16x16x32_bf16 v[0:3], v[186:189], v[234:237], v[0:3]
	v_mfma_f32_16x16x32_bf16 v[52:55], v[182:185], v[198:201], v[52:55]
	v_mfma_f32_16x16x32_bf16 v[48:51], v[190:193], v[198:201], v[48:51]
	v_mfma_f32_16x16x32_bf16 v[36:39], v[182:185], v[206:209], v[36:39]
	v_mfma_f32_16x16x32_bf16 v[32:35], v[190:193], v[206:209], v[32:35]
	v_mfma_f32_16x16x32_bf16 v[20:23], v[182:185], v[222:225], v[20:23]
	v_mfma_f32_16x16x32_bf16 v[16:19], v[190:193], v[222:225], v[16:19]
	v_mfma_f32_16x16x32_bf16 v[4:7], v[182:185], v[238:241], v[4:7]
	v_mfma_f32_16x16x32_bf16 v[0:3], v[190:193], v[238:241], v[0:3]
	s_setprio 0
	s_barrier
	s_add_i32 s22, 0, 0x18000
	v_add_u32_e32 v160, s22, v167
	s_add_i32 s23, 0, 0x1c000
	ds_read_b128 v[148:151], v160
	ds_read_b128 v[152:155], v160 offset:1024
	ds_read_b128 v[156:159], v160 offset:2048
	ds_read_b128 v[174:177], v160 offset:3072
	v_add_u32_e32 v160, s23, v167
	ds_read_b128 v[178:181], v160
	ds_read_b128 v[182:185], v160 offset:1024
	ds_read_b128 v[186:189], v160 offset:2048
	ds_read_b128 v[190:193], v160 offset:3072
	s_add_u32 s50, vcc_lo, 0x40000
	s_addc_u32 s51, vcc_hi, 0
	s_mov_b32 m0, s87
	v_lshl_add_u64 v[226:227], s[50:51], 0, v[128:129]
	ds_read_b128 v[194:197], v173 offset:32768
	ds_read_b128 v[198:201], v173 offset:33792
	ds_read_b128 v[202:205], v173 offset:34816
	ds_read_b128 v[206:209], v173 offset:35840
	ds_read_b128 v[210:213], v173 offset:36864
	ds_read_b128 v[222:225], v173 offset:37888
	ds_read_b128 v[234:237], v173 offset:38912
	ds_read_b128 v[238:241], v173 offset:39936
	global_load_lds_dwordx4 v[226:227], off
	v_lshl_add_u64 v[226:227], s[50:51], 0, v[132:133]
	s_mov_b32 m0, s88
	s_nop 0
	global_load_lds_dwordx4 v[226:227], off
	s_waitcnt vmcnt(8)
	s_waitcnt lgkmcnt(0)
	s_barrier
	s_setprio 1
	s_waitcnt lgkmcnt(0)
	v_mfma_f32_16x16x32_bf16 v[124:127], v[148:151], v[194:197], v[124:127]
	v_mfma_f32_16x16x32_bf16 v[120:123], v[156:159], v[194:197], v[120:123]
	v_mfma_f32_16x16x32_bf16 v[108:111], v[148:151], v[202:205], v[108:111]
	v_mfma_f32_16x16x32_bf16 v[104:107], v[156:159], v[202:205], v[104:107]
	v_mfma_f32_16x16x32_bf16 v[92:95], v[148:151], v[210:213], v[92:95]
	v_mfma_f32_16x16x32_bf16 v[88:91], v[156:159], v[210:213], v[88:91]
	v_mfma_f32_16x16x32_bf16 v[76:79], v[148:151], v[234:237], v[76:79]
	v_mfma_f32_16x16x32_bf16 v[72:75], v[156:159], v[234:237], v[72:75]
	v_mfma_f32_16x16x32_bf16 v[124:127], v[152:155], v[198:201], v[124:127]
	v_mfma_f32_16x16x32_bf16 v[120:123], v[174:177], v[198:201], v[120:123]
	v_mfma_f32_16x16x32_bf16 v[108:111], v[152:155], v[206:209], v[108:111]
	v_mfma_f32_16x16x32_bf16 v[104:107], v[174:177], v[206:209], v[104:107]
	v_mfma_f32_16x16x32_bf16 v[92:95], v[152:155], v[222:225], v[92:95]
	v_mfma_f32_16x16x32_bf16 v[88:91], v[174:177], v[222:225], v[88:91]
	v_mfma_f32_16x16x32_bf16 v[76:79], v[152:155], v[238:241], v[76:79]
	v_mfma_f32_16x16x32_bf16 v[72:75], v[174:177], v[238:241], v[72:75]
	v_mfma_f32_16x16x32_bf16 v[116:119], v[178:181], v[194:197], v[116:119]
	v_mfma_f32_16x16x32_bf16 v[112:115], v[186:189], v[194:197], v[112:115]
	v_mfma_f32_16x16x32_bf16 v[100:103], v[178:181], v[202:205], v[100:103]
	v_mfma_f32_16x16x32_bf16 v[96:99], v[186:189], v[202:205], v[96:99]
	v_mfma_f32_16x16x32_bf16 v[84:87], v[178:181], v[210:213], v[84:87]
	v_mfma_f32_16x16x32_bf16 v[80:83], v[186:189], v[210:213], v[80:83]
	v_mfma_f32_16x16x32_bf16 v[68:71], v[178:181], v[234:237], v[68:71]
	v_mfma_f32_16x16x32_bf16 v[64:67], v[186:189], v[234:237], v[64:67]
	v_mfma_f32_16x16x32_bf16 v[116:119], v[182:185], v[198:201], v[116:119]
	v_mfma_f32_16x16x32_bf16 v[112:115], v[190:193], v[198:201], v[112:115]
	v_mfma_f32_16x16x32_bf16 v[100:103], v[182:185], v[206:209], v[100:103]
	v_mfma_f32_16x16x32_bf16 v[96:99], v[190:193], v[206:209], v[96:99]
	v_mfma_f32_16x16x32_bf16 v[84:87], v[182:185], v[222:225], v[84:87]
	v_mfma_f32_16x16x32_bf16 v[80:83], v[190:193], v[222:225], v[80:83]
	v_mfma_f32_16x16x32_bf16 v[68:71], v[182:185], v[238:241], v[68:71]
	v_mfma_f32_16x16x32_bf16 v[64:67], v[190:193], v[238:241], v[64:67]
	s_setprio 0
	s_barrier
	s_add_i32 s22, s22, s80
	v_lshl_add_u64 v[162:163], v[162:163], 0, s[48:49]
	s_mov_b32 m0, s22
	ds_read_b128 v[194:197], v173 offset:49152
	ds_read_b128 v[198:201], v173 offset:50176
	ds_read_b128 v[202:205], v173 offset:51200
	ds_read_b128 v[206:209], v173 offset:52224
	ds_read_b128 v[210:213], v173 offset:53248
	ds_read_b128 v[222:225], v173 offset:54272
	ds_read_b128 v[234:237], v173 offset:55296
	ds_read_b128 v[238:241], v173 offset:56320
	global_load_lds_dwordx4 v[162:163], off
	s_add_i32 m0, s22, 0x2000
	s_add_u32 s50, s82, 0x40080
	v_lshl_add_u64 v[162:163], v[164:165], 0, s[48:49]
	s_addc_u32 s51, s83, 0
	s_add_i32 s22, s23, s80
	global_load_lds_dwordx4 v[162:163], off
	v_lshl_add_u64 v[162:163], s[50:51], 0, v[130:131]
	s_mov_b32 m0, s22
	s_nop 0
	global_load_lds_dwordx4 v[162:163], off
	v_lshl_add_u64 v[162:163], s[50:51], 0, v[134:135]
	s_add_i32 m0, s22, 0x2000
	s_nop 0
	global_load_lds_dwordx4 v[162:163], off
	v_lshl_add_u64 v[162:163], v[170:171], 0, s[48:49]
	s_mov_b32 m0, s90
	s_nop 0
	global_load_lds_dwordx4 v[162:163], off
	v_lshl_add_u64 v[162:163], v[214:215], 0, s[48:49]
	s_mov_b32 m0, s91
	s_nop 0
	global_load_lds_dwordx4 v[162:163], off
	s_waitcnt vmcnt(8)
	s_waitcnt lgkmcnt(0)
	s_barrier
	s_setprio 1
	s_waitcnt lgkmcnt(0)
	v_mfma_f32_16x16x32_bf16 v[60:63], v[148:151], v[194:197], v[60:63]
	v_mfma_f32_16x16x32_bf16 v[56:59], v[156:159], v[194:197], v[56:59]
	v_mfma_f32_16x16x32_bf16 v[44:47], v[148:151], v[202:205], v[44:47]
	v_mfma_f32_16x16x32_bf16 v[40:43], v[156:159], v[202:205], v[40:43]
	v_mfma_f32_16x16x32_bf16 v[28:31], v[148:151], v[210:213], v[28:31]
	v_mfma_f32_16x16x32_bf16 v[24:27], v[156:159], v[210:213], v[24:27]
	v_mfma_f32_16x16x32_bf16 v[12:15], v[148:151], v[234:237], v[12:15]
	v_mfma_f32_16x16x32_bf16 v[8:11], v[156:159], v[234:237], v[8:11]
	v_mfma_f32_16x16x32_bf16 v[60:63], v[152:155], v[198:201], v[60:63]
	v_mfma_f32_16x16x32_bf16 v[56:59], v[174:177], v[198:201], v[56:59]
	v_mfma_f32_16x16x32_bf16 v[44:47], v[152:155], v[206:209], v[44:47]
	v_mfma_f32_16x16x32_bf16 v[40:43], v[174:177], v[206:209], v[40:43]
	v_mfma_f32_16x16x32_bf16 v[28:31], v[152:155], v[222:225], v[28:31]
	v_mfma_f32_16x16x32_bf16 v[24:27], v[174:177], v[222:225], v[24:27]
	v_mfma_f32_16x16x32_bf16 v[12:15], v[152:155], v[238:241], v[12:15]
	v_mfma_f32_16x16x32_bf16 v[8:11], v[174:177], v[238:241], v[8:11]
	v_mfma_f32_16x16x32_bf16 v[52:55], v[178:181], v[194:197], v[52:55]
	v_mfma_f32_16x16x32_bf16 v[48:51], v[186:189], v[194:197], v[48:51]
	v_mfma_f32_16x16x32_bf16 v[36:39], v[178:181], v[202:205], v[36:39]
	v_mfma_f32_16x16x32_bf16 v[32:35], v[186:189], v[202:205], v[32:35]
	v_mfma_f32_16x16x32_bf16 v[20:23], v[178:181], v[210:213], v[20:23]
	v_mfma_f32_16x16x32_bf16 v[16:19], v[186:189], v[210:213], v[16:19]
	v_mfma_f32_16x16x32_bf16 v[4:7], v[178:181], v[234:237], v[4:7]
	v_mfma_f32_16x16x32_bf16 v[0:3], v[186:189], v[234:237], v[0:3]
	v_mfma_f32_16x16x32_bf16 v[52:55], v[182:185], v[198:201], v[52:55]
	v_mfma_f32_16x16x32_bf16 v[48:51], v[190:193], v[198:201], v[48:51]
	v_mfma_f32_16x16x32_bf16 v[36:39], v[182:185], v[206:209], v[36:39]
	v_mfma_f32_16x16x32_bf16 v[32:35], v[190:193], v[206:209], v[32:35]
	v_mfma_f32_16x16x32_bf16 v[20:23], v[182:185], v[222:225], v[20:23]
	v_mfma_f32_16x16x32_bf16 v[16:19], v[190:193], v[222:225], v[16:19]
	v_mfma_f32_16x16x32_bf16 v[4:7], v[182:185], v[238:241], v[4:7]
	v_mfma_f32_16x16x32_bf16 v[0:3], v[190:193], v[238:241], v[0:3]
	s_setprio 0
	s_barrier
	s_add_i32 s41, s41, 2
	s_add_u32 s42, s42, 0x100
	s_addc_u32 s43, s43, 0
	s_add_u32 s24, s24, 0x100
	s_addc_u32 s25, s25, 0
	s_cmp_gt_u32 s41, 13
	s_cbranch_scc0 .LBB0_253
	s_and_b64 vcc, exec, s[12:13]
	s_cbranch_vccz .LBB0_256
	s_barrier

.LBB0_377:
	s_add_u32 s40, s82, 0x80
	s_addc_u32 s41, s83, 0
	s_add_u32 s4, s84, 0x100
	s_addc_u32 s84, s85, 0
	s_mov_b32 s82, 0
	s_add_i32 s85, s82, 2
	s_add_u32 vcc_lo, s40, 0x80
	s_addc_u32 s83, s41, 0
	s_add_i32 s28, 0, 0x10000
	s_cmp_eq_u32 s95, s82
	s_cselect_b32 s83, s19, s83
	s_cselect_b32 s82, s18, vcc_lo
	s_cselect_b32 vcc_hi, s43, s84
	s_cselect_b32 vcc_lo, s42, s4
	s_add_i32 s22, 0, 0x14000
	v_add_u32_e32 v140, s28, v169
	v_add_u32_e32 v162, s22, v169
	ds_read_b128 v[128:131], v140
	ds_read_b128 v[132:135], v140 offset:1024
	ds_read_b128 v[136:139], v140 offset:2048
	ds_read_b128 v[140:143], v140 offset:3072
	ds_read_b128 v[144:147], v162
	ds_read_b128 v[148:151], v162 offset:1024
	ds_read_b128 v[152:155], v162 offset:2048
	ds_read_b128 v[180:183], v162 offset:3072
	v_lshl_add_u64 v[162:163], s[40:41], 0, v[176:177]
	s_add_i32 m0, s86, 0xc000
	ds_read_b128 v[184:187], v205
	ds_read_b128 v[188:191], v205 offset:1024
	ds_read_b128 v[192:195], v205 offset:2048
	ds_read_b128 v[196:199], v205 offset:3072
	ds_read_b128 v[206:209], v205 offset:4096
	ds_read_b128 v[210:213], v205 offset:5120
	ds_read_b128 v[222:225], v205 offset:6144
	ds_read_b128 v[234:237], v205 offset:7168
	global_load_lds_dwordx4 v[162:163], off
	v_lshl_add_u64 v[162:163], s[40:41], 0, v[178:179]
	s_add_i32 m0, s86, 0xe000
	s_nop 0
	global_load_lds_dwordx4 v[162:163], off
	s_waitcnt vmcnt(8)
	s_waitcnt lgkmcnt(0)
	s_barrier
	s_setprio 1
	s_waitcnt lgkmcnt(0)
	v_mfma_f32_16x16x32_bf16 v[124:127], v[128:131], v[184:187], 0
	v_mfma_f32_16x16x32_bf16 v[120:123], v[136:139], v[184:187], 0
	v_mfma_f32_16x16x32_bf16 v[108:111], v[128:131], v[192:195], 0
	v_mfma_f32_16x16x32_bf16 v[104:107], v[136:139], v[192:195], 0
	v_mfma_f32_16x16x32_bf16 v[92:95], v[128:131], v[206:209], 0
	v_mfma_f32_16x16x32_bf16 v[88:91], v[136:139], v[206:209], 0
	v_mfma_f32_16x16x32_bf16 v[76:79], v[128:131], v[222:225], 0
	v_mfma_f32_16x16x32_bf16 v[72:75], v[136:139], v[222:225], 0
	v_mfma_f32_16x16x32_bf16 v[124:127], v[132:135], v[188:191], v[124:127]
	v_mfma_f32_16x16x32_bf16 v[120:123], v[140:143], v[188:191], v[120:123]
	v_mfma_f32_16x16x32_bf16 v[108:111], v[132:135], v[196:199], v[108:111]
	v_mfma_f32_16x16x32_bf16 v[104:107], v[140:143], v[196:199], v[104:107]
	v_mfma_f32_16x16x32_bf16 v[92:95], v[132:135], v[210:213], v[92:95]
	v_mfma_f32_16x16x32_bf16 v[88:91], v[140:143], v[210:213], v[88:91]
	v_mfma_f32_16x16x32_bf16 v[76:79], v[132:135], v[234:237], v[76:79]
	v_mfma_f32_16x16x32_bf16 v[72:75], v[140:143], v[234:237], v[72:75]
	v_mfma_f32_16x16x32_bf16 v[116:119], v[144:147], v[184:187], 0
	v_mfma_f32_16x16x32_bf16 v[112:115], v[152:155], v[184:187], 0
	v_mfma_f32_16x16x32_bf16 v[100:103], v[144:147], v[192:195], 0
	v_mfma_f32_16x16x32_bf16 v[96:99], v[152:155], v[192:195], 0
	v_mfma_f32_16x16x32_bf16 v[84:87], v[144:147], v[206:209], 0
	v_mfma_f32_16x16x32_bf16 v[80:83], v[152:155], v[206:209], 0
	v_mfma_f32_16x16x32_bf16 v[68:71], v[144:147], v[222:225], 0
	v_mfma_f32_16x16x32_bf16 v[64:67], v[152:155], v[222:225], 0
	v_mfma_f32_16x16x32_bf16 v[116:119], v[148:151], v[188:191], v[116:119]
	v_mfma_f32_16x16x32_bf16 v[112:115], v[180:183], v[188:191], v[112:115]
	v_mfma_f32_16x16x32_bf16 v[100:103], v[148:151], v[196:199], v[100:103]
	v_mfma_f32_16x16x32_bf16 v[96:99], v[180:183], v[196:199], v[96:99]
	v_mfma_f32_16x16x32_bf16 v[84:87], v[148:151], v[210:213], v[84:87]
	v_mfma_f32_16x16x32_bf16 v[80:83], v[180:183], v[210:213], v[80:83]
	v_mfma_f32_16x16x32_bf16 v[68:71], v[148:151], v[234:237], v[68:71]
	v_mfma_f32_16x16x32_bf16 v[64:67], v[180:183], v[234:237], v[64:67]
	s_setprio 0
	s_barrier
	s_add_i32 s23, s28, s81
	v_lshl_add_u64 v[162:163], vcc, 0, v[160:161]
	s_mov_b32 m0, s23
	ds_read_b128 v[184:187], v205 offset:16384
	ds_read_b128 v[188:191], v205 offset:17408
	ds_read_b128 v[192:195], v205 offset:18432
	ds_read_b128 v[196:199], v205 offset:19456
	ds_read_b128 v[206:209], v205 offset:20480
	ds_read_b128 v[210:213], v205 offset:21504
	ds_read_b128 v[222:225], v205 offset:22528
	ds_read_b128 v[234:237], v205 offset:23552
	global_load_lds_dwordx4 v[162:163], off
	s_add_i32 m0, s23, 0x2000
	v_lshl_add_u64 v[164:165], vcc, 0, v[170:171]
	s_add_u32 vcc_lo, vcc_lo, s8
	s_addc_u32 vcc_hi, vcc_hi, 0
	s_add_i32 s22, s22, s81
	global_load_lds_dwordx4 v[164:165], off
	v_lshl_add_u64 v[200:201], vcc, 0, v[160:161]
	s_mov_b32 m0, s22
	v_lshl_add_u64 v[214:215], vcc, 0, v[170:171]
	global_load_lds_dwordx4 v[200:201], off
	s_add_i32 m0, s22, 0x2000
	v_lshl_add_u64 v[226:227], s[82:83], 0, v[156:157]
	global_load_lds_dwordx4 v[214:215], off
	s_mov_b32 m0, s86
	v_lshl_add_u64 v[238:239], s[82:83], 0, v[158:159]
	global_load_lds_dwordx4 v[226:227], off
	s_mov_b32 m0, s87
	s_nop 0
	global_load_lds_dwordx4 v[238:239], off
	s_waitcnt vmcnt(8)
	s_waitcnt lgkmcnt(0)
	s_barrier
	s_setprio 1
	s_waitcnt lgkmcnt(0)
	v_mfma_f32_16x16x32_bf16 v[60:63], v[128:131], v[184:187], 0
	v_mfma_f32_16x16x32_bf16 v[56:59], v[136:139], v[184:187], 0
	v_mfma_f32_16x16x32_bf16 v[44:47], v[128:131], v[192:195], 0
	v_mfma_f32_16x16x32_bf16 v[40:43], v[136:139], v[192:195], 0
	v_mfma_f32_16x16x32_bf16 v[28:31], v[128:131], v[206:209], 0
	v_mfma_f32_16x16x32_bf16 v[24:27], v[136:139], v[206:209], 0
	v_mfma_f32_16x16x32_bf16 v[12:15], v[128:131], v[222:225], 0
	v_mfma_f32_16x16x32_bf16 v[8:11], v[136:139], v[222:225], 0
	v_mfma_f32_16x16x32_bf16 v[60:63], v[132:135], v[188:191], v[60:63]
	v_mfma_f32_16x16x32_bf16 v[56:59], v[140:143], v[188:191], v[56:59]
	v_mfma_f32_16x16x32_bf16 v[44:47], v[132:135], v[196:199], v[44:47]
	v_mfma_f32_16x16x32_bf16 v[40:43], v[140:143], v[196:199], v[40:43]
	v_mfma_f32_16x16x32_bf16 v[28:31], v[132:135], v[210:213], v[28:31]
	v_mfma_f32_16x16x32_bf16 v[24:27], v[140:143], v[210:213], v[24:27]
	v_mfma_f32_16x16x32_bf16 v[12:15], v[132:135], v[234:237], v[12:15]
	v_mfma_f32_16x16x32_bf16 v[8:11], v[140:143], v[234:237], v[8:11]
	v_mfma_f32_16x16x32_bf16 v[52:55], v[144:147], v[184:187], 0
	v_mfma_f32_16x16x32_bf16 v[48:51], v[152:155], v[184:187], 0
	v_mfma_f32_16x16x32_bf16 v[36:39], v[144:147], v[192:195], 0
	v_mfma_f32_16x16x32_bf16 v[32:35], v[152:155], v[192:195], 0
	v_mfma_f32_16x16x32_bf16 v[20:23], v[144:147], v[206:209], 0
	v_mfma_f32_16x16x32_bf16 v[16:19], v[152:155], v[206:209], 0
	v_mfma_f32_16x16x32_bf16 v[4:7], v[144:147], v[222:225], 0
	v_mfma_f32_16x16x32_bf16 v[0:3], v[152:155], v[222:225], 0
	v_mfma_f32_16x16x32_bf16 v[52:55], v[148:151], v[188:191], v[52:55]
	v_mfma_f32_16x16x32_bf16 v[48:51], v[180:183], v[188:191], v[48:51]
	v_mfma_f32_16x16x32_bf16 v[36:39], v[148:151], v[196:199], v[36:39]
	v_mfma_f32_16x16x32_bf16 v[32:35], v[180:183], v[196:199], v[32:35]
	v_mfma_f32_16x16x32_bf16 v[20:23], v[148:151], v[210:213], v[20:23]
	v_mfma_f32_16x16x32_bf16 v[16:19], v[180:183], v[210:213], v[16:19]
	v_mfma_f32_16x16x32_bf16 v[4:7], v[148:151], v[234:237], v[4:7]
	v_mfma_f32_16x16x32_bf16 v[0:3], v[180:183], v[234:237], v[0:3]
	s_setprio 0
	s_barrier
	s_add_i32 s22, 0, 0x18000
	s_add_i32 s23, 0, 0x1c000
	v_add_u32_e32 v140, s22, v169
	v_add_u32_e32 v173, s23, v169
	ds_read_b128 v[128:131], v140
	ds_read_b128 v[132:135], v140 offset:1024
	ds_read_b128 v[136:139], v140 offset:2048
	ds_read_b128 v[140:143], v140 offset:3072
	ds_read_b128 v[144:147], v173
	ds_read_b128 v[148:151], v173 offset:1024
	ds_read_b128 v[152:155], v173 offset:2048
	ds_read_b128 v[180:183], v173 offset:3072
	s_add_u32 s82, s82, s8
	s_addc_u32 s83, s83, 0
	s_mov_b32 m0, s88
	v_lshl_add_u64 v[240:241], s[82:83], 0, v[156:157]
	ds_read_b128 v[184:187], v205 offset:32768
	ds_read_b128 v[188:191], v205 offset:33792
	ds_read_b128 v[192:195], v205 offset:34816
	ds_read_b128 v[196:199], v205 offset:35840
	ds_read_b128 v[206:209], v205 offset:36864
	ds_read_b128 v[210:213], v205 offset:37888
	ds_read_b128 v[222:225], v205 offset:38912
	ds_read_b128 v[234:237], v205 offset:39936
	global_load_lds_dwordx4 v[240:241], off
	v_lshl_add_u64 v[240:241], s[82:83], 0, v[158:159]
	s_mov_b32 m0, s89
	s_nop 0
	global_load_lds_dwordx4 v[240:241], off
	s_waitcnt vmcnt(8)
	s_waitcnt lgkmcnt(0)
	s_barrier
	s_setprio 1
	s_waitcnt lgkmcnt(0)
	v_mfma_f32_16x16x32_bf16 v[124:127], v[128:131], v[184:187], v[124:127]
	v_mfma_f32_16x16x32_bf16 v[120:123], v[136:139], v[184:187], v[120:123]
	v_mfma_f32_16x16x32_bf16 v[108:111], v[128:131], v[192:195], v[108:111]
	v_mfma_f32_16x16x32_bf16 v[104:107], v[136:139], v[192:195], v[104:107]
	v_mfma_f32_16x16x32_bf16 v[92:95], v[128:131], v[206:209], v[92:95]
	v_mfma_f32_16x16x32_bf16 v[88:91], v[136:139], v[206:209], v[88:91]
	v_mfma_f32_16x16x32_bf16 v[76:79], v[128:131], v[222:225], v[76:79]
	v_mfma_f32_16x16x32_bf16 v[72:75], v[136:139], v[222:225], v[72:75]
	v_mfma_f32_16x16x32_bf16 v[124:127], v[132:135], v[188:191], v[124:127]
	v_mfma_f32_16x16x32_bf16 v[120:123], v[140:143], v[188:191], v[120:123]
	v_mfma_f32_16x16x32_bf16 v[108:111], v[132:135], v[196:199], v[108:111]
	v_mfma_f32_16x16x32_bf16 v[104:107], v[140:143], v[196:199], v[104:107]
	v_mfma_f32_16x16x32_bf16 v[92:95], v[132:135], v[210:213], v[92:95]
	v_mfma_f32_16x16x32_bf16 v[88:91], v[140:143], v[210:213], v[88:91]
	v_mfma_f32_16x16x32_bf16 v[76:79], v[132:135], v[234:237], v[76:79]
	v_mfma_f32_16x16x32_bf16 v[72:75], v[140:143], v[234:237], v[72:75]
	v_mfma_f32_16x16x32_bf16 v[116:119], v[144:147], v[184:187], v[116:119]
	v_mfma_f32_16x16x32_bf16 v[112:115], v[152:155], v[184:187], v[112:115]
	v_mfma_f32_16x16x32_bf16 v[100:103], v[144:147], v[192:195], v[100:103]
	v_mfma_f32_16x16x32_bf16 v[96:99], v[152:155], v[192:195], v[96:99]
	v_mfma_f32_16x16x32_bf16 v[84:87], v[144:147], v[206:209], v[84:87]
	v_mfma_f32_16x16x32_bf16 v[80:83], v[152:155], v[206:209], v[80:83]
	v_mfma_f32_16x16x32_bf16 v[68:71], v[144:147], v[222:225], v[68:71]
	v_mfma_f32_16x16x32_bf16 v[64:67], v[152:155], v[222:225], v[64:67]
	v_mfma_f32_16x16x32_bf16 v[116:119], v[148:151], v[188:191], v[116:119]
	v_mfma_f32_16x16x32_bf16 v[112:115], v[180:183], v[188:191], v[112:115]
	v_mfma_f32_16x16x32_bf16 v[100:103], v[148:151], v[196:199], v[100:103]
	v_mfma_f32_16x16x32_bf16 v[96:99], v[180:183], v[196:199], v[96:99]
	v_mfma_f32_16x16x32_bf16 v[84:87], v[148:151], v[210:213], v[84:87]
	v_mfma_f32_16x16x32_bf16 v[80:83], v[180:183], v[210:213], v[80:83]
	v_mfma_f32_16x16x32_bf16 v[68:71], v[148:151], v[234:237], v[68:71]
	v_mfma_f32_16x16x32_bf16 v[64:67], v[180:183], v[234:237], v[64:67]
	s_setprio 0
	s_barrier
	s_add_i32 s22, s22, s81
	v_lshl_add_u64 v[162:163], v[162:163], 0, s[48:49]
	s_mov_b32 m0, s22
	ds_read_b128 v[184:187], v205 offset:49152
	ds_read_b128 v[188:191], v205 offset:50176
	ds_read_b128 v[192:195], v205 offset:51200
	ds_read_b128 v[196:199], v205 offset:52224
	ds_read_b128 v[206:209], v205 offset:53248
	ds_read_b128 v[210:213], v205 offset:54272
	ds_read_b128 v[222:225], v205 offset:55296
	ds_read_b128 v[234:237], v205 offset:56320
	global_load_lds_dwordx4 v[162:163], off
	v_lshl_add_u64 v[162:163], v[164:165], 0, s[48:49]
	s_add_i32 m0, s22, 0x2000
	s_add_i32 s22, s23, s81
	global_load_lds_dwordx4 v[162:163], off
	v_lshl_add_u64 v[162:163], v[200:201], 0, s[48:49]
	s_mov_b32 m0, s22
	s_nop 0
	global_load_lds_dwordx4 v[162:163], off
	v_lshl_add_u64 v[162:163], v[214:215], 0, s[48:49]
	s_add_i32 m0, s22, 0x2000
	s_nop 0
	global_load_lds_dwordx4 v[162:163], off
	v_lshl_add_u64 v[162:163], v[226:227], 0, s[48:49]
	s_mov_b32 m0, s90
	s_nop 0
	global_load_lds_dwordx4 v[162:163], off
	v_lshl_add_u64 v[162:163], v[238:239], 0, s[48:49]
	s_mov_b32 m0, s91
	s_nop 0
	global_load_lds_dwordx4 v[162:163], off
	s_waitcnt vmcnt(8)
	s_waitcnt lgkmcnt(0)
	s_barrier
	s_setprio 1
	s_waitcnt lgkmcnt(0)
	v_mfma_f32_16x16x32_bf16 v[60:63], v[128:131], v[184:187], v[60:63]
	v_mfma_f32_16x16x32_bf16 v[56:59], v[136:139], v[184:187], v[56:59]
	v_mfma_f32_16x16x32_bf16 v[44:47], v[128:131], v[192:195], v[44:47]
	v_mfma_f32_16x16x32_bf16 v[40:43], v[136:139], v[192:195], v[40:43]
	v_mfma_f32_16x16x32_bf16 v[28:31], v[128:131], v[206:209], v[28:31]
	v_mfma_f32_16x16x32_bf16 v[24:27], v[136:139], v[206:209], v[24:27]
	v_mfma_f32_16x16x32_bf16 v[12:15], v[128:131], v[222:225], v[12:15]
	v_mfma_f32_16x16x32_bf16 v[8:11], v[136:139], v[222:225], v[8:11]
	v_mfma_f32_16x16x32_bf16 v[60:63], v[132:135], v[188:191], v[60:63]
	v_mfma_f32_16x16x32_bf16 v[56:59], v[140:143], v[188:191], v[56:59]
	v_mfma_f32_16x16x32_bf16 v[44:47], v[132:135], v[196:199], v[44:47]
	v_mfma_f32_16x16x32_bf16 v[40:43], v[140:143], v[196:199], v[40:43]
	v_mfma_f32_16x16x32_bf16 v[28:31], v[132:135], v[210:213], v[28:31]
	v_mfma_f32_16x16x32_bf16 v[24:27], v[140:143], v[210:213], v[24:27]
	v_mfma_f32_16x16x32_bf16 v[12:15], v[132:135], v[234:237], v[12:15]
	v_mfma_f32_16x16x32_bf16 v[8:11], v[140:143], v[234:237], v[8:11]
	v_mfma_f32_16x16x32_bf16 v[52:55], v[144:147], v[184:187], v[52:55]
	v_mfma_f32_16x16x32_bf16 v[48:51], v[152:155], v[184:187], v[48:51]
	v_mfma_f32_16x16x32_bf16 v[36:39], v[144:147], v[192:195], v[36:39]
	v_mfma_f32_16x16x32_bf16 v[32:35], v[152:155], v[192:195], v[32:35]
	v_mfma_f32_16x16x32_bf16 v[20:23], v[144:147], v[206:209], v[20:23]
	v_mfma_f32_16x16x32_bf16 v[16:19], v[152:155], v[206:209], v[16:19]
	v_mfma_f32_16x16x32_bf16 v[4:7], v[144:147], v[222:225], v[4:7]
	v_mfma_f32_16x16x32_bf16 v[0:3], v[152:155], v[222:225], v[0:3]
	v_mfma_f32_16x16x32_bf16 v[52:55], v[148:151], v[188:191], v[52:55]
	v_mfma_f32_16x16x32_bf16 v[48:51], v[180:183], v[188:191], v[48:51]
	v_mfma_f32_16x16x32_bf16 v[36:39], v[148:151], v[196:199], v[36:39]
	v_mfma_f32_16x16x32_bf16 v[32:35], v[180:183], v[196:199], v[32:35]
	v_mfma_f32_16x16x32_bf16 v[20:23], v[148:151], v[210:213], v[20:23]
	v_mfma_f32_16x16x32_bf16 v[16:19], v[180:183], v[210:213], v[16:19]
	v_mfma_f32_16x16x32_bf16 v[4:7], v[148:151], v[234:237], v[4:7]
	v_mfma_f32_16x16x32_bf16 v[0:3], v[180:183], v[234:237], v[0:3]
	s_setprio 0
	s_barrier
	s_add_u32 s40, s40, 0x100
	s_addc_u32 s41, s41, 0
	s_add_u32 s4, s4, 0x100
	s_addc_u32 s84, s84, 0
	s_cmp_ge_u32 s85, s94
	s_mov_b32 s82, s85
.LBB0_378:
	s_add_i32 s85, s82, 2
	s_add_u32 vcc_lo, s40, 0x80
	s_addc_u32 s83, s41, 0
	s_add_i32 s28, 0, 0x10000
	s_cmp_eq_u32 s95, s82
	s_cselect_b32 s83, s19, s83
	s_cselect_b32 s82, s18, vcc_lo
	s_cselect_b32 vcc_hi, s43, s84
	s_cselect_b32 vcc_lo, s42, s4
	s_add_i32 s22, 0, 0x14000
	v_add_u32_e32 v140, s28, v169
	v_add_u32_e32 v162, s22, v169
	ds_read_b128 v[128:131], v140
	ds_read_b128 v[132:135], v140 offset:1024
	ds_read_b128 v[136:139], v140 offset:2048
	ds_read_b128 v[140:143], v140 offset:3072
	ds_read_b128 v[144:147], v162
	ds_read_b128 v[148:151], v162 offset:1024
	ds_read_b128 v[152:155], v162 offset:2048
	ds_read_b128 v[180:183], v162 offset:3072
	v_lshl_add_u64 v[162:163], s[40:41], 0, v[176:177]
	s_add_i32 m0, s86, 0xc000
	ds_read_b128 v[184:187], v205
	ds_read_b128 v[188:191], v205 offset:1024
	ds_read_b128 v[192:195], v205 offset:2048
	ds_read_b128 v[196:199], v205 offset:3072
	ds_read_b128 v[206:209], v205 offset:4096
	ds_read_b128 v[210:213], v205 offset:5120
	ds_read_b128 v[222:225], v205 offset:6144
	ds_read_b128 v[234:237], v205 offset:7168
	global_load_lds_dwordx4 v[162:163], off
	v_lshl_add_u64 v[162:163], s[40:41], 0, v[178:179]
	s_add_i32 m0, s86, 0xe000
	s_nop 0
	global_load_lds_dwordx4 v[162:163], off
	s_waitcnt vmcnt(8)
	s_waitcnt lgkmcnt(0)
	s_barrier
	s_setprio 1
	s_waitcnt lgkmcnt(0)
	v_mfma_f32_16x16x32_bf16 v[124:127], v[128:131], v[184:187], v[124:127]
	v_mfma_f32_16x16x32_bf16 v[120:123], v[136:139], v[184:187], v[120:123]
	v_mfma_f32_16x16x32_bf16 v[108:111], v[128:131], v[192:195], v[108:111]
	v_mfma_f32_16x16x32_bf16 v[104:107], v[136:139], v[192:195], v[104:107]
	v_mfma_f32_16x16x32_bf16 v[92:95], v[128:131], v[206:209], v[92:95]
	v_mfma_f32_16x16x32_bf16 v[88:91], v[136:139], v[206:209], v[88:91]
	v_mfma_f32_16x16x32_bf16 v[76:79], v[128:131], v[222:225], v[76:79]
	v_mfma_f32_16x16x32_bf16 v[72:75], v[136:139], v[222:225], v[72:75]
	v_mfma_f32_16x16x32_bf16 v[124:127], v[132:135], v[188:191], v[124:127]
	v_mfma_f32_16x16x32_bf16 v[120:123], v[140:143], v[188:191], v[120:123]
	v_mfma_f32_16x16x32_bf16 v[108:111], v[132:135], v[196:199], v[108:111]
	v_mfma_f32_16x16x32_bf16 v[104:107], v[140:143], v[196:199], v[104:107]
	v_mfma_f32_16x16x32_bf16 v[92:95], v[132:135], v[210:213], v[92:95]
	v_mfma_f32_16x16x32_bf16 v[88:91], v[140:143], v[210:213], v[88:91]
	v_mfma_f32_16x16x32_bf16 v[76:79], v[132:135], v[234:237], v[76:79]
	v_mfma_f32_16x16x32_bf16 v[72:75], v[140:143], v[234:237], v[72:75]
	v_mfma_f32_16x16x32_bf16 v[116:119], v[144:147], v[184:187], v[116:119]
	v_mfma_f32_16x16x32_bf16 v[112:115], v[152:155], v[184:187], v[112:115]
	v_mfma_f32_16x16x32_bf16 v[100:103], v[144:147], v[192:195], v[100:103]
	v_mfma_f32_16x16x32_bf16 v[96:99], v[152:155], v[192:195], v[96:99]
	v_mfma_f32_16x16x32_bf16 v[84:87], v[144:147], v[206:209], v[84:87]
	v_mfma_f32_16x16x32_bf16 v[80:83], v[152:155], v[206:209], v[80:83]
	v_mfma_f32_16x16x32_bf16 v[68:71], v[144:147], v[222:225], v[68:71]
	v_mfma_f32_16x16x32_bf16 v[64:67], v[152:155], v[222:225], v[64:67]
	v_mfma_f32_16x16x32_bf16 v[116:119], v[148:151], v[188:191], v[116:119]
	v_mfma_f32_16x16x32_bf16 v[112:115], v[180:183], v[188:191], v[112:115]
	v_mfma_f32_16x16x32_bf16 v[100:103], v[148:151], v[196:199], v[100:103]
	v_mfma_f32_16x16x32_bf16 v[96:99], v[180:183], v[196:199], v[96:99]
	v_mfma_f32_16x16x32_bf16 v[84:87], v[148:151], v[210:213], v[84:87]
	v_mfma_f32_16x16x32_bf16 v[80:83], v[180:183], v[210:213], v[80:83]
	v_mfma_f32_16x16x32_bf16 v[68:71], v[148:151], v[234:237], v[68:71]
	v_mfma_f32_16x16x32_bf16 v[64:67], v[180:183], v[234:237], v[64:67]
	s_setprio 0
	s_barrier
	s_add_i32 s23, s28, s81
	v_lshl_add_u64 v[162:163], vcc, 0, v[160:161]
	s_mov_b32 m0, s23
	ds_read_b128 v[184:187], v205 offset:16384
	ds_read_b128 v[188:191], v205 offset:17408
	ds_read_b128 v[192:195], v205 offset:18432
	ds_read_b128 v[196:199], v205 offset:19456
	ds_read_b128 v[206:209], v205 offset:20480
	ds_read_b128 v[210:213], v205 offset:21504
	ds_read_b128 v[222:225], v205 offset:22528
	ds_read_b128 v[234:237], v205 offset:23552
	global_load_lds_dwordx4 v[162:163], off
	s_add_i32 m0, s23, 0x2000
	v_lshl_add_u64 v[164:165], vcc, 0, v[170:171]
	s_add_u32 vcc_lo, vcc_lo, s8
	s_addc_u32 vcc_hi, vcc_hi, 0
	s_add_i32 s22, s22, s81
	global_load_lds_dwordx4 v[164:165], off
	v_lshl_add_u64 v[200:201], vcc, 0, v[160:161]
	s_mov_b32 m0, s22
	v_lshl_add_u64 v[214:215], vcc, 0, v[170:171]
	global_load_lds_dwordx4 v[200:201], off
	s_add_i32 m0, s22, 0x2000
	v_lshl_add_u64 v[226:227], s[82:83], 0, v[156:157]
	global_load_lds_dwordx4 v[214:215], off
	s_mov_b32 m0, s86
	v_lshl_add_u64 v[238:239], s[82:83], 0, v[158:159]
	global_load_lds_dwordx4 v[226:227], off
	s_mov_b32 m0, s87
	s_nop 0
	global_load_lds_dwordx4 v[238:239], off
	s_waitcnt vmcnt(8)
	s_waitcnt lgkmcnt(0)
	s_barrier
	s_setprio 1
	s_waitcnt lgkmcnt(0)
	v_mfma_f32_16x16x32_bf16 v[60:63], v[128:131], v[184:187], v[60:63]
	v_mfma_f32_16x16x32_bf16 v[56:59], v[136:139], v[184:187], v[56:59]
	v_mfma_f32_16x16x32_bf16 v[44:47], v[128:131], v[192:195], v[44:47]
	v_mfma_f32_16x16x32_bf16 v[40:43], v[136:139], v[192:195], v[40:43]
	v_mfma_f32_16x16x32_bf16 v[28:31], v[128:131], v[206:209], v[28:31]
	v_mfma_f32_16x16x32_bf16 v[24:27], v[136:139], v[206:209], v[24:27]
	v_mfma_f32_16x16x32_bf16 v[12:15], v[128:131], v[222:225], v[12:15]
	v_mfma_f32_16x16x32_bf16 v[8:11], v[136:139], v[222:225], v[8:11]
	v_mfma_f32_16x16x32_bf16 v[60:63], v[132:135], v[188:191], v[60:63]
	v_mfma_f32_16x16x32_bf16 v[56:59], v[140:143], v[188:191], v[56:59]
	v_mfma_f32_16x16x32_bf16 v[44:47], v[132:135], v[196:199], v[44:47]
	v_mfma_f32_16x16x32_bf16 v[40:43], v[140:143], v[196:199], v[40:43]
	v_mfma_f32_16x16x32_bf16 v[28:31], v[132:135], v[210:213], v[28:31]
	v_mfma_f32_16x16x32_bf16 v[24:27], v[140:143], v[210:213], v[24:27]
	v_mfma_f32_16x16x32_bf16 v[12:15], v[132:135], v[234:237], v[12:15]
	v_mfma_f32_16x16x32_bf16 v[8:11], v[140:143], v[234:237], v[8:11]
	v_mfma_f32_16x16x32_bf16 v[52:55], v[144:147], v[184:187], v[52:55]
	v_mfma_f32_16x16x32_bf16 v[48:51], v[152:155], v[184:187], v[48:51]
	v_mfma_f32_16x16x32_bf16 v[36:39], v[144:147], v[192:195], v[36:39]
	v_mfma_f32_16x16x32_bf16 v[32:35], v[152:155], v[192:195], v[32:35]
	v_mfma_f32_16x16x32_bf16 v[20:23], v[144:147], v[206:209], v[20:23]
	v_mfma_f32_16x16x32_bf16 v[16:19], v[152:155], v[206:209], v[16:19]
	v_mfma_f32_16x16x32_bf16 v[4:7], v[144:147], v[222:225], v[4:7]
	v_mfma_f32_16x16x32_bf16 v[0:3], v[152:155], v[222:225], v[0:3]
	v_mfma_f32_16x16x32_bf16 v[52:55], v[148:151], v[188:191], v[52:55]
	v_mfma_f32_16x16x32_bf16 v[48:51], v[180:183], v[188:191], v[48:51]
	v_mfma_f32_16x16x32_bf16 v[36:39], v[148:151], v[196:199], v[36:39]
	v_mfma_f32_16x16x32_bf16 v[32:35], v[180:183], v[196:199], v[32:35]
	v_mfma_f32_16x16x32_bf16 v[20:23], v[148:151], v[210:213], v[20:23]
	v_mfma_f32_16x16x32_bf16 v[16:19], v[180:183], v[210:213], v[16:19]
	v_mfma_f32_16x16x32_bf16 v[4:7], v[148:151], v[234:237], v[4:7]
	v_mfma_f32_16x16x32_bf16 v[0:3], v[180:183], v[234:237], v[0:3]
	s_setprio 0
	s_barrier
	s_add_i32 s22, 0, 0x18000
	s_add_i32 s23, 0, 0x1c000
	v_add_u32_e32 v140, s22, v169
	v_add_u32_e32 v173, s23, v169
	ds_read_b128 v[128:131], v140
	ds_read_b128 v[132:135], v140 offset:1024
	ds_read_b128 v[136:139], v140 offset:2048
	ds_read_b128 v[140:143], v140 offset:3072
	ds_read_b128 v[144:147], v173
	ds_read_b128 v[148:151], v173 offset:1024
	ds_read_b128 v[152:155], v173 offset:2048
	ds_read_b128 v[180:183], v173 offset:3072
	s_add_u32 s82, s82, s8
	s_addc_u32 s83, s83, 0
	s_mov_b32 m0, s88
	v_lshl_add_u64 v[240:241], s[82:83], 0, v[156:157]
	ds_read_b128 v[184:187], v205 offset:32768
	ds_read_b128 v[188:191], v205 offset:33792
	ds_read_b128 v[192:195], v205 offset:34816
	ds_read_b128 v[196:199], v205 offset:35840
	ds_read_b128 v[206:209], v205 offset:36864
	ds_read_b128 v[210:213], v205 offset:37888
	ds_read_b128 v[222:225], v205 offset:38912
	ds_read_b128 v[234:237], v205 offset:39936
	global_load_lds_dwordx4 v[240:241], off
	v_lshl_add_u64 v[240:241], s[82:83], 0, v[158:159]
	s_mov_b32 m0, s89
	s_nop 0
	global_load_lds_dwordx4 v[240:241], off
	s_waitcnt vmcnt(8)
	s_waitcnt lgkmcnt(0)
	s_barrier
	s_setprio 1
	s_waitcnt lgkmcnt(0)
	v_mfma_f32_16x16x32_bf16 v[124:127], v[128:131], v[184:187], v[124:127]
	v_mfma_f32_16x16x32_bf16 v[120:123], v[136:139], v[184:187], v[120:123]
	v_mfma_f32_16x16x32_bf16 v[108:111], v[128:131], v[192:195], v[108:111]
	v_mfma_f32_16x16x32_bf16 v[104:107], v[136:139], v[192:195], v[104:107]
	v_mfma_f32_16x16x32_bf16 v[92:95], v[128:131], v[206:209], v[92:95]
	v_mfma_f32_16x16x32_bf16 v[88:91], v[136:139], v[206:209], v[88:91]
	v_mfma_f32_16x16x32_bf16 v[76:79], v[128:131], v[222:225], v[76:79]
	v_mfma_f32_16x16x32_bf16 v[72:75], v[136:139], v[222:225], v[72:75]
	v_mfma_f32_16x16x32_bf16 v[124:127], v[132:135], v[188:191], v[124:127]
	v_mfma_f32_16x16x32_bf16 v[120:123], v[140:143], v[188:191], v[120:123]
	v_mfma_f32_16x16x32_bf16 v[108:111], v[132:135], v[196:199], v[108:111]
	v_mfma_f32_16x16x32_bf16 v[104:107], v[140:143], v[196:199], v[104:107]
	v_mfma_f32_16x16x32_bf16 v[92:95], v[132:135], v[210:213], v[92:95]
	v_mfma_f32_16x16x32_bf16 v[88:91], v[140:143], v[210:213], v[88:91]
	v_mfma_f32_16x16x32_bf16 v[76:79], v[132:135], v[234:237], v[76:79]
	v_mfma_f32_16x16x32_bf16 v[72:75], v[140:143], v[234:237], v[72:75]
	v_mfma_f32_16x16x32_bf16 v[116:119], v[144:147], v[184:187], v[116:119]
	v_mfma_f32_16x16x32_bf16 v[112:115], v[152:155], v[184:187], v[112:115]
	v_mfma_f32_16x16x32_bf16 v[100:103], v[144:147], v[192:195], v[100:103]
	v_mfma_f32_16x16x32_bf16 v[96:99], v[152:155], v[192:195], v[96:99]
	v_mfma_f32_16x16x32_bf16 v[84:87], v[144:147], v[206:209], v[84:87]
	v_mfma_f32_16x16x32_bf16 v[80:83], v[152:155], v[206:209], v[80:83]
	v_mfma_f32_16x16x32_bf16 v[68:71], v[144:147], v[222:225], v[68:71]
	v_mfma_f32_16x16x32_bf16 v[64:67], v[152:155], v[222:225], v[64:67]
	v_mfma_f32_16x16x32_bf16 v[116:119], v[148:151], v[188:191], v[116:119]
	v_mfma_f32_16x16x32_bf16 v[112:115], v[180:183], v[188:191], v[112:115]
	v_mfma_f32_16x16x32_bf16 v[100:103], v[148:151], v[196:199], v[100:103]
	v_mfma_f32_16x16x32_bf16 v[96:99], v[180:183], v[196:199], v[96:99]
	v_mfma_f32_16x16x32_bf16 v[84:87], v[148:151], v[210:213], v[84:87]
	v_mfma_f32_16x16x32_bf16 v[80:83], v[180:183], v[210:213], v[80:83]
	v_mfma_f32_16x16x32_bf16 v[68:71], v[148:151], v[234:237], v[68:71]
	v_mfma_f32_16x16x32_bf16 v[64:67], v[180:183], v[234:237], v[64:67]
	s_setprio 0
	s_barrier
	s_add_i32 s22, s22, s81
	v_lshl_add_u64 v[162:163], v[162:163], 0, s[48:49]
	s_mov_b32 m0, s22
	ds_read_b128 v[184:187], v205 offset:49152
	ds_read_b128 v[188:191], v205 offset:50176
	ds_read_b128 v[192:195], v205 offset:51200
	ds_read_b128 v[196:199], v205 offset:52224
	ds_read_b128 v[206:209], v205 offset:53248
	ds_read_b128 v[210:213], v205 offset:54272
	ds_read_b128 v[222:225], v205 offset:55296
	ds_read_b128 v[234:237], v205 offset:56320
	global_load_lds_dwordx4 v[162:163], off
	v_lshl_add_u64 v[162:163], v[164:165], 0, s[48:49]
	s_add_i32 m0, s22, 0x2000
	s_add_i32 s22, s23, s81
	global_load_lds_dwordx4 v[162:163], off
	v_lshl_add_u64 v[162:163], v[200:201], 0, s[48:49]
	s_mov_b32 m0, s22
	s_nop 0
	global_load_lds_dwordx4 v[162:163], off
	v_lshl_add_u64 v[162:163], v[214:215], 0, s[48:49]
	s_add_i32 m0, s22, 0x2000
	s_nop 0
	global_load_lds_dwordx4 v[162:163], off
	v_lshl_add_u64 v[162:163], v[226:227], 0, s[48:49]
	s_mov_b32 m0, s90
	s_nop 0
	global_load_lds_dwordx4 v[162:163], off
	v_lshl_add_u64 v[162:163], v[238:239], 0, s[48:49]
	s_mov_b32 m0, s91
	s_nop 0
	global_load_lds_dwordx4 v[162:163], off
	s_waitcnt vmcnt(8)
	s_waitcnt lgkmcnt(0)
	s_barrier
	s_setprio 1
	s_waitcnt lgkmcnt(0)
	v_mfma_f32_16x16x32_bf16 v[60:63], v[128:131], v[184:187], v[60:63]
	v_mfma_f32_16x16x32_bf16 v[56:59], v[136:139], v[184:187], v[56:59]
	v_mfma_f32_16x16x32_bf16 v[44:47], v[128:131], v[192:195], v[44:47]
	v_mfma_f32_16x16x32_bf16 v[40:43], v[136:139], v[192:195], v[40:43]
	v_mfma_f32_16x16x32_bf16 v[28:31], v[128:131], v[206:209], v[28:31]
	v_mfma_f32_16x16x32_bf16 v[24:27], v[136:139], v[206:209], v[24:27]
	v_mfma_f32_16x16x32_bf16 v[12:15], v[128:131], v[222:225], v[12:15]
	v_mfma_f32_16x16x32_bf16 v[8:11], v[136:139], v[222:225], v[8:11]
	v_mfma_f32_16x16x32_bf16 v[60:63], v[132:135], v[188:191], v[60:63]
	v_mfma_f32_16x16x32_bf16 v[56:59], v[140:143], v[188:191], v[56:59]
	v_mfma_f32_16x16x32_bf16 v[44:47], v[132:135], v[196:199], v[44:47]
	v_mfma_f32_16x16x32_bf16 v[40:43], v[140:143], v[196:199], v[40:43]
	v_mfma_f32_16x16x32_bf16 v[28:31], v[132:135], v[210:213], v[28:31]
	v_mfma_f32_16x16x32_bf16 v[24:27], v[140:143], v[210:213], v[24:27]
	v_mfma_f32_16x16x32_bf16 v[12:15], v[132:135], v[234:237], v[12:15]
	v_mfma_f32_16x16x32_bf16 v[8:11], v[140:143], v[234:237], v[8:11]
	v_mfma_f32_16x16x32_bf16 v[52:55], v[144:147], v[184:187], v[52:55]
	v_mfma_f32_16x16x32_bf16 v[48:51], v[152:155], v[184:187], v[48:51]
	v_mfma_f32_16x16x32_bf16 v[36:39], v[144:147], v[192:195], v[36:39]
	v_mfma_f32_16x16x32_bf16 v[32:35], v[152:155], v[192:195], v[32:35]
	v_mfma_f32_16x16x32_bf16 v[20:23], v[144:147], v[206:209], v[20:23]
	v_mfma_f32_16x16x32_bf16 v[16:19], v[152:155], v[206:209], v[16:19]
	v_mfma_f32_16x16x32_bf16 v[4:7], v[144:147], v[222:225], v[4:7]
	v_mfma_f32_16x16x32_bf16 v[0:3], v[152:155], v[222:225], v[0:3]
	v_mfma_f32_16x16x32_bf16 v[52:55], v[148:151], v[188:191], v[52:55]
	v_mfma_f32_16x16x32_bf16 v[48:51], v[180:183], v[188:191], v[48:51]
	v_mfma_f32_16x16x32_bf16 v[36:39], v[148:151], v[196:199], v[36:39]
	v_mfma_f32_16x16x32_bf16 v[32:35], v[180:183], v[196:199], v[32:35]
	v_mfma_f32_16x16x32_bf16 v[20:23], v[148:151], v[210:213], v[20:23]
	v_mfma_f32_16x16x32_bf16 v[16:19], v[180:183], v[210:213], v[16:19]
	v_mfma_f32_16x16x32_bf16 v[4:7], v[148:151], v[234:237], v[4:7]
	v_mfma_f32_16x16x32_bf16 v[0:3], v[180:183], v[234:237], v[0:3]
	s_setprio 0
	s_barrier
	s_add_u32 s40, s40, 0x100
	s_addc_u32 s41, s41, 0
	s_add_u32 s4, s4, 0x100
	s_addc_u32 s84, s84, 0
	s_cmp_ge_u32 s85, s94
	s_mov_b32 s82, s85
	s_cbranch_scc0 .LBB0_378
	s_and_b64 vcc, exec, s[14:15]
	s_cbranch_vccz .LBB0_381
	s_barrier

.LBB0_477:
	s_ashr_i32 s17, s16, 31
	s_lshl_b64 s[18:19], s[16:17], 19
	s_add_u32 s18, s0, s18
	s_addc_u32 s19, s1, s19
	s_and_b64 s[24:25], s[38:39], exec
	s_cselect_b32 s4, s19, s41
	s_cselect_b32 s9, s18, s40
	s_ashr_i32 s85, s84, 31
	s_lshl_b64 s[24:25], s[84:85], 19
	s_add_u32 s82, s80, s24
	s_addc_u32 s83, s81, s25
	s_and_b64 s[24:25], s[38:39], exec
	s_cselect_b32 s17, s83, s13
	s_cselect_b32 s24, s82, s12
	s_add_u32 s40, s40, 0x40080
	s_addc_u32 s41, s41, 0
	s_add_u32 s25, s12, 0x100
	s_addc_u32 s50, s13, 0
	s_mov_b32 s51, -2
	s_add_u32 s12, s40, 0xfffc0080
	s_addc_u32 s13, s41, -1
	s_add_i32 s85, 0, 0x10000
	s_cmp_eq_u32 s51, 12
	s_cselect_b32 s43, s4, s13
	s_cselect_b32 s42, s9, s12
	v_add_u32_e32 v158, s85, v196
	s_cselect_b32 s13, s17, s50
	s_cselect_b32 s12, s24, s25
	s_add_i32 s27, 0, 0x14000
	ds_read_b128 v[150:153], v158
	ds_read_b128 v[154:157], v158 offset:1024
	ds_read_b128 v[170:173], v158 offset:2048
	ds_read_b128 v[174:177], v158 offset:3072
	v_add_u32_e32 v158, s27, v196
	ds_read_b128 v[178:181], v158
	ds_read_b128 v[182:185], v158 offset:1024
	ds_read_b128 v[186:189], v158 offset:2048
	ds_read_b128 v[200:203], v158 offset:3072
	v_lshl_add_u64 v[158:159], s[40:41], 0, v[146:147]
	s_add_i32 m0, s15, 0xc000
	ds_read_b128 v[204:207], v199
	ds_read_b128 v[208:211], v199 offset:1024
	ds_read_b128 v[212:215], v199 offset:2048
	ds_read_b128 v[234:237], v199 offset:3072
	ds_read_b128 v[238:241], v199 offset:4096
	ds_read_b128 v[242:245], v199 offset:5120
	ds_read_b128 v[246:249], v199 offset:6144
	ds_read_b128 v[222:225], v199 offset:7168
	global_load_lds_dwordx4 v[158:159], off
	v_lshl_add_u64 v[158:159], s[40:41], 0, v[148:149]
	s_add_i32 m0, s15, 0xe000
	s_nop 0
	global_load_lds_dwordx4 v[158:159], off
	s_waitcnt vmcnt(8)
	s_waitcnt lgkmcnt(0)
	s_barrier
	s_setprio 1
	s_waitcnt lgkmcnt(0)
	v_mfma_f32_16x16x32_bf16 v[124:127], v[150:153], v[204:207], 0
	v_mfma_f32_16x16x32_bf16 v[120:123], v[170:173], v[204:207], 0
	v_mfma_f32_16x16x32_bf16 v[108:111], v[150:153], v[212:215], 0
	v_mfma_f32_16x16x32_bf16 v[104:107], v[170:173], v[212:215], 0
	v_mfma_f32_16x16x32_bf16 v[92:95], v[150:153], v[238:241], 0
	v_mfma_f32_16x16x32_bf16 v[88:91], v[170:173], v[238:241], 0
	v_mfma_f32_16x16x32_bf16 v[76:79], v[150:153], v[246:249], 0
	v_mfma_f32_16x16x32_bf16 v[72:75], v[170:173], v[246:249], 0
	v_mfma_f32_16x16x32_bf16 v[124:127], v[154:157], v[208:211], v[124:127]
	v_mfma_f32_16x16x32_bf16 v[120:123], v[174:177], v[208:211], v[120:123]
	v_mfma_f32_16x16x32_bf16 v[108:111], v[154:157], v[234:237], v[108:111]
	v_mfma_f32_16x16x32_bf16 v[104:107], v[174:177], v[234:237], v[104:107]
	v_mfma_f32_16x16x32_bf16 v[92:95], v[154:157], v[242:245], v[92:95]
	v_mfma_f32_16x16x32_bf16 v[88:91], v[174:177], v[242:245], v[88:91]
	v_mfma_f32_16x16x32_bf16 v[76:79], v[154:157], v[222:225], v[76:79]
	v_mfma_f32_16x16x32_bf16 v[72:75], v[174:177], v[222:225], v[72:75]
	v_mfma_f32_16x16x32_bf16 v[116:119], v[178:181], v[204:207], 0
	v_mfma_f32_16x16x32_bf16 v[112:115], v[186:189], v[204:207], 0
	v_mfma_f32_16x16x32_bf16 v[100:103], v[178:181], v[212:215], 0
	v_mfma_f32_16x16x32_bf16 v[96:99], v[186:189], v[212:215], 0
	v_mfma_f32_16x16x32_bf16 v[84:87], v[178:181], v[238:241], 0
	v_mfma_f32_16x16x32_bf16 v[80:83], v[186:189], v[238:241], 0
	v_mfma_f32_16x16x32_bf16 v[68:71], v[178:181], v[246:249], 0
	v_mfma_f32_16x16x32_bf16 v[64:67], v[186:189], v[246:249], 0
	v_mfma_f32_16x16x32_bf16 v[116:119], v[182:185], v[208:211], v[116:119]
	v_mfma_f32_16x16x32_bf16 v[112:115], v[200:203], v[208:211], v[112:115]
	v_mfma_f32_16x16x32_bf16 v[100:103], v[182:185], v[234:237], v[100:103]
	v_mfma_f32_16x16x32_bf16 v[96:99], v[200:203], v[234:237], v[96:99]
	v_mfma_f32_16x16x32_bf16 v[84:87], v[182:185], v[242:245], v[84:87]
	v_mfma_f32_16x16x32_bf16 v[80:83], v[200:203], v[242:245], v[80:83]
	v_mfma_f32_16x16x32_bf16 v[68:71], v[182:185], v[222:225], v[68:71]
	v_mfma_f32_16x16x32_bf16 v[64:67], v[200:203], v[222:225], v[64:67]
	s_setprio 0
	s_barrier
	s_add_i32 s85, s85, s86
	v_lshl_add_u64 v[158:159], s[12:13], 0, v[130:131]
	s_mov_b32 m0, s85
	ds_read_b128 v[204:207], v199 offset:16384
	ds_read_b128 v[208:211], v199 offset:17408
	ds_read_b128 v[212:215], v199 offset:18432
	ds_read_b128 v[222:225], v199 offset:19456
	ds_read_b128 v[234:237], v199 offset:20480
	ds_read_b128 v[238:241], v199 offset:21504
	ds_read_b128 v[242:245], v199 offset:22528
	ds_read_b128 v[246:249], v199 offset:23552
	global_load_lds_dwordx4 v[158:159], off
	s_add_i32 m0, s85, 0x2000
	s_add_u32 vcc_lo, s12, 0x40000
	v_lshl_add_u64 v[250:251], s[12:13], 0, v[134:135]
	s_addc_u32 vcc_hi, s13, 0
	s_add_i32 s27, s27, s86
	global_load_lds_dwordx4 v[250:251], off
	v_lshl_add_u64 v[226:227], vcc, 0, v[130:131]
	s_mov_b32 m0, s27
	v_lshl_add_u64 v[162:163], s[42:43], 0, v[132:133]
	global_load_lds_dwordx4 v[226:227], off
	v_lshl_add_u64 v[226:227], vcc, 0, v[134:135]
	s_add_i32 m0, s27, 0x2000
	s_nop 0
	global_load_lds_dwordx4 v[226:227], off
	v_lshl_add_u64 v[226:227], s[42:43], 0, v[128:129]
	s_mov_b32 m0, s15
	s_nop 0
	global_load_lds_dwordx4 v[226:227], off
	s_mov_b32 m0, s87
	s_nop 0
	global_load_lds_dwordx4 v[162:163], off
	s_waitcnt vmcnt(8)
	s_waitcnt lgkmcnt(0)
	s_barrier
	s_setprio 1
	s_waitcnt lgkmcnt(0)
	v_mfma_f32_16x16x32_bf16 v[60:63], v[150:153], v[204:207], 0
	v_mfma_f32_16x16x32_bf16 v[56:59], v[170:173], v[204:207], 0
	v_mfma_f32_16x16x32_bf16 v[44:47], v[150:153], v[212:215], 0
	v_mfma_f32_16x16x32_bf16 v[40:43], v[170:173], v[212:215], 0
	v_mfma_f32_16x16x32_bf16 v[28:31], v[150:153], v[234:237], 0
	v_mfma_f32_16x16x32_bf16 v[24:27], v[170:173], v[234:237], 0
	v_mfma_f32_16x16x32_bf16 v[12:15], v[150:153], v[242:245], 0
	v_mfma_f32_16x16x32_bf16 v[8:11], v[170:173], v[242:245], 0
	v_mfma_f32_16x16x32_bf16 v[60:63], v[154:157], v[208:211], v[60:63]
	v_mfma_f32_16x16x32_bf16 v[56:59], v[174:177], v[208:211], v[56:59]
	v_mfma_f32_16x16x32_bf16 v[44:47], v[154:157], v[222:225], v[44:47]
	v_mfma_f32_16x16x32_bf16 v[40:43], v[174:177], v[222:225], v[40:43]
	v_mfma_f32_16x16x32_bf16 v[28:31], v[154:157], v[238:241], v[28:31]
	v_mfma_f32_16x16x32_bf16 v[24:27], v[174:177], v[238:241], v[24:27]
	v_mfma_f32_16x16x32_bf16 v[12:15], v[154:157], v[246:249], v[12:15]
	v_mfma_f32_16x16x32_bf16 v[8:11], v[174:177], v[246:249], v[8:11]
	v_mfma_f32_16x16x32_bf16 v[52:55], v[178:181], v[204:207], 0
	v_mfma_f32_16x16x32_bf16 v[48:51], v[186:189], v[204:207], 0
	v_mfma_f32_16x16x32_bf16 v[36:39], v[178:181], v[212:215], 0
	v_mfma_f32_16x16x32_bf16 v[32:35], v[186:189], v[212:215], 0
	v_mfma_f32_16x16x32_bf16 v[20:23], v[178:181], v[234:237], 0
	v_mfma_f32_16x16x32_bf16 v[16:19], v[186:189], v[234:237], 0
	v_mfma_f32_16x16x32_bf16 v[4:7], v[178:181], v[242:245], 0
	v_mfma_f32_16x16x32_bf16 v[0:3], v[186:189], v[242:245], 0
	v_mfma_f32_16x16x32_bf16 v[52:55], v[182:185], v[208:211], v[52:55]
	v_mfma_f32_16x16x32_bf16 v[48:51], v[200:203], v[208:211], v[48:51]
	v_mfma_f32_16x16x32_bf16 v[36:39], v[182:185], v[222:225], v[36:39]
	v_mfma_f32_16x16x32_bf16 v[32:35], v[200:203], v[222:225], v[32:35]
	v_mfma_f32_16x16x32_bf16 v[20:23], v[182:185], v[238:241], v[20:23]
	v_mfma_f32_16x16x32_bf16 v[16:19], v[200:203], v[238:241], v[16:19]
	v_mfma_f32_16x16x32_bf16 v[4:7], v[182:185], v[246:249], v[4:7]
	v_mfma_f32_16x16x32_bf16 v[0:3], v[200:203], v[246:249], v[0:3]
	s_setprio 0
	s_barrier
	s_add_i32 s27, 0, 0x18000
	v_add_u32_e32 v160, s27, v196
	s_add_i32 s85, 0, 0x1c000
	ds_read_b128 v[150:153], v160
	ds_read_b128 v[154:157], v160 offset:1024
	ds_read_b128 v[170:173], v160 offset:2048
	ds_read_b128 v[174:177], v160 offset:3072
	v_add_u32_e32 v160, s85, v196
	ds_read_b128 v[178:181], v160
	ds_read_b128 v[182:185], v160 offset:1024
	ds_read_b128 v[186:189], v160 offset:2048
	ds_read_b128 v[200:203], v160 offset:3072
	s_add_u32 s42, s42, 0x40000
	s_addc_u32 s43, s43, 0
	s_mov_b32 m0, s88
	v_lshl_add_u64 v[164:165], s[42:43], 0, v[128:129]
	ds_read_b128 v[204:207], v199 offset:32768
	ds_read_b128 v[208:211], v199 offset:33792
	ds_read_b128 v[212:215], v199 offset:34816
	ds_read_b128 v[222:225], v199 offset:35840
	ds_read_b128 v[234:237], v199 offset:36864
	ds_read_b128 v[238:241], v199 offset:37888
	ds_read_b128 v[242:245], v199 offset:38912
	ds_read_b128 v[246:249], v199 offset:39936
	global_load_lds_dwordx4 v[164:165], off
	v_lshl_add_u64 v[164:165], s[42:43], 0, v[132:133]
	s_mov_b32 m0, s89
	s_nop 0
	global_load_lds_dwordx4 v[164:165], off
	s_waitcnt vmcnt(8)
	s_waitcnt lgkmcnt(0)
	s_barrier
	s_setprio 1
	s_waitcnt lgkmcnt(0)
	v_mfma_f32_16x16x32_bf16 v[124:127], v[150:153], v[204:207], v[124:127]
	v_mfma_f32_16x16x32_bf16 v[120:123], v[170:173], v[204:207], v[120:123]
	v_mfma_f32_16x16x32_bf16 v[108:111], v[150:153], v[212:215], v[108:111]
	v_mfma_f32_16x16x32_bf16 v[104:107], v[170:173], v[212:215], v[104:107]
	v_mfma_f32_16x16x32_bf16 v[92:95], v[150:153], v[234:237], v[92:95]
	v_mfma_f32_16x16x32_bf16 v[88:91], v[170:173], v[234:237], v[88:91]
	v_mfma_f32_16x16x32_bf16 v[76:79], v[150:153], v[242:245], v[76:79]
	v_mfma_f32_16x16x32_bf16 v[72:75], v[170:173], v[242:245], v[72:75]
	v_mfma_f32_16x16x32_bf16 v[124:127], v[154:157], v[208:211], v[124:127]
	v_mfma_f32_16x16x32_bf16 v[120:123], v[174:177], v[208:211], v[120:123]
	v_mfma_f32_16x16x32_bf16 v[108:111], v[154:157], v[222:225], v[108:111]
	v_mfma_f32_16x16x32_bf16 v[104:107], v[174:177], v[222:225], v[104:107]
	v_mfma_f32_16x16x32_bf16 v[92:95], v[154:157], v[238:241], v[92:95]
	v_mfma_f32_16x16x32_bf16 v[88:91], v[174:177], v[238:241], v[88:91]
	v_mfma_f32_16x16x32_bf16 v[76:79], v[154:157], v[246:249], v[76:79]
	v_mfma_f32_16x16x32_bf16 v[72:75], v[174:177], v[246:249], v[72:75]
	v_mfma_f32_16x16x32_bf16 v[116:119], v[178:181], v[204:207], v[116:119]
	v_mfma_f32_16x16x32_bf16 v[112:115], v[186:189], v[204:207], v[112:115]
	v_mfma_f32_16x16x32_bf16 v[100:103], v[178:181], v[212:215], v[100:103]
	v_mfma_f32_16x16x32_bf16 v[96:99], v[186:189], v[212:215], v[96:99]
	v_mfma_f32_16x16x32_bf16 v[84:87], v[178:181], v[234:237], v[84:87]
	v_mfma_f32_16x16x32_bf16 v[80:83], v[186:189], v[234:237], v[80:83]
	v_mfma_f32_16x16x32_bf16 v[68:71], v[178:181], v[242:245], v[68:71]
	v_mfma_f32_16x16x32_bf16 v[64:67], v[186:189], v[242:245], v[64:67]
	v_mfma_f32_16x16x32_bf16 v[116:119], v[182:185], v[208:211], v[116:119]
	v_mfma_f32_16x16x32_bf16 v[112:115], v[200:203], v[208:211], v[112:115]
	v_mfma_f32_16x16x32_bf16 v[100:103], v[182:185], v[222:225], v[100:103]
	v_mfma_f32_16x16x32_bf16 v[96:99], v[200:203], v[222:225], v[96:99]
	v_mfma_f32_16x16x32_bf16 v[84:87], v[182:185], v[238:241], v[84:87]
	v_mfma_f32_16x16x32_bf16 v[80:83], v[200:203], v[238:241], v[80:83]
	v_mfma_f32_16x16x32_bf16 v[68:71], v[182:185], v[246:249], v[68:71]
	v_mfma_f32_16x16x32_bf16 v[64:67], v[200:203], v[246:249], v[64:67]
	s_setprio 0
	s_barrier
	s_add_i32 s27, s27, s86
	v_lshl_add_u64 v[158:159], v[158:159], 0, s[48:49]
	s_mov_b32 m0, s27
	ds_read_b128 v[204:207], v199 offset:49152
	ds_read_b128 v[208:211], v199 offset:50176
	ds_read_b128 v[212:215], v199 offset:51200
	ds_read_b128 v[222:225], v199 offset:52224
	ds_read_b128 v[234:237], v199 offset:53248
	ds_read_b128 v[238:241], v199 offset:54272
	ds_read_b128 v[242:245], v199 offset:55296
	ds_read_b128 v[246:249], v199 offset:56320
	global_load_lds_dwordx4 v[158:159], off
	s_add_i32 m0, s27, 0x2000
	s_add_u32 s12, s12, 0x40080
	v_lshl_add_u64 v[158:159], v[250:251], 0, s[48:49]
	s_addc_u32 s13, s13, 0
	s_add_i32 s27, s85, s86
	global_load_lds_dwordx4 v[158:159], off
	v_lshl_add_u64 v[158:159], s[12:13], 0, v[130:131]
	s_mov_b32 m0, s27
	s_nop 0
	global_load_lds_dwordx4 v[158:159], off
	v_lshl_add_u64 v[158:159], s[12:13], 0, v[134:135]
	s_add_i32 m0, s27, 0x2000
	s_nop 0
	global_load_lds_dwordx4 v[158:159], off
	v_lshl_add_u64 v[158:159], v[226:227], 0, s[48:49]
	s_mov_b32 m0, s92
	s_nop 0
	global_load_lds_dwordx4 v[158:159], off
	v_lshl_add_u64 v[158:159], v[162:163], 0, s[48:49]
	s_mov_b32 m0, s93
	s_nop 0
	global_load_lds_dwordx4 v[158:159], off
	s_waitcnt vmcnt(8)
	s_waitcnt lgkmcnt(0)
	s_barrier
	s_setprio 1
	s_waitcnt lgkmcnt(0)
	v_mfma_f32_16x16x32_bf16 v[60:63], v[150:153], v[204:207], v[60:63]
	v_mfma_f32_16x16x32_bf16 v[56:59], v[170:173], v[204:207], v[56:59]
	v_mfma_f32_16x16x32_bf16 v[44:47], v[150:153], v[212:215], v[44:47]
	v_mfma_f32_16x16x32_bf16 v[40:43], v[170:173], v[212:215], v[40:43]
	v_mfma_f32_16x16x32_bf16 v[28:31], v[150:153], v[234:237], v[28:31]
	v_mfma_f32_16x16x32_bf16 v[24:27], v[170:173], v[234:237], v[24:27]
	v_mfma_f32_16x16x32_bf16 v[12:15], v[150:153], v[242:245], v[12:15]
	v_mfma_f32_16x16x32_bf16 v[8:11], v[170:173], v[242:245], v[8:11]
	v_mfma_f32_16x16x32_bf16 v[60:63], v[154:157], v[208:211], v[60:63]
	v_mfma_f32_16x16x32_bf16 v[56:59], v[174:177], v[208:211], v[56:59]
	v_mfma_f32_16x16x32_bf16 v[44:47], v[154:157], v[222:225], v[44:47]
	v_mfma_f32_16x16x32_bf16 v[40:43], v[174:177], v[222:225], v[40:43]
	v_mfma_f32_16x16x32_bf16 v[28:31], v[154:157], v[238:241], v[28:31]
	v_mfma_f32_16x16x32_bf16 v[24:27], v[174:177], v[238:241], v[24:27]
	v_mfma_f32_16x16x32_bf16 v[12:15], v[154:157], v[246:249], v[12:15]
	v_mfma_f32_16x16x32_bf16 v[8:11], v[174:177], v[246:249], v[8:11]
	v_mfma_f32_16x16x32_bf16 v[52:55], v[178:181], v[204:207], v[52:55]
	v_mfma_f32_16x16x32_bf16 v[48:51], v[186:189], v[204:207], v[48:51]
	v_mfma_f32_16x16x32_bf16 v[36:39], v[178:181], v[212:215], v[36:39]
	v_mfma_f32_16x16x32_bf16 v[32:35], v[186:189], v[212:215], v[32:35]
	v_mfma_f32_16x16x32_bf16 v[20:23], v[178:181], v[234:237], v[20:23]
	v_mfma_f32_16x16x32_bf16 v[16:19], v[186:189], v[234:237], v[16:19]
	v_mfma_f32_16x16x32_bf16 v[4:7], v[178:181], v[242:245], v[4:7]
	v_mfma_f32_16x16x32_bf16 v[0:3], v[186:189], v[242:245], v[0:3]
	v_mfma_f32_16x16x32_bf16 v[52:55], v[182:185], v[208:211], v[52:55]
	v_mfma_f32_16x16x32_bf16 v[48:51], v[200:203], v[208:211], v[48:51]
	v_mfma_f32_16x16x32_bf16 v[36:39], v[182:185], v[222:225], v[36:39]
	v_mfma_f32_16x16x32_bf16 v[32:35], v[200:203], v[222:225], v[32:35]
	v_mfma_f32_16x16x32_bf16 v[20:23], v[182:185], v[238:241], v[20:23]
	v_mfma_f32_16x16x32_bf16 v[16:19], v[200:203], v[238:241], v[16:19]
	v_mfma_f32_16x16x32_bf16 v[4:7], v[182:185], v[246:249], v[4:7]
	v_mfma_f32_16x16x32_bf16 v[0:3], v[200:203], v[246:249], v[0:3]
	s_setprio 0
	s_barrier
	s_add_i32 s51, s51, 2
	s_add_u32 s40, s40, 0x100
	s_addc_u32 s41, s41, 0
	s_add_u32 s25, s25, 0x100
	s_addc_u32 s50, s50, 0
	s_cmp_gt_u32 s51, 13
.LBB0_478:
	s_add_u32 s12, s40, 0xfffc0080
	s_addc_u32 s13, s41, -1
	s_add_i32 s85, 0, 0x10000
	s_cmp_eq_u32 s51, 12
	s_cselect_b32 s43, s4, s13
	s_cselect_b32 s42, s9, s12
	v_add_u32_e32 v158, s85, v196
	s_cselect_b32 s13, s17, s50
	s_cselect_b32 s12, s24, s25
	s_add_i32 s27, 0, 0x14000
	ds_read_b128 v[150:153], v158
	ds_read_b128 v[154:157], v158 offset:1024
	ds_read_b128 v[170:173], v158 offset:2048
	ds_read_b128 v[174:177], v158 offset:3072
	v_add_u32_e32 v158, s27, v196
	ds_read_b128 v[178:181], v158
	ds_read_b128 v[182:185], v158 offset:1024
	ds_read_b128 v[186:189], v158 offset:2048
	ds_read_b128 v[200:203], v158 offset:3072
	v_lshl_add_u64 v[158:159], s[40:41], 0, v[146:147]
	s_add_i32 m0, s15, 0xc000
	ds_read_b128 v[204:207], v199
	ds_read_b128 v[208:211], v199 offset:1024
	ds_read_b128 v[212:215], v199 offset:2048
	ds_read_b128 v[234:237], v199 offset:3072
	ds_read_b128 v[238:241], v199 offset:4096
	ds_read_b128 v[242:245], v199 offset:5120
	ds_read_b128 v[246:249], v199 offset:6144
	ds_read_b128 v[222:225], v199 offset:7168
	global_load_lds_dwordx4 v[158:159], off
	v_lshl_add_u64 v[158:159], s[40:41], 0, v[148:149]
	s_add_i32 m0, s15, 0xe000
	s_nop 0
	global_load_lds_dwordx4 v[158:159], off
	s_waitcnt vmcnt(8)
	s_waitcnt lgkmcnt(0)
	s_barrier
	s_setprio 1
	s_waitcnt lgkmcnt(0)
	v_mfma_f32_16x16x32_bf16 v[124:127], v[150:153], v[204:207], v[124:127]
	v_mfma_f32_16x16x32_bf16 v[120:123], v[170:173], v[204:207], v[120:123]
	v_mfma_f32_16x16x32_bf16 v[108:111], v[150:153], v[212:215], v[108:111]
	v_mfma_f32_16x16x32_bf16 v[104:107], v[170:173], v[212:215], v[104:107]
	v_mfma_f32_16x16x32_bf16 v[92:95], v[150:153], v[238:241], v[92:95]
	v_mfma_f32_16x16x32_bf16 v[88:91], v[170:173], v[238:241], v[88:91]
	v_mfma_f32_16x16x32_bf16 v[76:79], v[150:153], v[246:249], v[76:79]
	v_mfma_f32_16x16x32_bf16 v[72:75], v[170:173], v[246:249], v[72:75]
	v_mfma_f32_16x16x32_bf16 v[124:127], v[154:157], v[208:211], v[124:127]
	v_mfma_f32_16x16x32_bf16 v[120:123], v[174:177], v[208:211], v[120:123]
	v_mfma_f32_16x16x32_bf16 v[108:111], v[154:157], v[234:237], v[108:111]
	v_mfma_f32_16x16x32_bf16 v[104:107], v[174:177], v[234:237], v[104:107]
	v_mfma_f32_16x16x32_bf16 v[92:95], v[154:157], v[242:245], v[92:95]
	v_mfma_f32_16x16x32_bf16 v[88:91], v[174:177], v[242:245], v[88:91]
	v_mfma_f32_16x16x32_bf16 v[76:79], v[154:157], v[222:225], v[76:79]
	v_mfma_f32_16x16x32_bf16 v[72:75], v[174:177], v[222:225], v[72:75]
	v_mfma_f32_16x16x32_bf16 v[116:119], v[178:181], v[204:207], v[116:119]
	v_mfma_f32_16x16x32_bf16 v[112:115], v[186:189], v[204:207], v[112:115]
	v_mfma_f32_16x16x32_bf16 v[100:103], v[178:181], v[212:215], v[100:103]
	v_mfma_f32_16x16x32_bf16 v[96:99], v[186:189], v[212:215], v[96:99]
	v_mfma_f32_16x16x32_bf16 v[84:87], v[178:181], v[238:241], v[84:87]
	v_mfma_f32_16x16x32_bf16 v[80:83], v[186:189], v[238:241], v[80:83]
	v_mfma_f32_16x16x32_bf16 v[68:71], v[178:181], v[246:249], v[68:71]
	v_mfma_f32_16x16x32_bf16 v[64:67], v[186:189], v[246:249], v[64:67]
	v_mfma_f32_16x16x32_bf16 v[116:119], v[182:185], v[208:211], v[116:119]
	v_mfma_f32_16x16x32_bf16 v[112:115], v[200:203], v[208:211], v[112:115]
	v_mfma_f32_16x16x32_bf16 v[100:103], v[182:185], v[234:237], v[100:103]
	v_mfma_f32_16x16x32_bf16 v[96:99], v[200:203], v[234:237], v[96:99]
	v_mfma_f32_16x16x32_bf16 v[84:87], v[182:185], v[242:245], v[84:87]
	v_mfma_f32_16x16x32_bf16 v[80:83], v[200:203], v[242:245], v[80:83]
	v_mfma_f32_16x16x32_bf16 v[68:71], v[182:185], v[222:225], v[68:71]
	v_mfma_f32_16x16x32_bf16 v[64:67], v[200:203], v[222:225], v[64:67]
	s_setprio 0
	s_barrier
	s_add_i32 s85, s85, s86
	v_lshl_add_u64 v[158:159], s[12:13], 0, v[130:131]
	s_mov_b32 m0, s85
	ds_read_b128 v[204:207], v199 offset:16384
	ds_read_b128 v[208:211], v199 offset:17408
	ds_read_b128 v[212:215], v199 offset:18432
	ds_read_b128 v[222:225], v199 offset:19456
	ds_read_b128 v[234:237], v199 offset:20480
	ds_read_b128 v[238:241], v199 offset:21504
	ds_read_b128 v[242:245], v199 offset:22528
	ds_read_b128 v[246:249], v199 offset:23552
	global_load_lds_dwordx4 v[158:159], off
	s_add_i32 m0, s85, 0x2000
	s_add_u32 vcc_lo, s12, 0x40000
	v_lshl_add_u64 v[250:251], s[12:13], 0, v[134:135]
	s_addc_u32 vcc_hi, s13, 0
	s_add_i32 s27, s27, s86
	global_load_lds_dwordx4 v[250:251], off
	v_lshl_add_u64 v[226:227], vcc, 0, v[130:131]
	s_mov_b32 m0, s27
	v_lshl_add_u64 v[162:163], s[42:43], 0, v[132:133]
	global_load_lds_dwordx4 v[226:227], off
	v_lshl_add_u64 v[226:227], vcc, 0, v[134:135]
	s_add_i32 m0, s27, 0x2000
	s_nop 0
	global_load_lds_dwordx4 v[226:227], off
	v_lshl_add_u64 v[226:227], s[42:43], 0, v[128:129]
	s_mov_b32 m0, s15
	s_nop 0
	global_load_lds_dwordx4 v[226:227], off
	s_mov_b32 m0, s87
	s_nop 0
	global_load_lds_dwordx4 v[162:163], off
	s_waitcnt vmcnt(8)
	s_waitcnt lgkmcnt(0)
	s_barrier
	s_setprio 1
	s_waitcnt lgkmcnt(0)
	v_mfma_f32_16x16x32_bf16 v[60:63], v[150:153], v[204:207], v[60:63]
	v_mfma_f32_16x16x32_bf16 v[56:59], v[170:173], v[204:207], v[56:59]
	v_mfma_f32_16x16x32_bf16 v[44:47], v[150:153], v[212:215], v[44:47]
	v_mfma_f32_16x16x32_bf16 v[40:43], v[170:173], v[212:215], v[40:43]
	v_mfma_f32_16x16x32_bf16 v[28:31], v[150:153], v[234:237], v[28:31]
	v_mfma_f32_16x16x32_bf16 v[24:27], v[170:173], v[234:237], v[24:27]
	v_mfma_f32_16x16x32_bf16 v[12:15], v[150:153], v[242:245], v[12:15]
	v_mfma_f32_16x16x32_bf16 v[8:11], v[170:173], v[242:245], v[8:11]
	v_mfma_f32_16x16x32_bf16 v[60:63], v[154:157], v[208:211], v[60:63]
	v_mfma_f32_16x16x32_bf16 v[56:59], v[174:177], v[208:211], v[56:59]
	v_mfma_f32_16x16x32_bf16 v[44:47], v[154:157], v[222:225], v[44:47]
	v_mfma_f32_16x16x32_bf16 v[40:43], v[174:177], v[222:225], v[40:43]
	v_mfma_f32_16x16x32_bf16 v[28:31], v[154:157], v[238:241], v[28:31]
	v_mfma_f32_16x16x32_bf16 v[24:27], v[174:177], v[238:241], v[24:27]
	v_mfma_f32_16x16x32_bf16 v[12:15], v[154:157], v[246:249], v[12:15]
	v_mfma_f32_16x16x32_bf16 v[8:11], v[174:177], v[246:249], v[8:11]
	v_mfma_f32_16x16x32_bf16 v[52:55], v[178:181], v[204:207], v[52:55]
	v_mfma_f32_16x16x32_bf16 v[48:51], v[186:189], v[204:207], v[48:51]
	v_mfma_f32_16x16x32_bf16 v[36:39], v[178:181], v[212:215], v[36:39]
	v_mfma_f32_16x16x32_bf16 v[32:35], v[186:189], v[212:215], v[32:35]
	v_mfma_f32_16x16x32_bf16 v[20:23], v[178:181], v[234:237], v[20:23]
	v_mfma_f32_16x16x32_bf16 v[16:19], v[186:189], v[234:237], v[16:19]
	v_mfma_f32_16x16x32_bf16 v[4:7], v[178:181], v[242:245], v[4:7]
	v_mfma_f32_16x16x32_bf16 v[0:3], v[186:189], v[242:245], v[0:3]
	v_mfma_f32_16x16x32_bf16 v[52:55], v[182:185], v[208:211], v[52:55]
	v_mfma_f32_16x16x32_bf16 v[48:51], v[200:203], v[208:211], v[48:51]
	v_mfma_f32_16x16x32_bf16 v[36:39], v[182:185], v[222:225], v[36:39]
	v_mfma_f32_16x16x32_bf16 v[32:35], v[200:203], v[222:225], v[32:35]
	v_mfma_f32_16x16x32_bf16 v[20:23], v[182:185], v[238:241], v[20:23]
	v_mfma_f32_16x16x32_bf16 v[16:19], v[200:203], v[238:241], v[16:19]
	v_mfma_f32_16x16x32_bf16 v[4:7], v[182:185], v[246:249], v[4:7]
	v_mfma_f32_16x16x32_bf16 v[0:3], v[200:203], v[246:249], v[0:3]
	s_setprio 0
	s_barrier
	s_add_i32 s27, 0, 0x18000
	v_add_u32_e32 v160, s27, v196
	s_add_i32 s85, 0, 0x1c000
	ds_read_b128 v[150:153], v160
	ds_read_b128 v[154:157], v160 offset:1024
	ds_read_b128 v[170:173], v160 offset:2048
	ds_read_b128 v[174:177], v160 offset:3072
	v_add_u32_e32 v160, s85, v196
	ds_read_b128 v[178:181], v160
	ds_read_b128 v[182:185], v160 offset:1024
	ds_read_b128 v[186:189], v160 offset:2048
	ds_read_b128 v[200:203], v160 offset:3072
	s_add_u32 s42, s42, 0x40000
	s_addc_u32 s43, s43, 0
	s_mov_b32 m0, s88
	v_lshl_add_u64 v[164:165], s[42:43], 0, v[128:129]
	ds_read_b128 v[204:207], v199 offset:32768
	ds_read_b128 v[208:211], v199 offset:33792
	ds_read_b128 v[212:215], v199 offset:34816
	ds_read_b128 v[222:225], v199 offset:35840
	ds_read_b128 v[234:237], v199 offset:36864
	ds_read_b128 v[238:241], v199 offset:37888
	ds_read_b128 v[242:245], v199 offset:38912
	ds_read_b128 v[246:249], v199 offset:39936
	global_load_lds_dwordx4 v[164:165], off
	v_lshl_add_u64 v[164:165], s[42:43], 0, v[132:133]
	s_mov_b32 m0, s89
	s_nop 0
	global_load_lds_dwordx4 v[164:165], off
	s_waitcnt vmcnt(8)
	s_waitcnt lgkmcnt(0)
	s_barrier
	s_setprio 1
	s_waitcnt lgkmcnt(0)
	v_mfma_f32_16x16x32_bf16 v[124:127], v[150:153], v[204:207], v[124:127]
	v_mfma_f32_16x16x32_bf16 v[120:123], v[170:173], v[204:207], v[120:123]
	v_mfma_f32_16x16x32_bf16 v[108:111], v[150:153], v[212:215], v[108:111]
	v_mfma_f32_16x16x32_bf16 v[104:107], v[170:173], v[212:215], v[104:107]
	v_mfma_f32_16x16x32_bf16 v[92:95], v[150:153], v[234:237], v[92:95]
	v_mfma_f32_16x16x32_bf16 v[88:91], v[170:173], v[234:237], v[88:91]
	v_mfma_f32_16x16x32_bf16 v[76:79], v[150:153], v[242:245], v[76:79]
	v_mfma_f32_16x16x32_bf16 v[72:75], v[170:173], v[242:245], v[72:75]
	v_mfma_f32_16x16x32_bf16 v[124:127], v[154:157], v[208:211], v[124:127]
	v_mfma_f32_16x16x32_bf16 v[120:123], v[174:177], v[208:211], v[120:123]
	v_mfma_f32_16x16x32_bf16 v[108:111], v[154:157], v[222:225], v[108:111]
	v_mfma_f32_16x16x32_bf16 v[104:107], v[174:177], v[222:225], v[104:107]
	v_mfma_f32_16x16x32_bf16 v[92:95], v[154:157], v[238:241], v[92:95]
	v_mfma_f32_16x16x32_bf16 v[88:91], v[174:177], v[238:241], v[88:91]
	v_mfma_f32_16x16x32_bf16 v[76:79], v[154:157], v[246:249], v[76:79]
	v_mfma_f32_16x16x32_bf16 v[72:75], v[174:177], v[246:249], v[72:75]
	v_mfma_f32_16x16x32_bf16 v[116:119], v[178:181], v[204:207], v[116:119]
	v_mfma_f32_16x16x32_bf16 v[112:115], v[186:189], v[204:207], v[112:115]
	v_mfma_f32_16x16x32_bf16 v[100:103], v[178:181], v[212:215], v[100:103]
	v_mfma_f32_16x16x32_bf16 v[96:99], v[186:189], v[212:215], v[96:99]
	v_mfma_f32_16x16x32_bf16 v[84:87], v[178:181], v[234:237], v[84:87]
	v_mfma_f32_16x16x32_bf16 v[80:83], v[186:189], v[234:237], v[80:83]
	v_mfma_f32_16x16x32_bf16 v[68:71], v[178:181], v[242:245], v[68:71]
	v_mfma_f32_16x16x32_bf16 v[64:67], v[186:189], v[242:245], v[64:67]
	v_mfma_f32_16x16x32_bf16 v[116:119], v[182:185], v[208:211], v[116:119]
	v_mfma_f32_16x16x32_bf16 v[112:115], v[200:203], v[208:211], v[112:115]
	v_mfma_f32_16x16x32_bf16 v[100:103], v[182:185], v[222:225], v[100:103]
	v_mfma_f32_16x16x32_bf16 v[96:99], v[200:203], v[222:225], v[96:99]
	v_mfma_f32_16x16x32_bf16 v[84:87], v[182:185], v[238:241], v[84:87]
	v_mfma_f32_16x16x32_bf16 v[80:83], v[200:203], v[238:241], v[80:83]
	v_mfma_f32_16x16x32_bf16 v[68:71], v[182:185], v[246:249], v[68:71]
	v_mfma_f32_16x16x32_bf16 v[64:67], v[200:203], v[246:249], v[64:67]
	s_setprio 0
	s_barrier
	s_add_i32 s27, s27, s86
	v_lshl_add_u64 v[158:159], v[158:159], 0, s[48:49]
	s_mov_b32 m0, s27
	ds_read_b128 v[204:207], v199 offset:49152
	ds_read_b128 v[208:211], v199 offset:50176
	ds_read_b128 v[212:215], v199 offset:51200
	ds_read_b128 v[222:225], v199 offset:52224
	ds_read_b128 v[234:237], v199 offset:53248
	ds_read_b128 v[238:241], v199 offset:54272
	ds_read_b128 v[242:245], v199 offset:55296
	ds_read_b128 v[246:249], v199 offset:56320
	global_load_lds_dwordx4 v[158:159], off
	s_add_i32 m0, s27, 0x2000
	s_add_u32 s12, s12, 0x40080
	v_lshl_add_u64 v[158:159], v[250:251], 0, s[48:49]
	s_addc_u32 s13, s13, 0
	s_add_i32 s27, s85, s86
	global_load_lds_dwordx4 v[158:159], off
	v_lshl_add_u64 v[158:159], s[12:13], 0, v[130:131]
	s_mov_b32 m0, s27
	s_nop 0
	global_load_lds_dwordx4 v[158:159], off
	v_lshl_add_u64 v[158:159], s[12:13], 0, v[134:135]
	s_add_i32 m0, s27, 0x2000
	s_nop 0
	global_load_lds_dwordx4 v[158:159], off
	v_lshl_add_u64 v[158:159], v[226:227], 0, s[48:49]
	s_mov_b32 m0, s92
	s_nop 0
	global_load_lds_dwordx4 v[158:159], off
	v_lshl_add_u64 v[158:159], v[162:163], 0, s[48:49]
	s_mov_b32 m0, s93
	s_nop 0
	global_load_lds_dwordx4 v[158:159], off
	s_waitcnt vmcnt(8)
	s_waitcnt lgkmcnt(0)
	s_barrier
	s_setprio 1
	s_waitcnt lgkmcnt(0)
	v_mfma_f32_16x16x32_bf16 v[60:63], v[150:153], v[204:207], v[60:63]
	v_mfma_f32_16x16x32_bf16 v[56:59], v[170:173], v[204:207], v[56:59]
	v_mfma_f32_16x16x32_bf16 v[44:47], v[150:153], v[212:215], v[44:47]
	v_mfma_f32_16x16x32_bf16 v[40:43], v[170:173], v[212:215], v[40:43]
	v_mfma_f32_16x16x32_bf16 v[28:31], v[150:153], v[234:237], v[28:31]
	v_mfma_f32_16x16x32_bf16 v[24:27], v[170:173], v[234:237], v[24:27]
	v_mfma_f32_16x16x32_bf16 v[12:15], v[150:153], v[242:245], v[12:15]
	v_mfma_f32_16x16x32_bf16 v[8:11], v[170:173], v[242:245], v[8:11]
	v_mfma_f32_16x16x32_bf16 v[60:63], v[154:157], v[208:211], v[60:63]
	v_mfma_f32_16x16x32_bf16 v[56:59], v[174:177], v[208:211], v[56:59]
	v_mfma_f32_16x16x32_bf16 v[44:47], v[154:157], v[222:225], v[44:47]
	v_mfma_f32_16x16x32_bf16 v[40:43], v[174:177], v[222:225], v[40:43]
	v_mfma_f32_16x16x32_bf16 v[28:31], v[154:157], v[238:241], v[28:31]
	v_mfma_f32_16x16x32_bf16 v[24:27], v[174:177], v[238:241], v[24:27]
	v_mfma_f32_16x16x32_bf16 v[12:15], v[154:157], v[246:249], v[12:15]
	v_mfma_f32_16x16x32_bf16 v[8:11], v[174:177], v[246:249], v[8:11]
	v_mfma_f32_16x16x32_bf16 v[52:55], v[178:181], v[204:207], v[52:55]
	v_mfma_f32_16x16x32_bf16 v[48:51], v[186:189], v[204:207], v[48:51]
	v_mfma_f32_16x16x32_bf16 v[36:39], v[178:181], v[212:215], v[36:39]
	v_mfma_f32_16x16x32_bf16 v[32:35], v[186:189], v[212:215], v[32:35]
	v_mfma_f32_16x16x32_bf16 v[20:23], v[178:181], v[234:237], v[20:23]
	v_mfma_f32_16x16x32_bf16 v[16:19], v[186:189], v[234:237], v[16:19]
	v_mfma_f32_16x16x32_bf16 v[4:7], v[178:181], v[242:245], v[4:7]
	v_mfma_f32_16x16x32_bf16 v[0:3], v[186:189], v[242:245], v[0:3]
	v_mfma_f32_16x16x32_bf16 v[52:55], v[182:185], v[208:211], v[52:55]
	v_mfma_f32_16x16x32_bf16 v[48:51], v[200:203], v[208:211], v[48:51]
	v_mfma_f32_16x16x32_bf16 v[36:39], v[182:185], v[222:225], v[36:39]
	v_mfma_f32_16x16x32_bf16 v[32:35], v[200:203], v[222:225], v[32:35]
	v_mfma_f32_16x16x32_bf16 v[20:23], v[182:185], v[238:241], v[20:23]
	v_mfma_f32_16x16x32_bf16 v[16:19], v[200:203], v[238:241], v[16:19]
	v_mfma_f32_16x16x32_bf16 v[4:7], v[182:185], v[246:249], v[4:7]
	v_mfma_f32_16x16x32_bf16 v[0:3], v[200:203], v[246:249], v[0:3]
	s_setprio 0
	s_barrier
	s_add_i32 s51, s51, 2
	s_add_u32 s40, s40, 0x100
	s_addc_u32 s41, s41, 0
	s_add_u32 s25, s25, 0x100
	s_addc_u32 s50, s50, 0
	s_cmp_gt_u32 s51, 13
	s_cbranch_scc0 .LBB0_478
	s_and_b64 vcc, exec, s[10:11]
	s_cbranch_vccz .LBB0_481
	s_barrier

.LBB0_654:
	s_ashr_i32 s17, s16, 31
	s_lshl_b64 s[18:19], s[16:17], 19
	s_add_u32 s18, s68, s18
	s_addc_u32 s19, s69, s19
	s_and_b64 s[36:37], s[12:13], exec
	s_cselect_b32 s17, s19, s39
	s_cselect_b32 s84, s18, s38
	s_ashr_i32 s15, s14, 31
	s_lshl_b64 s[36:37], s[14:15], 19
	s_add_u32 s36, s28, s36
	s_addc_u32 s37, s66, s37
	s_and_b64 s[42:43], s[12:13], exec
	s_cselect_b32 s15, s37, s41
	s_cselect_b32 s85, s36, s40
	s_add_u32 s38, s38, 0x40080
	s_addc_u32 s39, s39, 0
	s_add_u32 s86, s40, 0x100
	s_addc_u32 s87, s41, 0
	s_mov_b32 s88, -2
	s_add_u32 s40, s38, 0xfffc0080
	s_addc_u32 s41, s39, -1
	s_add_i32 s89, 0, 0x10000
	s_cmp_eq_u32 s88, 12
	s_cselect_b32 s43, s17, s41
	s_cselect_b32 s42, s84, s40
	v_add_u32_e32 v143, s89, v141
	s_cselect_b32 s41, s15, s87
	s_cselect_b32 s40, s85, s86
	s_add_i32 s92, 0, 0x14000
	ds_read_b128 v[144:147], v143
	ds_read_b128 v[148:151], v143 offset:1024
	ds_read_b128 v[152:155], v143 offset:2048
	ds_read_b128 v[156:159], v143 offset:3072
	v_add_u32_e32 v143, s92, v141
	ds_read_b128 v[170:173], v143
	ds_read_b128 v[174:177], v143 offset:1024
	ds_read_b128 v[178:181], v143 offset:2048
	ds_read_b128 v[182:185], v143 offset:3072
	v_lshl_add_u64 v[162:163], s[38:39], 0, v[136:137]
	s_add_i32 m0, s27, 0xc000
	ds_read_b128 v[186:189], v142
	ds_read_b128 v[190:193], v142 offset:1024
	ds_read_b128 v[194:197], v142 offset:2048
	ds_read_b128 v[198:201], v142 offset:3072
	ds_read_b128 v[202:205], v142 offset:4096
	ds_read_b128 v[206:209], v142 offset:5120
	ds_read_b128 v[210:213], v142 offset:6144
	ds_read_b128 v[222:225], v142 offset:7168
	global_load_lds_dwordx4 v[162:163], off
	v_lshl_add_u64 v[162:163], s[38:39], 0, v[138:139]
	s_add_i32 m0, s27, 0xe000
	s_nop 0
	global_load_lds_dwordx4 v[162:163], off
	s_waitcnt vmcnt(8)
	s_waitcnt lgkmcnt(0)
	s_barrier
	s_setprio 1
	s_waitcnt lgkmcnt(0)
	v_mfma_f32_16x16x32_bf16 v[124:127], v[144:147], v[186:189], 0
	v_mfma_f32_16x16x32_bf16 v[120:123], v[152:155], v[186:189], 0
	v_mfma_f32_16x16x32_bf16 v[116:119], v[144:147], v[194:197], 0
	v_mfma_f32_16x16x32_bf16 v[112:115], v[152:155], v[194:197], 0
	v_mfma_f32_16x16x32_bf16 v[100:103], v[144:147], v[202:205], 0
	v_mfma_f32_16x16x32_bf16 v[96:99], v[152:155], v[202:205], 0
	v_mfma_f32_16x16x32_bf16 v[84:87], v[144:147], v[210:213], 0
	v_mfma_f32_16x16x32_bf16 v[80:83], v[152:155], v[210:213], 0
	v_mfma_f32_16x16x32_bf16 v[124:127], v[148:151], v[190:193], v[124:127]
	v_mfma_f32_16x16x32_bf16 v[120:123], v[156:159], v[190:193], v[120:123]
	v_mfma_f32_16x16x32_bf16 v[116:119], v[148:151], v[198:201], v[116:119]
	v_mfma_f32_16x16x32_bf16 v[112:115], v[156:159], v[198:201], v[112:115]
	v_mfma_f32_16x16x32_bf16 v[100:103], v[148:151], v[206:209], v[100:103]
	v_mfma_f32_16x16x32_bf16 v[96:99], v[156:159], v[206:209], v[96:99]
	v_mfma_f32_16x16x32_bf16 v[84:87], v[148:151], v[222:225], v[84:87]
	v_mfma_f32_16x16x32_bf16 v[80:83], v[156:159], v[222:225], v[80:83]
	v_mfma_f32_16x16x32_bf16 v[108:111], v[170:173], v[186:189], 0
	v_mfma_f32_16x16x32_bf16 v[104:107], v[178:181], v[186:189], 0
	v_mfma_f32_16x16x32_bf16 v[92:95], v[170:173], v[194:197], 0
	v_mfma_f32_16x16x32_bf16 v[88:91], v[178:181], v[194:197], 0
	v_mfma_f32_16x16x32_bf16 v[76:79], v[170:173], v[202:205], 0
	v_mfma_f32_16x16x32_bf16 v[72:75], v[178:181], v[202:205], 0
	v_mfma_f32_16x16x32_bf16 v[68:71], v[170:173], v[210:213], 0
	v_mfma_f32_16x16x32_bf16 v[64:67], v[178:181], v[210:213], 0
	v_mfma_f32_16x16x32_bf16 v[108:111], v[174:177], v[190:193], v[108:111]
	v_mfma_f32_16x16x32_bf16 v[104:107], v[182:185], v[190:193], v[104:107]
	v_mfma_f32_16x16x32_bf16 v[92:95], v[174:177], v[198:201], v[92:95]
	v_mfma_f32_16x16x32_bf16 v[88:91], v[182:185], v[198:201], v[88:91]
	v_mfma_f32_16x16x32_bf16 v[76:79], v[174:177], v[206:209], v[76:79]
	v_mfma_f32_16x16x32_bf16 v[72:75], v[182:185], v[206:209], v[72:75]
	v_mfma_f32_16x16x32_bf16 v[68:71], v[174:177], v[222:225], v[68:71]
	v_mfma_f32_16x16x32_bf16 v[64:67], v[182:185], v[222:225], v[64:67]
	s_setprio 0
	s_barrier
	s_add_i32 s89, s89, s26
	v_lshl_add_u64 v[162:163], s[40:41], 0, v[130:131]
	s_mov_b32 m0, s89
	ds_read_b128 v[186:189], v142 offset:16384
	ds_read_b128 v[190:193], v142 offset:17408
	ds_read_b128 v[194:197], v142 offset:18432
	ds_read_b128 v[198:201], v142 offset:19456
	ds_read_b128 v[202:205], v142 offset:20480
	ds_read_b128 v[206:209], v142 offset:21504
	ds_read_b128 v[210:213], v142 offset:22528
	ds_read_b128 v[222:225], v142 offset:23552
	global_load_lds_dwordx4 v[162:163], off
	s_add_i32 m0, s89, 0x2000
	s_add_u32 s90, s40, 0x40000
	v_lshl_add_u64 v[164:165], s[40:41], 0, v[134:135]
	s_addc_u32 s91, s41, 0
	s_add_i32 s89, s92, s26
	global_load_lds_dwordx4 v[164:165], off
	v_lshl_add_u64 v[214:215], s[90:91], 0, v[130:131]
	s_mov_b32 m0, s89
	v_lshl_add_u64 v[226:227], s[42:43], 0, v[132:133]
	global_load_lds_dwordx4 v[214:215], off
	v_lshl_add_u64 v[214:215], s[90:91], 0, v[134:135]
	s_add_i32 m0, s89, 0x2000
	s_nop 0
	global_load_lds_dwordx4 v[214:215], off
	v_lshl_add_u64 v[214:215], s[42:43], 0, v[128:129]
	s_mov_b32 m0, s27
	s_nop 0
	global_load_lds_dwordx4 v[214:215], off
	s_mov_b32 m0, s50
	s_nop 0
	global_load_lds_dwordx4 v[226:227], off
	s_waitcnt vmcnt(8)
	s_waitcnt lgkmcnt(0)
	s_barrier
	s_setprio 1
	s_waitcnt lgkmcnt(0)
	v_mfma_f32_16x16x32_bf16 v[60:63], v[144:147], v[186:189], 0
	v_mfma_f32_16x16x32_bf16 v[56:59], v[152:155], v[186:189], 0
	v_mfma_f32_16x16x32_bf16 v[52:55], v[144:147], v[194:197], 0
	v_mfma_f32_16x16x32_bf16 v[48:51], v[152:155], v[194:197], 0
	v_mfma_f32_16x16x32_bf16 v[36:39], v[144:147], v[202:205], 0
	v_mfma_f32_16x16x32_bf16 v[32:35], v[152:155], v[202:205], 0
	v_mfma_f32_16x16x32_bf16 v[20:23], v[144:147], v[210:213], 0
	v_mfma_f32_16x16x32_bf16 v[16:19], v[152:155], v[210:213], 0
	v_mfma_f32_16x16x32_bf16 v[60:63], v[148:151], v[190:193], v[60:63]
	v_mfma_f32_16x16x32_bf16 v[56:59], v[156:159], v[190:193], v[56:59]
	v_mfma_f32_16x16x32_bf16 v[52:55], v[148:151], v[198:201], v[52:55]
	v_mfma_f32_16x16x32_bf16 v[48:51], v[156:159], v[198:201], v[48:51]
	v_mfma_f32_16x16x32_bf16 v[36:39], v[148:151], v[206:209], v[36:39]
	v_mfma_f32_16x16x32_bf16 v[32:35], v[156:159], v[206:209], v[32:35]
	v_mfma_f32_16x16x32_bf16 v[20:23], v[148:151], v[222:225], v[20:23]
	v_mfma_f32_16x16x32_bf16 v[16:19], v[156:159], v[222:225], v[16:19]
	v_mfma_f32_16x16x32_bf16 v[44:47], v[170:173], v[186:189], 0
	v_mfma_f32_16x16x32_bf16 v[40:43], v[178:181], v[186:189], 0
	v_mfma_f32_16x16x32_bf16 v[28:31], v[170:173], v[194:197], 0
	v_mfma_f32_16x16x32_bf16 v[24:27], v[178:181], v[194:197], 0
	v_mfma_f32_16x16x32_bf16 v[12:15], v[170:173], v[202:205], 0
	v_mfma_f32_16x16x32_bf16 v[8:11], v[178:181], v[202:205], 0
	v_mfma_f32_16x16x32_bf16 v[4:7], v[170:173], v[210:213], 0
	v_mfma_f32_16x16x32_bf16 v[0:3], v[178:181], v[210:213], 0
	v_mfma_f32_16x16x32_bf16 v[44:47], v[174:177], v[190:193], v[44:47]
	v_mfma_f32_16x16x32_bf16 v[40:43], v[182:185], v[190:193], v[40:43]
	v_mfma_f32_16x16x32_bf16 v[28:31], v[174:177], v[198:201], v[28:31]
	v_mfma_f32_16x16x32_bf16 v[24:27], v[182:185], v[198:201], v[24:27]
	v_mfma_f32_16x16x32_bf16 v[12:15], v[174:177], v[206:209], v[12:15]
	v_mfma_f32_16x16x32_bf16 v[8:11], v[182:185], v[206:209], v[8:11]
	v_mfma_f32_16x16x32_bf16 v[4:7], v[174:177], v[222:225], v[4:7]
	v_mfma_f32_16x16x32_bf16 v[0:3], v[182:185], v[222:225], v[0:3]
	s_setprio 0
	s_barrier
	s_add_i32 s89, 0, 0x18000
	v_add_u32_e32 v143, s89, v141
	s_add_i32 s90, 0, 0x1c000
	ds_read_b128 v[144:147], v143
	ds_read_b128 v[148:151], v143 offset:1024
	ds_read_b128 v[152:155], v143 offset:2048
	ds_read_b128 v[156:159], v143 offset:3072
	v_add_u32_e32 v143, s90, v141
	ds_read_b128 v[170:173], v143
	ds_read_b128 v[174:177], v143 offset:1024
	ds_read_b128 v[178:181], v143 offset:2048
	ds_read_b128 v[182:185], v143 offset:3072
	s_add_u32 s42, s42, 0x40000
	s_addc_u32 s43, s43, 0
	s_mov_b32 m0, s51
	v_lshl_add_u64 v[234:235], s[42:43], 0, v[128:129]
	ds_read_b128 v[186:189], v142 offset:32768
	ds_read_b128 v[190:193], v142 offset:33792
	ds_read_b128 v[194:197], v142 offset:34816
	ds_read_b128 v[198:201], v142 offset:35840
	ds_read_b128 v[202:205], v142 offset:36864
	ds_read_b128 v[206:209], v142 offset:37888
	ds_read_b128 v[210:213], v142 offset:38912
	ds_read_b128 v[222:225], v142 offset:39936
	global_load_lds_dwordx4 v[234:235], off
	v_lshl_add_u64 v[234:235], s[42:43], 0, v[132:133]
	s_mov_b32 m0, s80
	s_nop 0
	global_load_lds_dwordx4 v[234:235], off
	s_waitcnt vmcnt(8)
	s_waitcnt lgkmcnt(0)
	s_barrier
	s_setprio 1
	s_waitcnt lgkmcnt(0)
	v_mfma_f32_16x16x32_bf16 v[124:127], v[144:147], v[186:189], v[124:127]
	v_mfma_f32_16x16x32_bf16 v[120:123], v[152:155], v[186:189], v[120:123]
	v_mfma_f32_16x16x32_bf16 v[116:119], v[144:147], v[194:197], v[116:119]
	v_mfma_f32_16x16x32_bf16 v[112:115], v[152:155], v[194:197], v[112:115]
	v_mfma_f32_16x16x32_bf16 v[100:103], v[144:147], v[202:205], v[100:103]
	v_mfma_f32_16x16x32_bf16 v[96:99], v[152:155], v[202:205], v[96:99]
	v_mfma_f32_16x16x32_bf16 v[84:87], v[144:147], v[210:213], v[84:87]
	v_mfma_f32_16x16x32_bf16 v[80:83], v[152:155], v[210:213], v[80:83]
	v_mfma_f32_16x16x32_bf16 v[124:127], v[148:151], v[190:193], v[124:127]
	v_mfma_f32_16x16x32_bf16 v[120:123], v[156:159], v[190:193], v[120:123]
	v_mfma_f32_16x16x32_bf16 v[116:119], v[148:151], v[198:201], v[116:119]
	v_mfma_f32_16x16x32_bf16 v[112:115], v[156:159], v[198:201], v[112:115]
	v_mfma_f32_16x16x32_bf16 v[100:103], v[148:151], v[206:209], v[100:103]
	v_mfma_f32_16x16x32_bf16 v[96:99], v[156:159], v[206:209], v[96:99]
	v_mfma_f32_16x16x32_bf16 v[84:87], v[148:151], v[222:225], v[84:87]
	v_mfma_f32_16x16x32_bf16 v[80:83], v[156:159], v[222:225], v[80:83]
	v_mfma_f32_16x16x32_bf16 v[108:111], v[170:173], v[186:189], v[108:111]
	v_mfma_f32_16x16x32_bf16 v[104:107], v[178:181], v[186:189], v[104:107]
	v_mfma_f32_16x16x32_bf16 v[92:95], v[170:173], v[194:197], v[92:95]
	v_mfma_f32_16x16x32_bf16 v[88:91], v[178:181], v[194:197], v[88:91]
	v_mfma_f32_16x16x32_bf16 v[76:79], v[170:173], v[202:205], v[76:79]
	v_mfma_f32_16x16x32_bf16 v[72:75], v[178:181], v[202:205], v[72:75]
	v_mfma_f32_16x16x32_bf16 v[68:71], v[170:173], v[210:213], v[68:71]
	v_mfma_f32_16x16x32_bf16 v[64:67], v[178:181], v[210:213], v[64:67]
	v_mfma_f32_16x16x32_bf16 v[108:111], v[174:177], v[190:193], v[108:111]
	v_mfma_f32_16x16x32_bf16 v[104:107], v[182:185], v[190:193], v[104:107]
	v_mfma_f32_16x16x32_bf16 v[92:95], v[174:177], v[198:201], v[92:95]
	v_mfma_f32_16x16x32_bf16 v[88:91], v[182:185], v[198:201], v[88:91]
	v_mfma_f32_16x16x32_bf16 v[76:79], v[174:177], v[206:209], v[76:79]
	v_mfma_f32_16x16x32_bf16 v[72:75], v[182:185], v[206:209], v[72:75]
	v_mfma_f32_16x16x32_bf16 v[68:71], v[174:177], v[222:225], v[68:71]
	v_mfma_f32_16x16x32_bf16 v[64:67], v[182:185], v[222:225], v[64:67]
	s_setprio 0
	s_barrier
	s_add_i32 s42, s89, s26
	v_lshl_add_u64 v[162:163], v[162:163], 0, s[48:49]
	s_mov_b32 m0, s42
	ds_read_b128 v[186:189], v142 offset:49152
	ds_read_b128 v[190:193], v142 offset:50176
	ds_read_b128 v[194:197], v142 offset:51200
	ds_read_b128 v[198:201], v142 offset:52224
	ds_read_b128 v[202:205], v142 offset:53248
	ds_read_b128 v[206:209], v142 offset:54272
	ds_read_b128 v[210:213], v142 offset:55296
	ds_read_b128 v[222:225], v142 offset:56320
	global_load_lds_dwordx4 v[162:163], off
	s_add_i32 m0, s42, 0x2000
	s_add_u32 s40, s40, 0x40080
	v_lshl_add_u64 v[162:163], v[164:165], 0, s[48:49]
	s_addc_u32 s41, s41, 0
	s_add_i32 s42, s90, s26
	global_load_lds_dwordx4 v[162:163], off
	v_lshl_add_u64 v[162:163], s[40:41], 0, v[130:131]
	s_mov_b32 m0, s42
	s_nop 0
	global_load_lds_dwordx4 v[162:163], off
	v_lshl_add_u64 v[162:163], s[40:41], 0, v[134:135]
	s_add_i32 m0, s42, 0x2000
	s_nop 0
	global_load_lds_dwordx4 v[162:163], off
	v_lshl_add_u64 v[162:163], v[214:215], 0, s[48:49]
	s_mov_b32 m0, s81
	s_nop 0
	global_load_lds_dwordx4 v[162:163], off
	v_lshl_add_u64 v[162:163], v[226:227], 0, s[48:49]
	s_mov_b32 m0, s82
	s_nop 0
	global_load_lds_dwordx4 v[162:163], off
	s_waitcnt vmcnt(8)
	s_waitcnt lgkmcnt(0)
	s_barrier
	s_setprio 1
	s_waitcnt lgkmcnt(0)
	v_mfma_f32_16x16x32_bf16 v[60:63], v[144:147], v[186:189], v[60:63]
	v_mfma_f32_16x16x32_bf16 v[56:59], v[152:155], v[186:189], v[56:59]
	v_mfma_f32_16x16x32_bf16 v[52:55], v[144:147], v[194:197], v[52:55]
	v_mfma_f32_16x16x32_bf16 v[48:51], v[152:155], v[194:197], v[48:51]
	v_mfma_f32_16x16x32_bf16 v[36:39], v[144:147], v[202:205], v[36:39]
	v_mfma_f32_16x16x32_bf16 v[32:35], v[152:155], v[202:205], v[32:35]
	v_mfma_f32_16x16x32_bf16 v[20:23], v[144:147], v[210:213], v[20:23]
	v_mfma_f32_16x16x32_bf16 v[16:19], v[152:155], v[210:213], v[16:19]
	v_mfma_f32_16x16x32_bf16 v[60:63], v[148:151], v[190:193], v[60:63]
	v_mfma_f32_16x16x32_bf16 v[56:59], v[156:159], v[190:193], v[56:59]
	v_mfma_f32_16x16x32_bf16 v[52:55], v[148:151], v[198:201], v[52:55]
	v_mfma_f32_16x16x32_bf16 v[48:51], v[156:159], v[198:201], v[48:51]
	v_mfma_f32_16x16x32_bf16 v[36:39], v[148:151], v[206:209], v[36:39]
	v_mfma_f32_16x16x32_bf16 v[32:35], v[156:159], v[206:209], v[32:35]
	v_mfma_f32_16x16x32_bf16 v[20:23], v[148:151], v[222:225], v[20:23]
	v_mfma_f32_16x16x32_bf16 v[16:19], v[156:159], v[222:225], v[16:19]
	v_mfma_f32_16x16x32_bf16 v[44:47], v[170:173], v[186:189], v[44:47]
	v_mfma_f32_16x16x32_bf16 v[40:43], v[178:181], v[186:189], v[40:43]
	v_mfma_f32_16x16x32_bf16 v[28:31], v[170:173], v[194:197], v[28:31]
	v_mfma_f32_16x16x32_bf16 v[24:27], v[178:181], v[194:197], v[24:27]
	v_mfma_f32_16x16x32_bf16 v[12:15], v[170:173], v[202:205], v[12:15]
	v_mfma_f32_16x16x32_bf16 v[8:11], v[178:181], v[202:205], v[8:11]
	v_mfma_f32_16x16x32_bf16 v[4:7], v[170:173], v[210:213], v[4:7]
	v_mfma_f32_16x16x32_bf16 v[0:3], v[178:181], v[210:213], v[0:3]
	v_mfma_f32_16x16x32_bf16 v[44:47], v[174:177], v[190:193], v[44:47]
	v_mfma_f32_16x16x32_bf16 v[40:43], v[182:185], v[190:193], v[40:43]
	v_mfma_f32_16x16x32_bf16 v[28:31], v[174:177], v[198:201], v[28:31]
	v_mfma_f32_16x16x32_bf16 v[24:27], v[182:185], v[198:201], v[24:27]
	v_mfma_f32_16x16x32_bf16 v[12:15], v[174:177], v[206:209], v[12:15]
	v_mfma_f32_16x16x32_bf16 v[8:11], v[182:185], v[206:209], v[8:11]
	v_mfma_f32_16x16x32_bf16 v[4:7], v[174:177], v[222:225], v[4:7]
	v_mfma_f32_16x16x32_bf16 v[0:3], v[182:185], v[222:225], v[0:3]
	s_setprio 0
	s_barrier
	s_add_i32 s88, s88, 2
	s_add_u32 s38, s38, 0x100
	s_addc_u32 s39, s39, 0
	s_add_u32 s86, s86, 0x100
	s_addc_u32 s87, s87, 0
	s_cmp_gt_u32 s88, 13
.LBB0_655:
	s_add_u32 s40, s38, 0xfffc0080
	s_addc_u32 s41, s39, -1
	s_add_i32 s89, 0, 0x10000
	s_cmp_eq_u32 s88, 12
	s_cselect_b32 s43, s17, s41
	s_cselect_b32 s42, s84, s40
	v_add_u32_e32 v143, s89, v141
	s_cselect_b32 s41, s15, s87
	s_cselect_b32 s40, s85, s86
	s_add_i32 s92, 0, 0x14000
	ds_read_b128 v[144:147], v143
	ds_read_b128 v[148:151], v143 offset:1024
	ds_read_b128 v[152:155], v143 offset:2048
	ds_read_b128 v[156:159], v143 offset:3072
	v_add_u32_e32 v143, s92, v141
	ds_read_b128 v[170:173], v143
	ds_read_b128 v[174:177], v143 offset:1024
	ds_read_b128 v[178:181], v143 offset:2048
	ds_read_b128 v[182:185], v143 offset:3072
	v_lshl_add_u64 v[162:163], s[38:39], 0, v[136:137]
	s_add_i32 m0, s27, 0xc000
	ds_read_b128 v[186:189], v142
	ds_read_b128 v[190:193], v142 offset:1024
	ds_read_b128 v[194:197], v142 offset:2048
	ds_read_b128 v[198:201], v142 offset:3072
	ds_read_b128 v[202:205], v142 offset:4096
	ds_read_b128 v[206:209], v142 offset:5120
	ds_read_b128 v[210:213], v142 offset:6144
	ds_read_b128 v[222:225], v142 offset:7168
	global_load_lds_dwordx4 v[162:163], off
	v_lshl_add_u64 v[162:163], s[38:39], 0, v[138:139]
	s_add_i32 m0, s27, 0xe000
	s_nop 0
	global_load_lds_dwordx4 v[162:163], off
	s_waitcnt vmcnt(8)
	s_waitcnt lgkmcnt(0)
	s_barrier
	s_setprio 1
	s_waitcnt lgkmcnt(0)
	v_mfma_f32_16x16x32_bf16 v[124:127], v[144:147], v[186:189], v[124:127]
	v_mfma_f32_16x16x32_bf16 v[120:123], v[152:155], v[186:189], v[120:123]
	v_mfma_f32_16x16x32_bf16 v[116:119], v[144:147], v[194:197], v[116:119]
	v_mfma_f32_16x16x32_bf16 v[112:115], v[152:155], v[194:197], v[112:115]
	v_mfma_f32_16x16x32_bf16 v[100:103], v[144:147], v[202:205], v[100:103]
	v_mfma_f32_16x16x32_bf16 v[96:99], v[152:155], v[202:205], v[96:99]
	v_mfma_f32_16x16x32_bf16 v[84:87], v[144:147], v[210:213], v[84:87]
	v_mfma_f32_16x16x32_bf16 v[80:83], v[152:155], v[210:213], v[80:83]
	v_mfma_f32_16x16x32_bf16 v[124:127], v[148:151], v[190:193], v[124:127]
	v_mfma_f32_16x16x32_bf16 v[120:123], v[156:159], v[190:193], v[120:123]
	v_mfma_f32_16x16x32_bf16 v[116:119], v[148:151], v[198:201], v[116:119]
	v_mfma_f32_16x16x32_bf16 v[112:115], v[156:159], v[198:201], v[112:115]
	v_mfma_f32_16x16x32_bf16 v[100:103], v[148:151], v[206:209], v[100:103]
	v_mfma_f32_16x16x32_bf16 v[96:99], v[156:159], v[206:209], v[96:99]
	v_mfma_f32_16x16x32_bf16 v[84:87], v[148:151], v[222:225], v[84:87]
	v_mfma_f32_16x16x32_bf16 v[80:83], v[156:159], v[222:225], v[80:83]
	v_mfma_f32_16x16x32_bf16 v[108:111], v[170:173], v[186:189], v[108:111]
	v_mfma_f32_16x16x32_bf16 v[104:107], v[178:181], v[186:189], v[104:107]
	v_mfma_f32_16x16x32_bf16 v[92:95], v[170:173], v[194:197], v[92:95]
	v_mfma_f32_16x16x32_bf16 v[88:91], v[178:181], v[194:197], v[88:91]
	v_mfma_f32_16x16x32_bf16 v[76:79], v[170:173], v[202:205], v[76:79]
	v_mfma_f32_16x16x32_bf16 v[72:75], v[178:181], v[202:205], v[72:75]
	v_mfma_f32_16x16x32_bf16 v[68:71], v[170:173], v[210:213], v[68:71]
	v_mfma_f32_16x16x32_bf16 v[64:67], v[178:181], v[210:213], v[64:67]
	v_mfma_f32_16x16x32_bf16 v[108:111], v[174:177], v[190:193], v[108:111]
	v_mfma_f32_16x16x32_bf16 v[104:107], v[182:185], v[190:193], v[104:107]
	v_mfma_f32_16x16x32_bf16 v[92:95], v[174:177], v[198:201], v[92:95]
	v_mfma_f32_16x16x32_bf16 v[88:91], v[182:185], v[198:201], v[88:91]
	v_mfma_f32_16x16x32_bf16 v[76:79], v[174:177], v[206:209], v[76:79]
	v_mfma_f32_16x16x32_bf16 v[72:75], v[182:185], v[206:209], v[72:75]
	v_mfma_f32_16x16x32_bf16 v[68:71], v[174:177], v[222:225], v[68:71]
	v_mfma_f32_16x16x32_bf16 v[64:67], v[182:185], v[222:225], v[64:67]
	s_setprio 0
	s_barrier
	s_add_i32 s89, s89, s26
	v_lshl_add_u64 v[162:163], s[40:41], 0, v[130:131]
	s_mov_b32 m0, s89
	ds_read_b128 v[186:189], v142 offset:16384
	ds_read_b128 v[190:193], v142 offset:17408
	ds_read_b128 v[194:197], v142 offset:18432
	ds_read_b128 v[198:201], v142 offset:19456
	ds_read_b128 v[202:205], v142 offset:20480
	ds_read_b128 v[206:209], v142 offset:21504
	ds_read_b128 v[210:213], v142 offset:22528
	ds_read_b128 v[222:225], v142 offset:23552
	global_load_lds_dwordx4 v[162:163], off
	s_add_i32 m0, s89, 0x2000
	s_add_u32 s90, s40, 0x40000
	v_lshl_add_u64 v[164:165], s[40:41], 0, v[134:135]
	s_addc_u32 s91, s41, 0
	s_add_i32 s89, s92, s26
	global_load_lds_dwordx4 v[164:165], off
	v_lshl_add_u64 v[214:215], s[90:91], 0, v[130:131]
	s_mov_b32 m0, s89
	v_lshl_add_u64 v[226:227], s[42:43], 0, v[132:133]
	global_load_lds_dwordx4 v[214:215], off
	v_lshl_add_u64 v[214:215], s[90:91], 0, v[134:135]
	s_add_i32 m0, s89, 0x2000
	s_nop 0
	global_load_lds_dwordx4 v[214:215], off
	v_lshl_add_u64 v[214:215], s[42:43], 0, v[128:129]
	s_mov_b32 m0, s27
	s_nop 0
	global_load_lds_dwordx4 v[214:215], off
	s_mov_b32 m0, s50
	s_nop 0
	global_load_lds_dwordx4 v[226:227], off
	s_waitcnt vmcnt(8)
	s_waitcnt lgkmcnt(0)
	s_barrier
	s_setprio 1
	s_waitcnt lgkmcnt(0)
	v_mfma_f32_16x16x32_bf16 v[60:63], v[144:147], v[186:189], v[60:63]
	v_mfma_f32_16x16x32_bf16 v[56:59], v[152:155], v[186:189], v[56:59]
	v_mfma_f32_16x16x32_bf16 v[52:55], v[144:147], v[194:197], v[52:55]
	v_mfma_f32_16x16x32_bf16 v[48:51], v[152:155], v[194:197], v[48:51]
	v_mfma_f32_16x16x32_bf16 v[36:39], v[144:147], v[202:205], v[36:39]
	v_mfma_f32_16x16x32_bf16 v[32:35], v[152:155], v[202:205], v[32:35]
	v_mfma_f32_16x16x32_bf16 v[20:23], v[144:147], v[210:213], v[20:23]
	v_mfma_f32_16x16x32_bf16 v[16:19], v[152:155], v[210:213], v[16:19]
	v_mfma_f32_16x16x32_bf16 v[60:63], v[148:151], v[190:193], v[60:63]
	v_mfma_f32_16x16x32_bf16 v[56:59], v[156:159], v[190:193], v[56:59]
	v_mfma_f32_16x16x32_bf16 v[52:55], v[148:151], v[198:201], v[52:55]
	v_mfma_f32_16x16x32_bf16 v[48:51], v[156:159], v[198:201], v[48:51]
	v_mfma_f32_16x16x32_bf16 v[36:39], v[148:151], v[206:209], v[36:39]
	v_mfma_f32_16x16x32_bf16 v[32:35], v[156:159], v[206:209], v[32:35]
	v_mfma_f32_16x16x32_bf16 v[20:23], v[148:151], v[222:225], v[20:23]
	v_mfma_f32_16x16x32_bf16 v[16:19], v[156:159], v[222:225], v[16:19]
	v_mfma_f32_16x16x32_bf16 v[44:47], v[170:173], v[186:189], v[44:47]
	v_mfma_f32_16x16x32_bf16 v[40:43], v[178:181], v[186:189], v[40:43]
	v_mfma_f32_16x16x32_bf16 v[28:31], v[170:173], v[194:197], v[28:31]
	v_mfma_f32_16x16x32_bf16 v[24:27], v[178:181], v[194:197], v[24:27]
	v_mfma_f32_16x16x32_bf16 v[12:15], v[170:173], v[202:205], v[12:15]
	v_mfma_f32_16x16x32_bf16 v[8:11], v[178:181], v[202:205], v[8:11]
	v_mfma_f32_16x16x32_bf16 v[4:7], v[170:173], v[210:213], v[4:7]
	v_mfma_f32_16x16x32_bf16 v[0:3], v[178:181], v[210:213], v[0:3]
	v_mfma_f32_16x16x32_bf16 v[44:47], v[174:177], v[190:193], v[44:47]
	v_mfma_f32_16x16x32_bf16 v[40:43], v[182:185], v[190:193], v[40:43]
	v_mfma_f32_16x16x32_bf16 v[28:31], v[174:177], v[198:201], v[28:31]
	v_mfma_f32_16x16x32_bf16 v[24:27], v[182:185], v[198:201], v[24:27]
	v_mfma_f32_16x16x32_bf16 v[12:15], v[174:177], v[206:209], v[12:15]
	v_mfma_f32_16x16x32_bf16 v[8:11], v[182:185], v[206:209], v[8:11]
	v_mfma_f32_16x16x32_bf16 v[4:7], v[174:177], v[222:225], v[4:7]
	v_mfma_f32_16x16x32_bf16 v[0:3], v[182:185], v[222:225], v[0:3]
	s_setprio 0
	s_barrier
	s_add_i32 s89, 0, 0x18000
	v_add_u32_e32 v143, s89, v141
	s_add_i32 s90, 0, 0x1c000
	ds_read_b128 v[144:147], v143
	ds_read_b128 v[148:151], v143 offset:1024
	ds_read_b128 v[152:155], v143 offset:2048
	ds_read_b128 v[156:159], v143 offset:3072
	v_add_u32_e32 v143, s90, v141
	ds_read_b128 v[170:173], v143
	ds_read_b128 v[174:177], v143 offset:1024
	ds_read_b128 v[178:181], v143 offset:2048
	ds_read_b128 v[182:185], v143 offset:3072
	s_add_u32 s42, s42, 0x40000
	s_addc_u32 s43, s43, 0
	s_mov_b32 m0, s51
	v_lshl_add_u64 v[234:235], s[42:43], 0, v[128:129]
	ds_read_b128 v[186:189], v142 offset:32768
	ds_read_b128 v[190:193], v142 offset:33792
	ds_read_b128 v[194:197], v142 offset:34816
	ds_read_b128 v[198:201], v142 offset:35840
	ds_read_b128 v[202:205], v142 offset:36864
	ds_read_b128 v[206:209], v142 offset:37888
	ds_read_b128 v[210:213], v142 offset:38912
	ds_read_b128 v[222:225], v142 offset:39936
	global_load_lds_dwordx4 v[234:235], off
	v_lshl_add_u64 v[234:235], s[42:43], 0, v[132:133]
	s_mov_b32 m0, s80
	s_nop 0
	global_load_lds_dwordx4 v[234:235], off
	s_waitcnt vmcnt(8)
	s_waitcnt lgkmcnt(0)
	s_barrier
	s_setprio 1
	s_waitcnt lgkmcnt(0)
	v_mfma_f32_16x16x32_bf16 v[124:127], v[144:147], v[186:189], v[124:127]
	v_mfma_f32_16x16x32_bf16 v[120:123], v[152:155], v[186:189], v[120:123]
	v_mfma_f32_16x16x32_bf16 v[116:119], v[144:147], v[194:197], v[116:119]
	v_mfma_f32_16x16x32_bf16 v[112:115], v[152:155], v[194:197], v[112:115]
	v_mfma_f32_16x16x32_bf16 v[100:103], v[144:147], v[202:205], v[100:103]
	v_mfma_f32_16x16x32_bf16 v[96:99], v[152:155], v[202:205], v[96:99]
	v_mfma_f32_16x16x32_bf16 v[84:87], v[144:147], v[210:213], v[84:87]
	v_mfma_f32_16x16x32_bf16 v[80:83], v[152:155], v[210:213], v[80:83]
	v_mfma_f32_16x16x32_bf16 v[124:127], v[148:151], v[190:193], v[124:127]
	v_mfma_f32_16x16x32_bf16 v[120:123], v[156:159], v[190:193], v[120:123]
	v_mfma_f32_16x16x32_bf16 v[116:119], v[148:151], v[198:201], v[116:119]
	v_mfma_f32_16x16x32_bf16 v[112:115], v[156:159], v[198:201], v[112:115]
	v_mfma_f32_16x16x32_bf16 v[100:103], v[148:151], v[206:209], v[100:103]
	v_mfma_f32_16x16x32_bf16 v[96:99], v[156:159], v[206:209], v[96:99]
	v_mfma_f32_16x16x32_bf16 v[84:87], v[148:151], v[222:225], v[84:87]
	v_mfma_f32_16x16x32_bf16 v[80:83], v[156:159], v[222:225], v[80:83]
	v_mfma_f32_16x16x32_bf16 v[108:111], v[170:173], v[186:189], v[108:111]
	v_mfma_f32_16x16x32_bf16 v[104:107], v[178:181], v[186:189], v[104:107]
	v_mfma_f32_16x16x32_bf16 v[92:95], v[170:173], v[194:197], v[92:95]
	v_mfma_f32_16x16x32_bf16 v[88:91], v[178:181], v[194:197], v[88:91]
	v_mfma_f32_16x16x32_bf16 v[76:79], v[170:173], v[202:205], v[76:79]
	v_mfma_f32_16x16x32_bf16 v[72:75], v[178:181], v[202:205], v[72:75]
	v_mfma_f32_16x16x32_bf16 v[68:71], v[170:173], v[210:213], v[68:71]
	v_mfma_f32_16x16x32_bf16 v[64:67], v[178:181], v[210:213], v[64:67]
	v_mfma_f32_16x16x32_bf16 v[108:111], v[174:177], v[190:193], v[108:111]
	v_mfma_f32_16x16x32_bf16 v[104:107], v[182:185], v[190:193], v[104:107]
	v_mfma_f32_16x16x32_bf16 v[92:95], v[174:177], v[198:201], v[92:95]
	v_mfma_f32_16x16x32_bf16 v[88:91], v[182:185], v[198:201], v[88:91]
	v_mfma_f32_16x16x32_bf16 v[76:79], v[174:177], v[206:209], v[76:79]
	v_mfma_f32_16x16x32_bf16 v[72:75], v[182:185], v[206:209], v[72:75]
	v_mfma_f32_16x16x32_bf16 v[68:71], v[174:177], v[222:225], v[68:71]
	v_mfma_f32_16x16x32_bf16 v[64:67], v[182:185], v[222:225], v[64:67]
	s_setprio 0
	s_barrier
	s_add_i32 s42, s89, s26
	v_lshl_add_u64 v[162:163], v[162:163], 0, s[48:49]
	s_mov_b32 m0, s42
	ds_read_b128 v[186:189], v142 offset:49152
	ds_read_b128 v[190:193], v142 offset:50176
	ds_read_b128 v[194:197], v142 offset:51200
	ds_read_b128 v[198:201], v142 offset:52224
	ds_read_b128 v[202:205], v142 offset:53248
	ds_read_b128 v[206:209], v142 offset:54272
	ds_read_b128 v[210:213], v142 offset:55296
	ds_read_b128 v[222:225], v142 offset:56320
	global_load_lds_dwordx4 v[162:163], off
	s_add_i32 m0, s42, 0x2000
	s_add_u32 s40, s40, 0x40080
	v_lshl_add_u64 v[162:163], v[164:165], 0, s[48:49]
	s_addc_u32 s41, s41, 0
	s_add_i32 s42, s90, s26
	global_load_lds_dwordx4 v[162:163], off
	v_lshl_add_u64 v[162:163], s[40:41], 0, v[130:131]
	s_mov_b32 m0, s42
	s_nop 0
	global_load_lds_dwordx4 v[162:163], off
	v_lshl_add_u64 v[162:163], s[40:41], 0, v[134:135]
	s_add_i32 m0, s42, 0x2000
	s_nop 0
	global_load_lds_dwordx4 v[162:163], off
	v_lshl_add_u64 v[162:163], v[214:215], 0, s[48:49]
	s_mov_b32 m0, s81
	s_nop 0
	global_load_lds_dwordx4 v[162:163], off
	v_lshl_add_u64 v[162:163], v[226:227], 0, s[48:49]
	s_mov_b32 m0, s82
	s_nop 0
	global_load_lds_dwordx4 v[162:163], off
	s_waitcnt vmcnt(8)
	s_waitcnt lgkmcnt(0)
	s_barrier
	s_setprio 1
	s_waitcnt lgkmcnt(0)
	v_mfma_f32_16x16x32_bf16 v[60:63], v[144:147], v[186:189], v[60:63]
	v_mfma_f32_16x16x32_bf16 v[56:59], v[152:155], v[186:189], v[56:59]
	v_mfma_f32_16x16x32_bf16 v[52:55], v[144:147], v[194:197], v[52:55]
	v_mfma_f32_16x16x32_bf16 v[48:51], v[152:155], v[194:197], v[48:51]
	v_mfma_f32_16x16x32_bf16 v[36:39], v[144:147], v[202:205], v[36:39]
	v_mfma_f32_16x16x32_bf16 v[32:35], v[152:155], v[202:205], v[32:35]
	v_mfma_f32_16x16x32_bf16 v[20:23], v[144:147], v[210:213], v[20:23]
	v_mfma_f32_16x16x32_bf16 v[16:19], v[152:155], v[210:213], v[16:19]
	v_mfma_f32_16x16x32_bf16 v[60:63], v[148:151], v[190:193], v[60:63]
	v_mfma_f32_16x16x32_bf16 v[56:59], v[156:159], v[190:193], v[56:59]
	v_mfma_f32_16x16x32_bf16 v[52:55], v[148:151], v[198:201], v[52:55]
	v_mfma_f32_16x16x32_bf16 v[48:51], v[156:159], v[198:201], v[48:51]
	v_mfma_f32_16x16x32_bf16 v[36:39], v[148:151], v[206:209], v[36:39]
	v_mfma_f32_16x16x32_bf16 v[32:35], v[156:159], v[206:209], v[32:35]
	v_mfma_f32_16x16x32_bf16 v[20:23], v[148:151], v[222:225], v[20:23]
	v_mfma_f32_16x16x32_bf16 v[16:19], v[156:159], v[222:225], v[16:19]
	v_mfma_f32_16x16x32_bf16 v[44:47], v[170:173], v[186:189], v[44:47]
	v_mfma_f32_16x16x32_bf16 v[40:43], v[178:181], v[186:189], v[40:43]
	v_mfma_f32_16x16x32_bf16 v[28:31], v[170:173], v[194:197], v[28:31]
	v_mfma_f32_16x16x32_bf16 v[24:27], v[178:181], v[194:197], v[24:27]
	v_mfma_f32_16x16x32_bf16 v[12:15], v[170:173], v[202:205], v[12:15]
	v_mfma_f32_16x16x32_bf16 v[8:11], v[178:181], v[202:205], v[8:11]
	v_mfma_f32_16x16x32_bf16 v[4:7], v[170:173], v[210:213], v[4:7]
	v_mfma_f32_16x16x32_bf16 v[0:3], v[178:181], v[210:213], v[0:3]
	v_mfma_f32_16x16x32_bf16 v[44:47], v[174:177], v[190:193], v[44:47]
	v_mfma_f32_16x16x32_bf16 v[40:43], v[182:185], v[190:193], v[40:43]
	v_mfma_f32_16x16x32_bf16 v[28:31], v[174:177], v[198:201], v[28:31]
	v_mfma_f32_16x16x32_bf16 v[24:27], v[182:185], v[198:201], v[24:27]
	v_mfma_f32_16x16x32_bf16 v[12:15], v[174:177], v[206:209], v[12:15]
	v_mfma_f32_16x16x32_bf16 v[8:11], v[182:185], v[206:209], v[8:11]
	v_mfma_f32_16x16x32_bf16 v[4:7], v[174:177], v[222:225], v[4:7]
	v_mfma_f32_16x16x32_bf16 v[0:3], v[182:185], v[222:225], v[0:3]
	s_setprio 0
	s_barrier
	s_add_i32 s88, s88, 2
	s_add_u32 s38, s38, 0x100
	s_addc_u32 s39, s39, 0
	s_add_u32 s86, s86, 0x100
	s_addc_u32 s87, s87, 0
	s_cmp_gt_u32 s88, 13
	s_cbranch_scc0 .LBB0_655
	v_readlane_b32 s88, v254, 60
	v_readlane_b32 s86, v255, 21
	v_readlane_b32 s84, v255, 23
	s_and_b64 vcc, exec, s[8:9]
	v_readlane_b32 s89, v254, 61
	v_readlane_b32 s87, v255, 22
	v_readlane_b32 s85, v255, 24
	s_cbranch_vccz .LBB0_658
	s_barrier
